# adds: K-loop LDS-DMA issued in SGPR-base + 32-bit VGPR-offset form, removing one 64-bit VALU address add per DMA from the loading wave (85 sites)
# baseline (speedup 1.0000x reference)
;     __host__ __device__ __forceinline__ bool next(int i, Unit& u) const { const int vv = vid + (i / 5) * G; if (vv >= 256) return false; u.pm = vv >> 2; u.pn = (vv & 3) + 4 * (i % 5); return true; }
; #define PG8_STAGE(bufoff, gbase, voff) do { _Pragma("unroll") for (int _i = 0; _i < 2; ++_i) \
;         __builtin_amdgcn_global_load_lds((const unsigned*)((const char*)(gbase) + (voff)[_i]), (PG8_LAS unsigned*)(lds + (bufoff) + ldsw + _i * 8192), 16, 0, 0); } while (0)
; #define PG8_WAIT_V(n) asm volatile("s_waitcnt vmcnt(" #n ")" ::: "memory")
; #define PG8_BAR __builtin_amdgcn_s_barrier()
;     __host__ __device__ __forceinline__ bool next(int i, pg8::Unit& u) const { const long Lx = (long)i * G + c; if (Lx >= 128) return false; const int Lq = (int)Lx; u.pm = 8 * (Lq >> 5) + (Lq & 7); u.pn = (Lq >> 3) & 3; return true; }
;     __device__ __forceinline__ size_t b_off(const pg8::Unit& u) const { return (size_t)(u.pm >> 3) * 4 * 131072; }
;     ...
;     const char* cA = (const char*)g.A + (size_t)cur.pm * tstepA + (size_t)cur.pn * APN + kofA; const char* cB = (const char*)g.Bt + (size_t)cur.pn * tstepB + S.b_off(cur) + kofB;
;     S.a_ready(cur);
;     if constexpr (SP2) {
;         PG8_STAGE(PG8_SB(0, 0), cB, voffB); PG8_STAGE(PG8_SB(0, 1), cB + hstepB, voffB); PG8_STAGE(PG8_SA(0, 0), cA, voffA); PG8_STAGE(PG8_SA(0, 1), cA + hstepA, voffA);
;         P();
;         if (wr == 1) PG8_BAR;
;         PG8_WAIT_V(2); PG8_BAR;
;         PG8_STAGE(PG8_SB(1, 0), cB + kstep, voffB); PG8_STAGE(PG8_SA(1, 0), cA + kstepA, voffA); PG8_STAGE(PG8_SB(1, 1), cB + hstepB + kstep, voffB);
;         PG8_WAIT_V(6); PG8_BAR;
;     } else {
;         PG8_STAGE(PG8_SB(0, 0), cB, voffB); PG8_STAGE(PG8_SA(0, 0), cA, voffA); PG8_STAGE(PG8_SB(0, 1), cB + hstepB, voffB); PG8_STAGE(PG8_SA(0, 1), cA + hstepA, voffA);
;         if (wr == 1) PG8_BAR;
;         PG8_WAIT_V(4); PG8_BAR;
;         PG8_STAGE(PG8_SB(1, 0), cB + kstep, voffB); PG8_STAGE(PG8_SA(1, 0), cA + kstepA, voffA); PG8_STAGE(PG8_SB(1, 1), cB + hstepB + kstep, voffB);
;         PG8_WAIT_V(6); PG8_BAR;
;     }
;     for (;;) {
;         const bool has_next = S.next(ui + 1, nxt);
;         const char* nA = has_next ? (const char*)g.A + (size_t)nxt.pm * tstepA + (size_t)nxt.pn * APN + kofA : cA; const char* nB = has_next ? (const char*)g.Bt + (size_t)nxt.pn * tstepB + S.b_off(nxt) + kofB : cB;
.LBB0_94:
	s_add_u32 s10, s15, 0x5704000
	s_addc_u32 s11, s16, 0
	s_lshl_b32 s4, s4, 5
	s_mov_b64 s[12:13], 0x80
	s_and_b32 s45, s4, 0x60
	s_add_i32 m0, s23, 0x18000
	v_lshl_add_u64 v[2:3], v[2:3], 0, s[12:13]
	s_lshl_b32 s41, s5, 6
	s_lshl_b32 s15, s5, 13
	s_lshl_b32 s16, s45, 7
	s_ashr_i32 s17, s14, 31
	s_waitcnt vmcnt(2)
	s_barrier
	global_load_lds_dwordx4 v[2:3], off
	s_add_i32 m0, s23, 0x1a000
	s_add_u32 s4, s26, 0x8000
	v_lshl_add_u64 v[0:1], v[0:1], 0, s[12:13]
	s_addc_u32 s5, s27, 0
	s_add_i32 s42, s23, 0x8000
	global_load_lds_dwordx4 v[0:1], off
	s_mov_b32 m0, s42
	s_add_i32 s43, s23, 0xa000
	global_load_lds_dwordx4 v134, s[4:5]
	v_lshl_add_u64 v[0:1], s[4:5], 0, v[130:131]
	s_add_u32 s4, s6, 0x10080
	s_mov_b32 m0, s43
	s_addc_u32 s5, s7, 0
	global_load_lds_dwordx4 v[0:1], off
	s_add_i32 m0, s23, 0x1c000
	s_nop 0
	global_load_lds_dwordx4 v132, s[4:5]
	v_lshl_add_u64 v[0:1], s[4:5], 0, v[128:129]
	s_add_i32 m0, s23, 0x1e000
	s_ashr_i32 s44, s38, 31
	global_load_lds_dwordx4 v[0:1], off
	v_and_b32_e32 v0, 48, v4
	v_lshlrev_b32_e32 v1, 6, v4
	s_movk_i32 s4, 0x3c0
	s_cmpk_lt_u32 s1, 0x100
	v_and_or_b32 v0, v1, s4, v0
	v_lshlrev_b32_e32 v1, 2, v4
	s_cselect_b64 s[4:5], -1, 0
	s_bitset1_b32 s45, 10
	v_and_b32_e32 v1, 32, v1
	s_add_u32 s14, s14, s38
	v_bitop3_b32 v2, v0, s15, v1 bitop3:0xde
	v_bitop3_b32 v0, s16, v0, v1 bitop3:0xf6
	s_waitcnt vmcnt(6)
	s_addc_u32 s15, s17, s44
	s_add_i32 s48, 0, 0x10000
	s_add_i32 s51, 0, 0x14000
	s_add_i32 s53, 0, 0x18000
	s_add_i32 s55, 0, 0x1c000
	v_add_u32_e32 v141, s48, v0
	v_add_u32_e32 v142, s51, v0
	s_add_i32 s48, s48, s0
	v_cndmask_b32_e64 v1, 0, 1, s[4:5]
	s_add_i32 s51, s51, s0
	v_add_u32_e32 v144, s53, v0
	v_add_u32_e32 v145, s55, v0
	s_add_i32 s53, s53, s0
	s_add_i32 s55, s55, s0
	v_mov_b64_e32 v[138:139], 0x80
	v_add_u32_e32 v143, 0, v2
	s_add_i32 s46, s23, 0xc000
	s_add_i32 s47, s23, 0xe000
	s_mov_b64 s[16:17], 0x100
	s_mov_b64 s[18:19], 0x180
	s_movk_i32 s49, 0x33c0
	s_add_i32 s50, s48, 0x2000
	s_add_i32 s52, s51, 0x2000
	s_add_i32 s54, s53, 0x2000
	s_add_i32 s56, s55, 0x2000
	v_cmp_ne_u32_e64 s[0:1], 1, v1
	s_barrier
	s_branch .LBB0_97

;     __host__ __device__ __forceinline__ bool next(int i, Unit& u) const { const int vv = vid + (i / 5) * G; if (vv >= 256) return false; u.pm = vv >> 2; u.pn = (vv & 3) + 4 * (i % 5); return true; }
; #define PG8_STAGE(bufoff, gbase, voff) do { _Pragma("unroll") for (int _i = 0; _i < 2; ++_i) \
;         __builtin_amdgcn_global_load_lds((const unsigned*)((const char*)(gbase) + (voff)[_i]), (PG8_LAS unsigned*)(lds + (bufoff) + ldsw + _i * 8192), 16, 0, 0); } while (0)
; #define PG8_WAIT_V(n) asm volatile("s_waitcnt vmcnt(" #n ")" ::: "memory")
; #define PG8_WAIT_L(n) asm volatile("s_waitcnt lgkmcnt(" #n ")" ::: "memory")
;     ...
;         const bool has_next = S.next(ui + 1, nxt);
;         const char* nA = has_next ? (const char*)g.A + (size_t)nxt.pm * tstepA + (size_t)nxt.pn * APN + kofA : cA; const char* nB = has_next ? (const char*)g.Bt + (size_t)nxt.pn * tstepB + S.b_off(nxt) + kofB : cB;
;         for (int t = 0; t < nt; t += 2) {
;             const bool last = (t == nt - 2);
;             const char* a1 = cA + (ptrdiff_t)(t + 1) * kstepA;
;             const char* a2 = last ? nA : cA + (ptrdiff_t)(t + 2) * kstepA; const char* b2 = last ? nB : cB + (ptrdiff_t)(t + 2) * kstep;
;             const char* a3 = a2 + kstepA; const char* b3 = b2 + kstep;
;             if (last && has_next) S.a_ready(nxt);
;             if constexpr (SP2) {
;             PG8_LDB(B0, 0, 0); PG8_LDB(B1, 0, 1); PG8_SCHED; PG8_LDA(At, 0, 0); PG8_STAGE(PG8_SA(1, 1), a1 + hstepA, voffA);
;             PG8_WAIT_V(8); PG8_WAIT_L(0); PG8_BAR; PG8_MMA(0, 0, At, B0); PG8_MMA(0, 1, At, B1); PG8_BAR; PG8_SCHED;
;             PG8_LDA(At, 0, 1); PG8_STAGE(PG8_SB(0, 0), b2, voffB); PG8_STAGE(PG8_SB(0, 1), b2 + hstepB, voffB); PG8_STAGE(PG8_SA(0, 0), a2, voffA);
;             PG8_WAIT_V(8); PG8_WAIT_L(0); PG8_BAR; PG8_MMA(1, 0, At, B0); PG8_MMA(1, 1, At, B1); PG8_BAR; PG8_SCHED;
;             PG8_LDB(B0, 1, 0); PG8_LDB(B1, 1, 1); PG8_SCHED; PG8_LDA(At, 1, 0); PG8_STAGE(PG8_SA(0, 1), a2 + hstepA, voffA);
;             PG8_WAIT_V(8); PG8_WAIT_L(0); PG8_BAR; PG8_MMA(0, 0, At, B0); PG8_MMA(0, 1, At, B1); PG8_BAR; PG8_SCHED;
;             PG8_LDA(At, 1, 1); PG8_STAGE(PG8_SB(1, 0), b3, voffB); PG8_STAGE(PG8_SB(1, 1), b3 + hstepB, voffB); PG8_STAGE(PG8_SA(1, 0), a3, voffA);
;             PG8_WAIT_V(8); PG8_WAIT_L(0); PG8_BAR; PG8_MMA(1, 0, At, B0); PG8_MMA(1, 1, At, B1); PG8_BAR; PG8_SCHED;
.LBB0_97:
	s_mov_b64 s[30:31], s[6:7]
	s_ashr_i32 s6, s14, 2
	s_and_b32 s6, s6, -8
	s_and_b32 s7, s14, 7
	s_mov_b32 s20, s58
	s_mov_b32 s21, s57
	v_cmp_lt_i64_e64 s[4:5], s[14:15], v[138:139]
	s_bfe_u32 s57, s14, 0x20003
	s_or_b32 s58, s6, s7
	s_and_b64 s[6:7], s[4:5], exec
	s_cselect_b32 s24, s58, s20
	s_cselect_b32 s6, s57, s21
	s_ashr_i32 s25, s24, 31
	s_lshl_b64 s[20:21], s[24:25], 20
	s_add_u32 s20, s2, s20
	s_addc_u32 s21, s3, s21
	s_ashr_i32 s7, s6, 31
	s_lshl_b64 s[6:7], s[6:7], 17
	s_add_u32 s20, s20, s6
	s_addc_u32 s21, s21, s7
	s_and_b64 s[28:29], s[4:5], exec
	ds_read_b128 v[0:3], v141
	ds_read_b128 v[4:7], v141 offset:1024
	ds_read_b128 v[8:11], v141 offset:2048
	ds_read_b128 v[12:15], v141 offset:3072
	ds_read_b128 v[16:19], v142
	ds_read_b128 v[20:23], v142 offset:1024
	ds_read_b128 v[24:27], v142 offset:2048
	ds_read_b128 v[28:31], v142 offset:3072
	s_cselect_b32 s29, s21, s27
	s_cselect_b32 s28, s20, s26
	s_add_u32 s25, s33, s6
	s_addc_u32 s34, s36, s7
	s_ashr_i32 s6, s24, 3
	s_ashr_i32 s7, s6, 31
	s_lshl_b64 s[6:7], s[6:7], 19
	s_add_u32 s6, s25, s6
	s_addc_u32 s7, s34, s7
	s_and_b64 s[24:25], s[4:5], exec
	s_cselect_b32 s25, s7, s31
	s_cselect_b32 s24, s6, s30
	s_add_u32 s60, s26, 0x10000
	s_addc_u32 s61, s27, 0
	s_add_u32 s34, s26, 0x18000
	s_addc_u32 s35, s27, 0
	s_add_u32 s62, s26, 0xc000
	s_addc_u32 s63, s27, 0
	s_mov_b32 m0, s46
	ds_read_b128 v[32:35], v143
	ds_read_b128 v[36:39], v143 offset:1024
	ds_read_b128 v[40:43], v143 offset:2048
	ds_read_b128 v[44:47], v143 offset:3072
	ds_read_b128 v[48:51], v143 offset:4096
	ds_read_b128 v[52:55], v143 offset:5120
	ds_read_b128 v[56:59], v143 offset:6144
	ds_read_b128 v[60:63], v143 offset:7168
	global_load_lds_dwordx4 v134, s[62:63]
	v_lshl_add_u64 v[64:65], s[62:63], 0, v[130:131]
	s_mov_b32 m0, s47
	s_nop 0
	global_load_lds_dwordx4 v[64:65], off
	s_waitcnt vmcnt(8)
	s_waitcnt lgkmcnt(0)
	s_barrier
	s_setprio 1
	s_waitcnt lgkmcnt(0)
	v_mfma_f32_16x16x32_bf16 v[64:67], v[0:3], v[32:35], 0
	v_mfma_f32_16x16x32_bf16 v[68:71], v[8:11], v[32:35], 0
	v_mfma_f32_16x16x32_bf16 v[72:75], v[0:3], v[40:43], 0
	v_mfma_f32_16x16x32_bf16 v[76:79], v[8:11], v[40:43], 0
	v_mfma_f32_16x16x32_bf16 v[80:83], v[0:3], v[48:51], 0
	v_mfma_f32_16x16x32_bf16 v[84:87], v[8:11], v[48:51], 0
	v_mfma_f32_16x16x32_bf16 v[88:91], v[0:3], v[56:59], 0
	v_mfma_f32_16x16x32_bf16 v[92:95], v[8:11], v[56:59], 0
	v_mfma_f32_16x16x32_bf16 v[64:67], v[4:7], v[36:39], v[64:67]
	v_mfma_f32_16x16x32_bf16 v[68:71], v[12:15], v[36:39], v[68:71]
	v_mfma_f32_16x16x32_bf16 v[72:75], v[4:7], v[44:47], v[72:75]
	v_mfma_f32_16x16x32_bf16 v[76:79], v[12:15], v[44:47], v[76:79]
	v_mfma_f32_16x16x32_bf16 v[80:83], v[4:7], v[52:55], v[80:83]
	v_mfma_f32_16x16x32_bf16 v[84:87], v[12:15], v[52:55], v[84:87]
	v_mfma_f32_16x16x32_bf16 v[88:91], v[4:7], v[60:63], v[88:91]
	v_mfma_f32_16x16x32_bf16 v[92:95], v[12:15], v[60:63], v[92:95]
	s_setprio 0
	s_setprio 1
	v_mfma_f32_16x16x32_bf16 v[96:99], v[16:19], v[32:35], 0
	v_mfma_f32_16x16x32_bf16 v[32:35], v[24:27], v[32:35], 0
	v_mfma_f32_16x16x32_bf16 v[96:99], v[20:23], v[36:39], v[96:99]
	v_mfma_f32_16x16x32_bf16 v[32:35], v[28:31], v[36:39], v[32:35]
	v_mfma_f32_16x16x32_bf16 v[36:39], v[16:19], v[40:43], 0
	v_mfma_f32_16x16x32_bf16 v[40:43], v[24:27], v[40:43], 0
	v_mfma_f32_16x16x32_bf16 v[36:39], v[20:23], v[44:47], v[36:39]
	v_mfma_f32_16x16x32_bf16 v[40:43], v[28:31], v[44:47], v[40:43]
	v_mfma_f32_16x16x32_bf16 v[44:47], v[16:19], v[48:51], 0
	v_mfma_f32_16x16x32_bf16 v[48:51], v[24:27], v[48:51], 0
	v_mfma_f32_16x16x32_bf16 v[44:47], v[20:23], v[52:55], v[44:47]
	v_mfma_f32_16x16x32_bf16 v[48:51], v[28:31], v[52:55], v[48:51]
	v_mfma_f32_16x16x32_bf16 v[52:55], v[16:19], v[56:59], 0
	v_mfma_f32_16x16x32_bf16 v[56:59], v[24:27], v[56:59], 0
	v_mfma_f32_16x16x32_bf16 v[52:55], v[20:23], v[60:63], v[52:55]
	v_mfma_f32_16x16x32_bf16 v[56:59], v[28:31], v[60:63], v[56:59]
	s_setprio 0
	s_barrier
	v_lshl_add_u64 v[210:211], s[30:31], 0, v[132:133]
	s_mov_b32 m0, s48
	v_lshl_add_u64 v[146:147], v[210:211], 0, s[16:17]
	v_lshl_add_u64 v[212:213], s[30:31], 0, v[128:129]
	s_add_u32 s62, s30, 0x10100
	ds_read_b128 v[60:63], v143 offset:16384
	ds_read_b128 v[100:103], v143 offset:17408
	ds_read_b128 v[104:107], v143 offset:18432
	ds_read_b128 v[108:111], v143 offset:19456
	ds_read_b128 v[112:115], v143 offset:20480
	ds_read_b128 v[116:119], v143 offset:21504
	ds_read_b128 v[120:123], v143 offset:22528
	ds_read_b128 v[124:127], v143 offset:23552
	global_load_lds_dwordx4 v[146:147], off
	v_lshl_add_u64 v[146:147], v[212:213], 0, s[16:17]
	s_mov_b32 m0, s50
	s_addc_u32 s63, s31, 0
	global_load_lds_dwordx4 v[146:147], off
	s_mov_b32 m0, s51
	s_nop 0
	global_load_lds_dwordx4 v132, s[62:63]
	s_mov_b32 m0, s52
	s_nop 0
	global_load_lds_dwordx4 v128, s[62:63]
	s_mov_b32 m0, s23
	s_nop 0
	global_load_lds_dwordx4 v134, s[60:61]
	v_lshl_add_u64 v[146:147], s[60:61], 0, v[130:131]
	s_mov_b32 m0, s37
	s_nop 0
	global_load_lds_dwordx4 v[146:147], off
	s_waitcnt vmcnt(8)
	s_waitcnt lgkmcnt(0)
	s_barrier
; #define PG8_STAGE(bufoff, gbase, voff) do { _Pragma("unroll") for (int _i = 0; _i < 2; ++_i) \
;         __builtin_amdgcn_global_load_lds((const unsigned*)((const char*)(gbase) + (voff)[_i]), (PG8_LAS unsigned*)(lds + (bufoff) + ldsw + _i * 8192), 16, 0, 0); } while (0)
; #define PG8_LDA(dst, b, h) do { _Pragma("unroll") for (int m = 0; m < 4; ++m) _Pragma("unroll") for (int k = 0; k < 2; ++k) dst[m][k] = *(const PG8_LAS bf16x8*)(lds + PG8_SA(b, h) + aoff + m * 2048 + k * 1024); } while (0)
; #define PG8_LDB(dst, b, h) do { _Pragma("unroll") for (int n = 0; n < 2; ++n) _Pragma("unroll") for (int k = 0; k < 2; ++k) dst[n][k] = *(const PG8_LAS bf16x8*)(lds + PG8_SB(b, h) + boff + n * 2048 + k * 1024); } while (0)
; #define PG8_MMA(ai, bj, At, Bt) do { __builtin_amdgcn_s_setprio(1); _Pragma("unroll") for (int m = 0; m < 4; ++m) _Pragma("unroll") for (int n = 0; n < 2; ++n) _Pragma("unroll") for (int k = 0; k < 2; ++k) \
;         acc[ai][bj][m][n] = __builtin_amdgcn_mfma_f32_16x16x32_bf16(Bt[n][k], At[m][k], acc[ai][bj][m][n], 0, 0, 0); __builtin_amdgcn_s_setprio(0); } while (0)
; #define PG8_WAIT_V(n) asm volatile("s_waitcnt vmcnt(" #n ")" ::: "memory")
; #define PG8_WAIT_L(n) asm volatile("s_waitcnt lgkmcnt(" #n ")" ::: "memory")
; #define PG8_BAR __builtin_amdgcn_s_barrier()
; #define PG8_SCHED __builtin_amdgcn_sched_barrier(0)
;     ...
;             PG8_LDB(B0, 0, 0); PG8_LDB(B1, 0, 1); PG8_SCHED; PG8_LDA(At, 0, 0); PG8_STAGE(PG8_SA(1, 1), a1 + hstepA, voffA);
;             PG8_WAIT_V(8); PG8_WAIT_L(0); PG8_BAR; PG8_MMA(0, 0, At, B0); PG8_MMA(0, 1, At, B1); PG8_BAR; PG8_SCHED;
;             PG8_LDA(At, 0, 1); PG8_STAGE(PG8_SB(0, 0), b2, voffB); PG8_STAGE(PG8_SB(0, 1), b2 + hstepB, voffB); PG8_STAGE(PG8_SA(0, 0), a2, voffA);
;             PG8_WAIT_V(8); PG8_WAIT_L(0); PG8_BAR; PG8_MMA(1, 0, At, B0); PG8_MMA(1, 1, At, B1); PG8_BAR; PG8_SCHED;
;             PG8_LDB(B0, 1, 0); PG8_LDB(B1, 1, 1); PG8_SCHED; PG8_LDA(At, 1, 0); PG8_STAGE(PG8_SA(0, 1), a2 + hstepA, voffA);
;             PG8_WAIT_V(8); PG8_WAIT_L(0); PG8_BAR; PG8_MMA(0, 0, At, B0); PG8_MMA(0, 1, At, B1); PG8_BAR; PG8_SCHED;
;             PG8_LDA(At, 1, 1); PG8_STAGE(PG8_SB(1, 0), b3, voffB); PG8_STAGE(PG8_SB(1, 1), b3 + hstepB, voffB); PG8_STAGE(PG8_SA(1, 0), a3, voffA);
	s_setprio 1
	s_waitcnt lgkmcnt(0)
	v_mfma_f32_16x16x32_bf16 v[146:149], v[0:3], v[60:63], 0
	v_mfma_f32_16x16x32_bf16 v[154:157], v[0:3], v[104:107], 0
	v_mfma_f32_16x16x32_bf16 v[162:165], v[0:3], v[112:115], 0
	v_mfma_f32_16x16x32_bf16 v[0:3], v[0:3], v[120:123], 0
	v_mfma_f32_16x16x32_bf16 v[146:149], v[4:7], v[100:103], v[146:149]
	v_mfma_f32_16x16x32_bf16 v[154:157], v[4:7], v[108:111], v[154:157]
	v_mfma_f32_16x16x32_bf16 v[162:165], v[4:7], v[116:119], v[162:165]
	v_mfma_f32_16x16x32_bf16 v[0:3], v[4:7], v[124:127], v[0:3]
	v_mfma_f32_16x16x32_bf16 v[4:7], v[8:11], v[120:123], 0
	v_mfma_f32_16x16x32_bf16 v[150:153], v[8:11], v[60:63], 0
	v_mfma_f32_16x16x32_bf16 v[158:161], v[8:11], v[104:107], 0
	v_mfma_f32_16x16x32_bf16 v[166:169], v[8:11], v[112:115], 0
	v_mfma_f32_16x16x32_bf16 v[4:7], v[12:15], v[124:127], v[4:7]
	v_mfma_f32_16x16x32_bf16 v[150:153], v[12:15], v[100:103], v[150:153]
	v_mfma_f32_16x16x32_bf16 v[158:161], v[12:15], v[108:111], v[158:161]
	v_mfma_f32_16x16x32_bf16 v[166:169], v[12:15], v[116:119], v[166:169]
	s_setprio 0
	s_setprio 1
	v_mfma_f32_16x16x32_bf16 v[8:11], v[16:19], v[60:63], 0
	v_mfma_f32_16x16x32_bf16 v[12:15], v[24:27], v[60:63], 0
	v_mfma_f32_16x16x32_bf16 v[8:11], v[20:23], v[100:103], v[8:11]
	v_mfma_f32_16x16x32_bf16 v[12:15], v[28:31], v[100:103], v[12:15]
	v_mfma_f32_16x16x32_bf16 v[60:63], v[16:19], v[104:107], 0
	v_mfma_f32_16x16x32_bf16 v[100:103], v[24:27], v[104:107], 0
	v_mfma_f32_16x16x32_bf16 v[104:107], v[16:19], v[112:115], 0
	v_mfma_f32_16x16x32_bf16 v[16:19], v[16:19], v[120:123], 0
	v_mfma_f32_16x16x32_bf16 v[60:63], v[20:23], v[108:111], v[60:63]
	v_mfma_f32_16x16x32_bf16 v[100:103], v[28:31], v[108:111], v[100:103]
	v_mfma_f32_16x16x32_bf16 v[104:107], v[20:23], v[116:119], v[104:107]
	v_mfma_f32_16x16x32_bf16 v[108:111], v[24:27], v[112:115], 0
	v_mfma_f32_16x16x32_bf16 v[16:19], v[20:23], v[124:127], v[16:19]
	v_mfma_f32_16x16x32_bf16 v[20:23], v[24:27], v[120:123], 0
	v_mfma_f32_16x16x32_bf16 v[108:111], v[28:31], v[116:119], v[108:111]
	v_mfma_f32_16x16x32_bf16 v[20:23], v[28:31], v[124:127], v[20:23]
	s_setprio 0
	s_barrier
	ds_read_b128 v[24:27], v144
	ds_read_b128 v[28:31], v144 offset:1024
	ds_read_b128 v[112:115], v144 offset:2048
	ds_read_b128 v[116:119], v144 offset:3072
	ds_read_b128 v[120:123], v145
	ds_read_b128 v[124:127], v145 offset:1024
	ds_read_b128 v[170:173], v145 offset:2048
	ds_read_b128 v[174:177], v145 offset:3072
	s_add_u32 s60, s26, 0x14000
	s_addc_u32 s61, s27, 0
	s_mov_b32 m0, s39
	ds_read_b128 v[178:181], v143 offset:32768
	ds_read_b128 v[182:185], v143 offset:33792
	ds_read_b128 v[186:189], v143 offset:34816
	ds_read_b128 v[190:193], v143 offset:35840
	ds_read_b128 v[194:197], v143 offset:36864
	ds_read_b128 v[198:201], v143 offset:37888
	ds_read_b128 v[202:205], v143 offset:38912
	ds_read_b128 v[206:209], v143 offset:39936
	global_load_lds_dwordx4 v134, s[60:61]
	v_lshl_add_u64 v[214:215], s[60:61], 0, v[130:131]
	s_mov_b32 m0, s40
	s_nop 0
	global_load_lds_dwordx4 v[214:215], off
	s_waitcnt vmcnt(8)
	s_waitcnt lgkmcnt(0)
	s_barrier
	s_setprio 1
	s_waitcnt lgkmcnt(0)
	v_mfma_f32_16x16x32_bf16 v[64:67], v[24:27], v[178:181], v[64:67]
	v_mfma_f32_16x16x32_bf16 v[68:71], v[112:115], v[178:181], v[68:71]
	v_mfma_f32_16x16x32_bf16 v[72:75], v[24:27], v[186:189], v[72:75]
	v_mfma_f32_16x16x32_bf16 v[76:79], v[112:115], v[186:189], v[76:79]
	v_mfma_f32_16x16x32_bf16 v[80:83], v[24:27], v[194:197], v[80:83]
	v_mfma_f32_16x16x32_bf16 v[84:87], v[112:115], v[194:197], v[84:87]
	v_mfma_f32_16x16x32_bf16 v[88:91], v[24:27], v[202:205], v[88:91]
	v_mfma_f32_16x16x32_bf16 v[92:95], v[112:115], v[202:205], v[92:95]
	v_mfma_f32_16x16x32_bf16 v[64:67], v[28:31], v[182:185], v[64:67]
	v_mfma_f32_16x16x32_bf16 v[68:71], v[116:119], v[182:185], v[68:71]
	v_mfma_f32_16x16x32_bf16 v[72:75], v[28:31], v[190:193], v[72:75]
	v_mfma_f32_16x16x32_bf16 v[76:79], v[116:119], v[190:193], v[76:79]
	v_mfma_f32_16x16x32_bf16 v[80:83], v[28:31], v[198:201], v[80:83]
	v_mfma_f32_16x16x32_bf16 v[84:87], v[116:119], v[198:201], v[84:87]
	v_mfma_f32_16x16x32_bf16 v[88:91], v[28:31], v[206:209], v[88:91]
	v_mfma_f32_16x16x32_bf16 v[92:95], v[116:119], v[206:209], v[92:95]
	s_setprio 0
	s_setprio 1
	v_mfma_f32_16x16x32_bf16 v[96:99], v[120:123], v[178:181], v[96:99]
	v_mfma_f32_16x16x32_bf16 v[32:35], v[170:173], v[178:181], v[32:35]
	v_mfma_f32_16x16x32_bf16 v[36:39], v[120:123], v[186:189], v[36:39]
	v_mfma_f32_16x16x32_bf16 v[40:43], v[170:173], v[186:189], v[40:43]
	v_mfma_f32_16x16x32_bf16 v[44:47], v[120:123], v[194:197], v[44:47]
	v_mfma_f32_16x16x32_bf16 v[48:51], v[170:173], v[194:197], v[48:51]
	v_mfma_f32_16x16x32_bf16 v[52:55], v[120:123], v[202:205], v[52:55]
	v_mfma_f32_16x16x32_bf16 v[56:59], v[170:173], v[202:205], v[56:59]
	v_mfma_f32_16x16x32_bf16 v[96:99], v[124:127], v[182:185], v[96:99]
	v_mfma_f32_16x16x32_bf16 v[32:35], v[174:177], v[182:185], v[32:35]
	v_mfma_f32_16x16x32_bf16 v[36:39], v[124:127], v[190:193], v[36:39]
	v_mfma_f32_16x16x32_bf16 v[40:43], v[174:177], v[190:193], v[40:43]
	v_mfma_f32_16x16x32_bf16 v[44:47], v[124:127], v[198:201], v[44:47]
	v_mfma_f32_16x16x32_bf16 v[48:51], v[174:177], v[198:201], v[48:51]
	v_mfma_f32_16x16x32_bf16 v[52:55], v[124:127], v[206:209], v[52:55]
	v_mfma_f32_16x16x32_bf16 v[56:59], v[174:177], v[206:209], v[56:59]
	s_setprio 0
	s_barrier
; #define PG8_STAGE(bufoff, gbase, voff) do { _Pragma("unroll") for (int _i = 0; _i < 2; ++_i) \
;         __builtin_amdgcn_global_load_lds((const unsigned*)((const char*)(gbase) + (voff)[_i]), (PG8_LAS unsigned*)(lds + (bufoff) + ldsw + _i * 8192), 16, 0, 0); } while (0)
; #define PG8_LDA(dst, b, h) do { _Pragma("unroll") for (int m = 0; m < 4; ++m) _Pragma("unroll") for (int k = 0; k < 2; ++k) dst[m][k] = *(const PG8_LAS bf16x8*)(lds + PG8_SA(b, h) + aoff + m * 2048 + k * 1024); } while (0)
; #define PG8_LDB(dst, b, h) do { _Pragma("unroll") for (int n = 0; n < 2; ++n) _Pragma("unroll") for (int k = 0; k < 2; ++k) dst[n][k] = *(const PG8_LAS bf16x8*)(lds + PG8_SB(b, h) + boff + n * 2048 + k * 1024); } while (0)
; #define PG8_MMA(ai, bj, At, Bt) do { __builtin_amdgcn_s_setprio(1); _Pragma("unroll") for (int m = 0; m < 4; ++m) _Pragma("unroll") for (int n = 0; n < 2; ++n) _Pragma("unroll") for (int k = 0; k < 2; ++k) \
;         acc[ai][bj][m][n] = __builtin_amdgcn_mfma_f32_16x16x32_bf16(Bt[n][k], At[m][k], acc[ai][bj][m][n], 0, 0, 0); __builtin_amdgcn_s_setprio(0); } while (0)
; #define PG8_WAIT_V(n) asm volatile("s_waitcnt vmcnt(" #n ")" ::: "memory")
; #define PG8_WAIT_L(n) asm volatile("s_waitcnt lgkmcnt(" #n ")" ::: "memory")
; #define PG8_BAR __builtin_amdgcn_s_barrier()
; #define PG8_SCHED __builtin_amdgcn_sched_barrier(0)
;     ...
;             PG8_LDA(At, 0, 1); PG8_STAGE(PG8_SB(0, 0), b2, voffB); PG8_STAGE(PG8_SB(0, 1), b2 + hstepB, voffB); PG8_STAGE(PG8_SA(0, 0), a2, voffA);
;             PG8_WAIT_V(8); PG8_WAIT_L(0); PG8_BAR; PG8_MMA(1, 0, At, B0); PG8_MMA(1, 1, At, B1); PG8_BAR; PG8_SCHED;
;             PG8_LDB(B0, 1, 0); PG8_LDB(B1, 1, 1); PG8_SCHED; PG8_LDA(At, 1, 0); PG8_STAGE(PG8_SA(0, 1), a2 + hstepA, voffA);
;             PG8_WAIT_V(8); PG8_WAIT_L(0); PG8_BAR; PG8_MMA(0, 0, At, B0); PG8_MMA(0, 1, At, B1); PG8_BAR; PG8_SCHED;
;             PG8_LDA(At, 1, 1); PG8_STAGE(PG8_SB(1, 0), b3, voffB); PG8_STAGE(PG8_SB(1, 1), b3 + hstepB, voffB); PG8_STAGE(PG8_SA(1, 0), a3, voffA);
;             PG8_WAIT_V(8); PG8_WAIT_L(0); PG8_BAR; PG8_MMA(1, 0, At, B0); PG8_MMA(1, 1, At, B1); PG8_BAR; PG8_SCHED;
	s_mov_b32 m0, s53
	v_lshl_add_u64 v[210:211], v[210:211], 0, s[18:19]
	s_add_u32 s30, s30, 0x10180
	ds_read_b128 v[178:181], v143 offset:49152
	ds_read_b128 v[182:185], v143 offset:50176
	ds_read_b128 v[186:189], v143 offset:51200
	ds_read_b128 v[190:193], v143 offset:52224
	ds_read_b128 v[194:197], v143 offset:53248
	ds_read_b128 v[198:201], v143 offset:54272
	ds_read_b128 v[202:205], v143 offset:55296
	ds_read_b128 v[206:209], v143 offset:56320
	global_load_lds_dwordx4 v[210:211], off
	v_lshl_add_u64 v[210:211], v[212:213], 0, s[18:19]
	s_mov_b32 m0, s54
	s_addc_u32 s31, s31, 0
	global_load_lds_dwordx4 v[210:211], off
	s_mov_b32 m0, s55
	s_nop 0
	global_load_lds_dwordx4 v132, s[30:31]
	s_mov_b32 m0, s56
	s_nop 0
	global_load_lds_dwordx4 v128, s[30:31]
	s_mov_b32 m0, s42
	s_nop 0
	global_load_lds_dwordx4 v134, s[34:35]
	s_mov_b32 m0, s43
	s_nop 0
	global_load_lds_dwordx4 v130, s[34:35]
	s_waitcnt vmcnt(8)
	s_waitcnt lgkmcnt(0)
	s_barrier
	s_setprio 1
	s_waitcnt lgkmcnt(0)
	v_mfma_f32_16x16x32_bf16 v[0:3], v[24:27], v[202:205], v[0:3]
	v_mfma_f32_16x16x32_bf16 v[4:7], v[112:115], v[202:205], v[4:7]
	v_mfma_f32_16x16x32_bf16 v[146:149], v[24:27], v[178:181], v[146:149]
	v_mfma_f32_16x16x32_bf16 v[150:153], v[112:115], v[178:181], v[150:153]
	v_mfma_f32_16x16x32_bf16 v[154:157], v[24:27], v[186:189], v[154:157]
	v_mfma_f32_16x16x32_bf16 v[158:161], v[112:115], v[186:189], v[158:161]
	v_mfma_f32_16x16x32_bf16 v[162:165], v[24:27], v[194:197], v[162:165]
	v_mfma_f32_16x16x32_bf16 v[166:169], v[112:115], v[194:197], v[166:169]
	v_mfma_f32_16x16x32_bf16 v[0:3], v[28:31], v[206:209], v[0:3]
	v_mfma_f32_16x16x32_bf16 v[4:7], v[116:119], v[206:209], v[4:7]
	v_mfma_f32_16x16x32_bf16 v[146:149], v[28:31], v[182:185], v[146:149]
	v_mfma_f32_16x16x32_bf16 v[150:153], v[116:119], v[182:185], v[150:153]
	v_mfma_f32_16x16x32_bf16 v[154:157], v[28:31], v[190:193], v[154:157]
	v_mfma_f32_16x16x32_bf16 v[158:161], v[116:119], v[190:193], v[158:161]
	v_mfma_f32_16x16x32_bf16 v[162:165], v[28:31], v[198:201], v[162:165]
	v_mfma_f32_16x16x32_bf16 v[166:169], v[116:119], v[198:201], v[166:169]
	s_setprio 0
	s_setprio 1
	v_mfma_f32_16x16x32_bf16 v[8:11], v[120:123], v[178:181], v[8:11]
	v_mfma_f32_16x16x32_bf16 v[12:15], v[170:173], v[178:181], v[12:15]
	v_mfma_f32_16x16x32_bf16 v[24:27], v[120:123], v[186:189], v[60:63]
	v_mfma_f32_16x16x32_bf16 v[28:31], v[170:173], v[186:189], v[100:103]
	v_mfma_f32_16x16x32_bf16 v[60:63], v[120:123], v[194:197], v[104:107]
	v_mfma_f32_16x16x32_bf16 v[100:103], v[170:173], v[194:197], v[108:111]
	v_mfma_f32_16x16x32_bf16 v[16:19], v[120:123], v[202:205], v[16:19]
	v_mfma_f32_16x16x32_bf16 v[20:23], v[170:173], v[202:205], v[20:23]
	v_mfma_f32_16x16x32_bf16 v[8:11], v[124:127], v[182:185], v[8:11]
	v_mfma_f32_16x16x32_bf16 v[12:15], v[174:177], v[182:185], v[12:15]
	v_mfma_f32_16x16x32_bf16 v[24:27], v[124:127], v[190:193], v[24:27]
	v_mfma_f32_16x16x32_bf16 v[28:31], v[174:177], v[190:193], v[28:31]
	v_mfma_f32_16x16x32_bf16 v[60:63], v[124:127], v[198:201], v[60:63]
	v_mfma_f32_16x16x32_bf16 v[100:103], v[174:177], v[198:201], v[100:103]
	v_mfma_f32_16x16x32_bf16 v[16:19], v[124:127], v[206:209], v[16:19]
	v_mfma_f32_16x16x32_bf16 v[20:23], v[174:177], v[206:209], v[20:23]
	s_setprio 0
	s_barrier
	ds_read_b128 v[104:107], v141
	ds_read_b128 v[108:111], v141 offset:1024
	ds_read_b128 v[112:115], v141 offset:2048
	ds_read_b128 v[116:119], v141 offset:3072
	ds_read_b128 v[120:123], v142
	ds_read_b128 v[124:127], v142 offset:1024
	ds_read_b128 v[170:173], v142 offset:2048
	ds_read_b128 v[174:177], v142 offset:3072
	s_add_u32 s30, s28, 0x8000
	s_addc_u32 s31, s29, 0
	s_add_u32 s26, s26, 0x1c000
	s_addc_u32 s27, s27, 0
	s_mov_b32 m0, s46
	ds_read_b128 v[178:181], v143
	ds_read_b128 v[182:185], v143 offset:1024
	ds_read_b128 v[186:189], v143 offset:2048
	ds_read_b128 v[190:193], v143 offset:3072
	ds_read_b128 v[194:197], v143 offset:4096
	ds_read_b128 v[198:201], v143 offset:5120
	ds_read_b128 v[202:205], v143 offset:6144
	ds_read_b128 v[206:209], v143 offset:7168
	global_load_lds_dwordx4 v134, s[26:27]
	v_lshl_add_u64 v[210:211], s[26:27], 0, v[130:131]
	s_mov_b32 m0, s47
	s_nop 0
	global_load_lds_dwordx4 v[210:211], off
	s_waitcnt vmcnt(8)
	s_waitcnt lgkmcnt(0)
	s_barrier
	s_setprio 1
	s_waitcnt lgkmcnt(0)
	v_mfma_f32_16x16x32_bf16 v[64:67], v[104:107], v[178:181], v[64:67]
	v_mfma_f32_16x16x32_bf16 v[68:71], v[112:115], v[178:181], v[68:71]
	v_mfma_f32_16x16x32_bf16 v[72:75], v[104:107], v[186:189], v[72:75]
	v_mfma_f32_16x16x32_bf16 v[76:79], v[112:115], v[186:189], v[76:79]
	v_mfma_f32_16x16x32_bf16 v[80:83], v[104:107], v[194:197], v[80:83]
	v_mfma_f32_16x16x32_bf16 v[84:87], v[112:115], v[194:197], v[84:87]
	v_mfma_f32_16x16x32_bf16 v[88:91], v[104:107], v[202:205], v[88:91]
	v_mfma_f32_16x16x32_bf16 v[64:67], v[108:111], v[182:185], v[64:67]
	v_mfma_f32_16x16x32_bf16 v[68:71], v[116:119], v[182:185], v[68:71]
	v_mfma_f32_16x16x32_bf16 v[72:75], v[108:111], v[190:193], v[72:75]
	v_mfma_f32_16x16x32_bf16 v[76:79], v[116:119], v[190:193], v[76:79]
	v_mfma_f32_16x16x32_bf16 v[80:83], v[108:111], v[198:201], v[80:83]
	v_mfma_f32_16x16x32_bf16 v[84:87], v[116:119], v[198:201], v[84:87]
	v_mfma_f32_16x16x32_bf16 v[210:213], v[108:111], v[206:209], v[88:91]
	v_mfma_f32_16x16x32_bf16 v[88:91], v[112:115], v[202:205], v[92:95]
	v_mfma_f32_16x16x32_bf16 v[214:217], v[116:119], v[206:209], v[88:91]
	s_setprio 0
	s_setprio 1
	v_mfma_f32_16x16x32_bf16 v[88:91], v[120:123], v[178:181], v[96:99]
	v_mfma_f32_16x16x32_bf16 v[32:35], v[170:173], v[178:181], v[32:35]
	v_mfma_f32_16x16x32_bf16 v[36:39], v[120:123], v[186:189], v[36:39]
	v_mfma_f32_16x16x32_bf16 v[40:43], v[170:173], v[186:189], v[40:43]
	v_mfma_f32_16x16x32_bf16 v[44:47], v[120:123], v[194:197], v[44:47]
	v_mfma_f32_16x16x32_bf16 v[48:51], v[170:173], v[194:197], v[48:51]
	v_mfma_f32_16x16x32_bf16 v[52:55], v[120:123], v[202:205], v[52:55]
	v_mfma_f32_16x16x32_bf16 v[56:59], v[170:173], v[202:205], v[56:59]
	v_mfma_f32_16x16x32_bf16 v[96:99], v[124:127], v[182:185], v[88:91]
	v_mfma_f32_16x16x32_bf16 v[32:35], v[174:177], v[182:185], v[32:35]
	v_mfma_f32_16x16x32_bf16 v[36:39], v[124:127], v[190:193], v[36:39]
	v_mfma_f32_16x16x32_bf16 v[40:43], v[174:177], v[190:193], v[40:43]
	v_mfma_f32_16x16x32_bf16 v[44:47], v[124:127], v[198:201], v[44:47]
	v_mfma_f32_16x16x32_bf16 v[48:51], v[174:177], v[198:201], v[48:51]
	v_mfma_f32_16x16x32_bf16 v[52:55], v[124:127], v[206:209], v[52:55]
	v_mfma_f32_16x16x32_bf16 v[56:59], v[174:177], v[206:209], v[56:59]
	s_setprio 0
	s_barrier
; #define PG8_STAGE(bufoff, gbase, voff) do { _Pragma("unroll") for (int _i = 0; _i < 2; ++_i) \
;         __builtin_amdgcn_global_load_lds((const unsigned*)((const char*)(gbase) + (voff)[_i]), (PG8_LAS unsigned*)(lds + (bufoff) + ldsw + _i * 8192), 16, 0, 0); } while (0)
; #define PG8_LDA(dst, b, h) do { _Pragma("unroll") for (int m = 0; m < 4; ++m) _Pragma("unroll") for (int k = 0; k < 2; ++k) dst[m][k] = *(const PG8_LAS bf16x8*)(lds + PG8_SA(b, h) + aoff + m * 2048 + k * 1024); } while (0)
; #define PG8_LDB(dst, b, h) do { _Pragma("unroll") for (int n = 0; n < 2; ++n) _Pragma("unroll") for (int k = 0; k < 2; ++k) dst[n][k] = *(const PG8_LAS bf16x8*)(lds + PG8_SB(b, h) + boff + n * 2048 + k * 1024); } while (0)
; #define PG8_MMA(ai, bj, At, Bt) do { __builtin_amdgcn_s_setprio(1); _Pragma("unroll") for (int m = 0; m < 4; ++m) _Pragma("unroll") for (int n = 0; n < 2; ++n) _Pragma("unroll") for (int k = 0; k < 2; ++k) \
;         acc[ai][bj][m][n] = __builtin_amdgcn_mfma_f32_16x16x32_bf16(Bt[n][k], At[m][k], acc[ai][bj][m][n], 0, 0, 0); __builtin_amdgcn_s_setprio(0); } while (0)
; #define PG8_WAIT_V(n) asm volatile("s_waitcnt vmcnt(" #n ")" ::: "memory")
; #define PG8_WAIT_L(n) asm volatile("s_waitcnt lgkmcnt(" #n ")" ::: "memory")
; #define PG8_BAR __builtin_amdgcn_s_barrier()
; #define PG8_SCHED __builtin_amdgcn_sched_barrier(0)
;     ...
;             PG8_LDA(At, 0, 1); PG8_STAGE(PG8_SB(0, 0), b2, voffB); PG8_STAGE(PG8_SB(0, 1), b2 + hstepB, voffB); PG8_STAGE(PG8_SA(0, 0), a2, voffA);
;             PG8_WAIT_V(8); PG8_WAIT_L(0); PG8_BAR; PG8_MMA(1, 0, At, B0); PG8_MMA(1, 1, At, B1); PG8_BAR; PG8_SCHED;
;             PG8_LDB(B0, 1, 0); PG8_LDB(B1, 1, 1); PG8_SCHED; PG8_LDA(At, 1, 0); PG8_STAGE(PG8_SA(0, 1), a2 + hstepA, voffA);
;             PG8_WAIT_V(8); PG8_WAIT_L(0); PG8_BAR; PG8_MMA(0, 0, At, B0); PG8_MMA(0, 1, At, B1); PG8_BAR; PG8_SCHED;
	s_mov_b32 m0, s48
	v_lshl_add_u64 v[246:247], s[24:25], 0, v[132:133]
	s_add_u32 s26, s24, 0x10000
	ds_read_b128 v[88:91], v143 offset:16384
	ds_read_b128 v[92:95], v143 offset:17408
	ds_read_b128 v[178:181], v143 offset:18432
	ds_read_b128 v[182:185], v143 offset:19456
	ds_read_b128 v[186:189], v143 offset:20480
	ds_read_b128 v[190:193], v143 offset:21504
	ds_read_b128 v[194:197], v143 offset:22528
	ds_read_b128 v[198:201], v143 offset:23552
	global_load_lds_dwordx4 v[246:247], off
	v_lshl_add_u64 v[248:249], s[24:25], 0, v[128:129]
	s_mov_b32 m0, s50
	s_addc_u32 s27, s25, 0
	global_load_lds_dwordx4 v[248:249], off
	s_mov_b32 m0, s51
	s_nop 0
	global_load_lds_dwordx4 v132, s[26:27]
	s_mov_b32 m0, s52
	s_nop 0
	global_load_lds_dwordx4 v128, s[26:27]
	s_mov_b32 m0, s23
	s_nop 0
	global_load_lds_dwordx4 v134, s[28:29]
	v_lshl_add_u64 v[202:203], s[28:29], 0, v[130:131]
	s_mov_b32 m0, s37
	s_nop 0
	global_load_lds_dwordx4 v[202:203], off
	s_waitcnt vmcnt(8)
	s_waitcnt lgkmcnt(0)
	s_barrier
	s_setprio 1
	s_waitcnt lgkmcnt(0)
	v_mfma_f32_16x16x32_bf16 v[0:3], v[104:107], v[194:197], v[0:3]
	v_mfma_f32_16x16x32_bf16 v[4:7], v[112:115], v[194:197], v[4:7]
	v_mfma_f32_16x16x32_bf16 v[146:149], v[104:107], v[88:91], v[146:149]
	v_mfma_f32_16x16x32_bf16 v[150:153], v[112:115], v[88:91], v[150:153]
	v_mfma_f32_16x16x32_bf16 v[154:157], v[104:107], v[178:181], v[154:157]
	v_mfma_f32_16x16x32_bf16 v[158:161], v[112:115], v[178:181], v[158:161]
	v_mfma_f32_16x16x32_bf16 v[162:165], v[104:107], v[186:189], v[162:165]
	v_mfma_f32_16x16x32_bf16 v[166:169], v[112:115], v[186:189], v[166:169]
	v_mfma_f32_16x16x32_bf16 v[0:3], v[108:111], v[198:201], v[0:3]
	v_mfma_f32_16x16x32_bf16 v[4:7], v[116:119], v[198:201], v[4:7]
	v_mfma_f32_16x16x32_bf16 v[146:149], v[108:111], v[92:95], v[146:149]
	v_mfma_f32_16x16x32_bf16 v[150:153], v[116:119], v[92:95], v[150:153]
	v_mfma_f32_16x16x32_bf16 v[154:157], v[108:111], v[182:185], v[154:157]
	v_mfma_f32_16x16x32_bf16 v[158:161], v[116:119], v[182:185], v[158:161]
	v_mfma_f32_16x16x32_bf16 v[162:165], v[108:111], v[190:193], v[162:165]
	v_mfma_f32_16x16x32_bf16 v[166:169], v[116:119], v[190:193], v[166:169]
	s_setprio 0
	s_setprio 1
	v_mfma_f32_16x16x32_bf16 v[8:11], v[120:123], v[88:91], v[8:11]
	v_mfma_f32_16x16x32_bf16 v[202:205], v[124:127], v[92:95], v[8:11]
	v_mfma_f32_16x16x32_bf16 v[8:11], v[170:173], v[88:91], v[12:15]
	v_mfma_f32_16x16x32_bf16 v[206:209], v[174:177], v[92:95], v[8:11]
	v_mfma_f32_16x16x32_bf16 v[8:11], v[120:123], v[178:181], v[24:27]
	v_mfma_f32_16x16x32_bf16 v[218:221], v[124:127], v[182:185], v[8:11]
	v_mfma_f32_16x16x32_bf16 v[8:11], v[170:173], v[178:181], v[28:31]
	v_mfma_f32_16x16x32_bf16 v[178:181], v[174:177], v[182:185], v[8:11]
	v_mfma_f32_16x16x32_bf16 v[8:11], v[120:123], v[186:189], v[60:63]
	v_mfma_f32_16x16x32_bf16 v[182:185], v[124:127], v[190:193], v[8:11]
	v_mfma_f32_16x16x32_bf16 v[8:11], v[170:173], v[186:189], v[100:103]
	v_mfma_f32_16x16x32_bf16 v[186:189], v[174:177], v[190:193], v[8:11]
	v_mfma_f32_16x16x32_bf16 v[8:11], v[120:123], v[194:197], v[16:19]
	v_mfma_f32_16x16x32_bf16 v[190:193], v[124:127], v[198:201], v[8:11]
	v_mfma_f32_16x16x32_bf16 v[8:11], v[170:173], v[194:197], v[20:23]
	v_mfma_f32_16x16x32_bf16 v[170:173], v[174:177], v[198:201], v[8:11]
	s_setprio 0
	s_barrier
	s_nop 4
	ds_read_b128 v[8:11], v144
	ds_read_b128 v[12:15], v144 offset:1024
	ds_read_b128 v[16:19], v144 offset:2048
	ds_read_b128 v[20:23], v144 offset:3072
	ds_read_b128 v[174:177], v145
	ds_read_b128 v[194:197], v145 offset:1024
	ds_read_b128 v[198:201], v145 offset:2048
	ds_read_b128 v[222:225], v145 offset:3072
	s_add_u32 s26, s28, 0x4000
	s_addc_u32 s27, s29, 0
	s_mov_b32 m0, s39
	ds_read_b128 v[24:27], v143 offset:32768
	ds_read_b128 v[28:31], v143 offset:33792
	ds_read_b128 v[60:63], v143 offset:34816
	ds_read_b128 v[226:229], v143 offset:35840
	ds_read_b128 v[230:233], v143 offset:36864
	ds_read_b128 v[234:237], v143 offset:37888
	ds_read_b128 v[238:241], v143 offset:38912
	ds_read_b128 v[242:245], v143 offset:39936
	global_load_lds_dwordx4 v134, s[26:27]
	v_lshl_add_u64 v[88:89], s[26:27], 0, v[130:131]
	s_mov_b32 m0, s40
	s_nop 0
	global_load_lds_dwordx4 v[88:89], off
	s_waitcnt vmcnt(8)
	s_waitcnt lgkmcnt(0)
	s_barrier
; #define PG8_STAGE(bufoff, gbase, voff) do { _Pragma("unroll") for (int _i = 0; _i < 2; ++_i) \
;         __builtin_amdgcn_global_load_lds((const unsigned*)((const char*)(gbase) + (voff)[_i]), (PG8_LAS unsigned*)(lds + (bufoff) + ldsw + _i * 8192), 16, 0, 0); } while (0)
; #define PG8_LDA(dst, b, h) do { _Pragma("unroll") for (int m = 0; m < 4; ++m) _Pragma("unroll") for (int k = 0; k < 2; ++k) dst[m][k] = *(const PG8_LAS bf16x8*)(lds + PG8_SA(b, h) + aoff + m * 2048 + k * 1024); } while (0)
; #define PG8_MMA(ai, bj, At, Bt) do { __builtin_amdgcn_s_setprio(1); _Pragma("unroll") for (int m = 0; m < 4; ++m) _Pragma("unroll") for (int n = 0; n < 2; ++n) _Pragma("unroll") for (int k = 0; k < 2; ++k) \
;         acc[ai][bj][m][n] = __builtin_amdgcn_mfma_f32_16x16x32_bf16(Bt[n][k], At[m][k], acc[ai][bj][m][n], 0, 0, 0); __builtin_amdgcn_s_setprio(0); } while (0)
; #define PG8_WAIT_V(n) asm volatile("s_waitcnt vmcnt(" #n ")" ::: "memory")
; #define PG8_WAIT_L(n) asm volatile("s_waitcnt lgkmcnt(" #n ")" ::: "memory")
; #define PG8_BAR __builtin_amdgcn_s_barrier()
; #define PG8_SCHED __builtin_amdgcn_sched_barrier(0)
;     ...
;             PG8_LDA(At, 1, 1); PG8_STAGE(PG8_SB(1, 0), b3, voffB); PG8_STAGE(PG8_SB(1, 1), b3 + hstepB, voffB); PG8_STAGE(PG8_SA(1, 0), a3, voffA);
;             PG8_WAIT_V(8); PG8_WAIT_L(0); PG8_BAR; PG8_MMA(1, 0, At, B0); PG8_MMA(1, 1, At, B1); PG8_BAR; PG8_SCHED;
;     ...
;         if (!has_next) break;
; #pragma unroll
;         for (int a = 0; a < 2; ++a)
; #pragma unroll
;             for (int b = 0; b < 2; ++b)
; #pragma unroll
;                 for (int m = 0; m < 4; ++m)
; #pragma unroll
;                     for (int n = 0; n < 2; ++n) acc[a][b][m][n] = (f32x4){0.f, 0.f, 0.f, 0.f};
;         cur = nxt; cA = nA; cB = nB; ++ui;
;         if constexpr (ALIGN_EPI) { if (wr == 1) PG8_BAR; }
	s_setprio 1
	s_waitcnt lgkmcnt(0)
	v_mfma_f32_16x16x32_bf16 v[64:67], v[8:11], v[24:27], v[64:67]
	v_mfma_f32_16x16x32_bf16 v[124:127], v[12:15], v[28:31], v[64:67]
	v_mfma_f32_16x16x32_bf16 v[64:67], v[16:19], v[24:27], v[68:71]
	v_mfma_f32_16x16x32_bf16 v[120:123], v[20:23], v[28:31], v[64:67]
	v_mfma_f32_16x16x32_bf16 v[64:67], v[8:11], v[60:63], v[72:75]
	v_mfma_f32_16x16x32_bf16 v[108:111], v[12:15], v[226:229], v[64:67]
	v_mfma_f32_16x16x32_bf16 v[64:67], v[16:19], v[60:63], v[76:79]
	v_mfma_f32_16x16x32_bf16 v[104:107], v[20:23], v[226:229], v[64:67]
	v_mfma_f32_16x16x32_bf16 v[64:67], v[8:11], v[230:233], v[80:83]
	v_mfma_f32_16x16x32_bf16 v[92:95], v[12:15], v[234:237], v[64:67]
	v_mfma_f32_16x16x32_bf16 v[64:67], v[16:19], v[230:233], v[84:87]
	v_mfma_f32_16x16x32_bf16 v[88:91], v[20:23], v[234:237], v[64:67]
	v_mfma_f32_16x16x32_bf16 v[64:67], v[8:11], v[238:241], v[210:213]
	v_mfma_f32_16x16x32_bf16 v[76:79], v[12:15], v[242:245], v[64:67]
	v_mfma_f32_16x16x32_bf16 v[64:67], v[16:19], v[238:241], v[214:217]
	v_mfma_f32_16x16x32_bf16 v[72:75], v[20:23], v[242:245], v[64:67]
	s_setprio 0
	s_setprio 1
	v_mfma_f32_16x16x32_bf16 v[64:67], v[174:177], v[24:27], v[96:99]
	v_mfma_f32_16x16x32_bf16 v[24:27], v[198:201], v[24:27], v[32:35]
	v_mfma_f32_16x16x32_bf16 v[112:115], v[222:225], v[28:31], v[24:27]
	v_mfma_f32_16x16x32_bf16 v[24:27], v[174:177], v[60:63], v[36:39]
	v_mfma_f32_16x16x32_bf16 v[100:103], v[194:197], v[226:229], v[24:27]
	v_mfma_f32_16x16x32_bf16 v[24:27], v[198:201], v[60:63], v[40:43]
	v_mfma_f32_16x16x32_bf16 v[96:99], v[222:225], v[226:229], v[24:27]
	v_mfma_f32_16x16x32_bf16 v[24:27], v[174:177], v[230:233], v[44:47]
	v_mfma_f32_16x16x32_bf16 v[84:87], v[194:197], v[234:237], v[24:27]
	v_mfma_f32_16x16x32_bf16 v[24:27], v[198:201], v[230:233], v[48:51]
	v_mfma_f32_16x16x32_bf16 v[80:83], v[222:225], v[234:237], v[24:27]
	v_mfma_f32_16x16x32_bf16 v[24:27], v[174:177], v[238:241], v[52:55]
	v_mfma_f32_16x16x32_bf16 v[60:63], v[194:197], v[242:245], v[24:27]
	v_mfma_f32_16x16x32_bf16 v[24:27], v[198:201], v[238:241], v[56:59]
	v_mfma_f32_16x16x32_bf16 v[116:119], v[194:197], v[28:31], v[64:67]
	v_mfma_f32_16x16x32_bf16 v[56:59], v[222:225], v[242:245], v[24:27]
	s_setprio 0
	s_barrier
	s_mov_b32 m0, s53
	s_nop 2
	v_lshl_add_u64 v[24:25], v[246:247], 0, s[12:13]
	s_add_u32 s24, s24, 0x10080
	ds_read_b128 v[32:35], v143 offset:49152
	ds_read_b128 v[36:39], v143 offset:50176
	ds_read_b128 v[210:213], v143 offset:51200
	ds_read_b128 v[214:217], v143 offset:52224
	ds_read_b128 v[226:229], v143 offset:53248
	ds_read_b128 v[230:233], v143 offset:54272
	ds_read_b128 v[234:237], v143 offset:55296
	ds_read_b128 v[238:241], v143 offset:56320
	global_load_lds_dwordx4 v[24:25], off
	v_lshl_add_u64 v[24:25], v[248:249], 0, s[12:13]
	s_mov_b32 m0, s54
	s_addc_u32 s25, s25, 0
	global_load_lds_dwordx4 v[24:25], off
	s_mov_b32 m0, s55
	s_nop 0
	global_load_lds_dwordx4 v132, s[24:25]
	s_mov_b32 m0, s56
	s_nop 0
	global_load_lds_dwordx4 v128, s[24:25]
	s_mov_b32 m0, s42
	s_nop 0
	global_load_lds_dwordx4 v134, s[30:31]
	v_lshl_add_u64 v[24:25], s[30:31], 0, v[130:131]
	s_mov_b32 m0, s43
	s_nop 0
	global_load_lds_dwordx4 v[24:25], off
	s_waitcnt vmcnt(8)
	s_waitcnt lgkmcnt(0)
	s_barrier
	s_setprio 1
	s_waitcnt lgkmcnt(0)
	v_mfma_f32_16x16x32_bf16 v[24:27], v[8:11], v[32:35], v[146:149]
	v_mfma_f32_16x16x32_bf16 v[68:71], v[12:15], v[36:39], v[24:27]
	v_mfma_f32_16x16x32_bf16 v[24:27], v[16:19], v[32:35], v[150:153]
	v_mfma_f32_16x16x32_bf16 v[64:67], v[20:23], v[36:39], v[24:27]
	v_mfma_f32_16x16x32_bf16 v[24:27], v[8:11], v[210:213], v[154:157]
	v_mfma_f32_16x16x32_bf16 v[44:47], v[12:15], v[214:217], v[24:27]
	v_mfma_f32_16x16x32_bf16 v[24:27], v[16:19], v[210:213], v[158:161]
	v_mfma_f32_16x16x32_bf16 v[40:43], v[20:23], v[214:217], v[24:27]
	v_mfma_f32_16x16x32_bf16 v[24:27], v[8:11], v[226:229], v[162:165]
	v_mfma_f32_16x16x32_bf16 v[0:3], v[8:11], v[234:237], v[0:3]
	v_mfma_f32_16x16x32_bf16 v[28:31], v[12:15], v[230:233], v[24:27]
	v_mfma_f32_16x16x32_bf16 v[24:27], v[16:19], v[226:229], v[166:169]
	v_mfma_f32_16x16x32_bf16 v[12:15], v[12:15], v[238:241], v[0:3]
	v_mfma_f32_16x16x32_bf16 v[0:3], v[16:19], v[234:237], v[4:7]
	v_mfma_f32_16x16x32_bf16 v[24:27], v[20:23], v[230:233], v[24:27]
	v_mfma_f32_16x16x32_bf16 v[8:11], v[20:23], v[238:241], v[0:3]
	s_setprio 0
	s_setprio 1
	v_mfma_f32_16x16x32_bf16 v[0:3], v[174:177], v[32:35], v[202:205]
	v_mfma_f32_16x16x32_bf16 v[52:55], v[194:197], v[36:39], v[0:3]
	v_mfma_f32_16x16x32_bf16 v[0:3], v[198:201], v[32:35], v[206:209]
	v_mfma_f32_16x16x32_bf16 v[48:51], v[222:225], v[36:39], v[0:3]
	v_mfma_f32_16x16x32_bf16 v[0:3], v[174:177], v[210:213], v[218:221]
	v_mfma_f32_16x16x32_bf16 v[36:39], v[194:197], v[214:217], v[0:3]
	v_mfma_f32_16x16x32_bf16 v[0:3], v[198:201], v[210:213], v[178:181]
	v_mfma_f32_16x16x32_bf16 v[32:35], v[222:225], v[214:217], v[0:3]
	v_mfma_f32_16x16x32_bf16 v[0:3], v[174:177], v[226:229], v[182:185]
	v_mfma_f32_16x16x32_bf16 v[20:23], v[194:197], v[230:233], v[0:3]
	v_mfma_f32_16x16x32_bf16 v[0:3], v[198:201], v[226:229], v[186:189]
	v_mfma_f32_16x16x32_bf16 v[16:19], v[222:225], v[230:233], v[0:3]
	v_mfma_f32_16x16x32_bf16 v[0:3], v[174:177], v[234:237], v[190:193]
	v_mfma_f32_16x16x32_bf16 v[4:7], v[194:197], v[238:241], v[0:3]
	v_mfma_f32_16x16x32_bf16 v[0:3], v[198:201], v[234:237], v[170:173]
	v_mfma_f32_16x16x32_bf16 v[0:3], v[222:225], v[238:241], v[0:3]
	s_setprio 0
	s_barrier
	s_and_b64 vcc, exec, s[0:1]
	s_cbranch_vccnz .LBB0_99
	s_barrier

; #define PG8_STAGE(bufoff, gbase, voff) do { _Pragma("unroll") for (int _i = 0; _i < 2; ++_i) \
;         __builtin_amdgcn_global_load_lds((const unsigned*)((const char*)(gbase) + (voff)[_i]), (PG8_LAS unsigned*)(lds + (bufoff) + ldsw + _i * 8192), 16, 0, 0); } while (0)
; #define PG8_WAIT_V(n) asm volatile("s_waitcnt vmcnt(" #n ")" ::: "memory")
; #define PG8_BAR __builtin_amdgcn_s_barrier()
;     __device__ __forceinline__ size_t b_off(const pg8::Unit& u) const { return (size_t)(u.pm >> 3) * 4 * 131072; }
;     ...
;     const char* cA = (const char*)g.A + (size_t)cur.pm * tstepA + (size_t)cur.pn * APN + kofA; const char* cB = (const char*)g.Bt + (size_t)cur.pn * tstepB + S.b_off(cur) + kofB;
;     S.a_ready(cur);
;     if constexpr (SP2) {
;         PG8_STAGE(PG8_SB(0, 0), cB, voffB); PG8_STAGE(PG8_SB(0, 1), cB + hstepB, voffB); PG8_STAGE(PG8_SA(0, 0), cA, voffA); PG8_STAGE(PG8_SA(0, 1), cA + hstepA, voffA);
;         P();
;         if (wr == 1) PG8_BAR;
;         PG8_WAIT_V(2); PG8_BAR;
;         PG8_STAGE(PG8_SB(1, 0), cB + kstep, voffB); PG8_STAGE(PG8_SA(1, 0), cA + kstepA, voffA); PG8_STAGE(PG8_SB(1, 1), cB + hstepB + kstep, voffB);
;         PG8_WAIT_V(6); PG8_BAR;
;     } else {
;         PG8_STAGE(PG8_SB(0, 0), cB, voffB); PG8_STAGE(PG8_SA(0, 0), cA, voffA); PG8_STAGE(PG8_SB(0, 1), cB + hstepB, voffB); PG8_STAGE(PG8_SA(0, 1), cA + hstepA, voffA);
;         if (wr == 1) PG8_BAR;
;         PG8_WAIT_V(4); PG8_BAR;
;         PG8_STAGE(PG8_SB(1, 0), cB + kstep, voffB); PG8_STAGE(PG8_SA(1, 0), cA + kstepA, voffA); PG8_STAGE(PG8_SB(1, 1), cB + hstepB + kstep, voffB);
;         PG8_WAIT_V(6); PG8_BAR;
;     }
.LBB0_322:
	v_readlane_b32 s18, v255, 0
	v_readlane_b32 s19, v255, 1
	s_mov_b32 s20, s18
	s_mul_i32 s19, s20, 0x14000
	s_mul_hi_u32 s18, s18, 0x14000
	s_add_u32 s19, s67, s19
	s_addc_u32 s18, s33, s18
	s_add_u32 s70, s19, 0x204000
	s_addc_u32 s83, s18, 0
	s_lshl_b32 s44, s20, 10
	s_lshl_b64 s[18:19], s[44:45], 2
	s_add_u32 s18, s67, s18
	s_addc_u32 s19, s33, s19
	s_add_u32 s18, s18, 0x1c0000
	s_addc_u32 s19, s19, 0
	s_add_u32 s20, s67, 0x32a04000
	s_addc_u32 s21, s33, 0
	s_add_u32 s22, s67, 0x36a04000
	s_addc_u32 s23, s33, 0
	s_add_u32 s24, s67, 0x38a04000
	s_addc_u32 s25, s33, 0
	s_lshl_b32 s27, s27, 5
	s_and_b32 s81, s27, 0x60
	s_lshl_b32 s44, s9, 6
	s_lshl_b32 s30, s9, 13
	s_lshl_b32 s27, s81, 7
	s_add_u32 s28, s86, 0x8000
	s_addc_u32 s29, s87, 0
	s_add_i32 m0, s51, 0x18000
	s_waitcnt vmcnt(2)
	s_barrier
	global_load_lds_dwordx4 v0, s[28:29]
	s_add_i32 m0, s51, 0x1a000
	v_lshl_add_u64 v[10:11], s[28:29], 0, v[162:163]
	s_add_u32 s28, s6, 0x8000
	s_addc_u32 s29, s7, 0
	s_add_i32 s71, s51, 0x8000
	global_load_lds_dwordx4 v[10:11], off
	s_mov_b32 m0, s71
	s_add_i32 s80, s51, 0xa000
	global_load_lds_dwordx4 v166, s[28:29]
	v_lshl_add_u64 v[10:11], s[28:29], 0, v[164:165]
	s_add_u32 s28, s86, 0xc000
	s_mov_b32 m0, s80
	s_addc_u32 s29, s87, 0
	global_load_lds_dwordx4 v[10:11], off
	s_add_i32 m0, s51, 0x1c000
	s_nop 0
	global_load_lds_dwordx4 v0, s[28:29]
	v_lshl_add_u64 v[10:11], s[28:29], 0, v[162:163]
	s_add_i32 m0, s51, 0x1e000
	v_and_b32_e32 v9, 48, v2
	global_load_lds_dwordx4 v[10:11], off
	v_lshlrev_b32_e32 v10, 6, v2
	s_movk_i32 s28, 0x3c0
	v_lshlrev_b32_e32 v2, 2, v2
	v_and_or_b32 v9, v10, s28, v9
	v_and_b32_e32 v2, 32, v2
	v_bitop3_b32 v10, v9, s30, v2 bitop3:0xde
	v_bitop3_b32 v182, s27, v9, v2 bitop3:0xf6
	v_lshlrev_b32_e32 v2, 10, v7
	v_and_b32_e32 v2, 0xfffff800, v2
	v_lshl_add_u32 v2, v6, 7, v2
	v_and_b32_e32 v6, 1, v7
	v_lshl_or_b32 v2, v6, 6, v2
	v_lshl_add_u32 v168, v8, 1, v2
	v_lshlrev_b32_e32 v2, 10, v3
	s_cmpk_lt_u32 s26, 0x100
	v_and_b32_e32 v2, 0xfffff800, v2
	s_waitcnt vmcnt(6)
	s_cselect_b64 s[26:27], -1, 0
	s_lshl_b32 s9, s9, 8
	v_lshl_add_u32 v2, v4, 7, v2
	v_and_b32_e32 v3, 1, v3
	s_add_i32 s68, s9, 0
	v_lshl_or_b32 v2, v3, 6, v2
	s_add_i32 s68, s68, 0x20400
	v_mov_b32_e32 v169, v1
	v_lshl_add_u32 v170, v5, 1, v2
	v_mov_b32_e32 v171, v1
	s_mov_b32 s9, 0
	v_add_u32_e32 v183, 0, v10
	s_barrier
	s_branch .LBB0_325

; #define PG8_STAGE(bufoff, gbase, voff) do { _Pragma("unroll") for (int _i = 0; _i < 2; ++_i) \
;         __builtin_amdgcn_global_load_lds((const unsigned*)((const char*)(gbase) + (voff)[_i]), (PG8_LAS unsigned*)(lds + (bufoff) + ldsw + _i * 8192), 16, 0, 0); } while (0)
; #define PG8_LDA(dst, b, h) do { _Pragma("unroll") for (int m = 0; m < 4; ++m) _Pragma("unroll") for (int k = 0; k < 2; ++k) dst[m][k] = *(const PG8_LAS bf16x8*)(lds + PG8_SA(b, h) + aoff + m * 2048 + k * 1024); } while (0)
; #define PG8_LDB(dst, b, h) do { _Pragma("unroll") for (int n = 0; n < 2; ++n) _Pragma("unroll") for (int k = 0; k < 2; ++k) dst[n][k] = *(const PG8_LAS bf16x8*)(lds + PG8_SB(b, h) + boff + n * 2048 + k * 1024); } while (0)
; #define PG8_MMA(ai, bj, At, Bt) do { __builtin_amdgcn_s_setprio(1); _Pragma("unroll") for (int m = 0; m < 4; ++m) _Pragma("unroll") for (int n = 0; n < 2; ++n) _Pragma("unroll") for (int k = 0; k < 2; ++k) \
;         acc[ai][bj][m][n] = __builtin_amdgcn_mfma_f32_16x16x32_bf16(Bt[n][k], At[m][k], acc[ai][bj][m][n], 0, 0, 0); __builtin_amdgcn_s_setprio(0); } while (0)
; #define PG8_WAIT_V(n) asm volatile("s_waitcnt vmcnt(" #n ")" ::: "memory")
; #define PG8_WAIT_L(n) asm volatile("s_waitcnt lgkmcnt(" #n ")" ::: "memory")
; #define PG8_BAR __builtin_amdgcn_s_barrier()
;     ...
;         for (int t = 0; t < nt; t += 2) {
;             const bool last = (t == nt - 2);
;             const char* a1 = cA + (ptrdiff_t)(t + 1) * kstepA;
;             const char* a2 = last ? nA : cA + (ptrdiff_t)(t + 2) * kstepA; const char* b2 = last ? nB : cB + (ptrdiff_t)(t + 2) * kstep;
;             const char* a3 = a2 + kstepA; const char* b3 = b2 + kstep;
;             if (last && has_next) S.a_ready(nxt);
;             if constexpr (SP2) {
;             PG8_LDB(B0, 0, 0); PG8_LDB(B1, 0, 1); PG8_SCHED; PG8_LDA(At, 0, 0); PG8_STAGE(PG8_SA(1, 1), a1 + hstepA, voffA);
;             PG8_WAIT_V(8); PG8_WAIT_L(0); PG8_BAR; PG8_MMA(0, 0, At, B0); PG8_MMA(0, 1, At, B1); PG8_BAR; PG8_SCHED;
;             PG8_LDA(At, 0, 1); PG8_STAGE(PG8_SB(0, 0), b2, voffB); PG8_STAGE(PG8_SB(0, 1), b2 + hstepB, voffB); PG8_STAGE(PG8_SA(0, 0), a2, voffA);
;             PG8_WAIT_V(8); PG8_WAIT_L(0); PG8_BAR; PG8_MMA(1, 0, At, B0); PG8_MMA(1, 1, At, B1); PG8_BAR; PG8_SCHED;
;             PG8_LDB(B0, 1, 0); PG8_LDB(B1, 1, 1); PG8_SCHED; PG8_LDA(At, 1, 0); PG8_STAGE(PG8_SA(0, 1), a2 + hstepA, voffA);
.LBB0_328:
	s_add_u32 s65, s6, 0x4000
	s_addc_u32 s66, s7, 0
	s_cmp_eq_u32 vcc_lo, 28
	s_cselect_b32 s90, s54, s65
	s_cselect_b32 s91, s29, s66
	s_cselect_b32 s88, s55, s56
	s_cselect_b32 s89, s31, s57
	s_add_u32 s86, s90, 0x8000
	s_addc_u32 s87, s91, 0
	s_add_i32 s65, 0, 0x10000
	s_add_i32 s66, 0, 0x14000
	v_add_u32_e32 v22, s65, v182
	v_add_u32_e32 v54, s66, v182
	ds_read_b128 v[10:13], v22
	ds_read_b128 v[14:17], v22 offset:1024
	ds_read_b128 v[18:21], v22 offset:2048
	ds_read_b128 v[22:25], v22 offset:3072
	ds_read_b128 v[26:29], v54
	ds_read_b128 v[38:41], v54 offset:1024
	ds_read_b128 v[50:53], v54 offset:2048
	ds_read_b128 v[54:57], v54 offset:3072
	s_add_i32 m0, s51, 0xc000
	ds_read_b128 v[172:175], v183
	ds_read_b128 v[176:179], v183 offset:1024
	ds_read_b128 v[184:187], v183 offset:2048
	ds_read_b128 v[188:191], v183 offset:3072
	ds_read_b128 v[192:195], v183 offset:4096
	ds_read_b128 v[196:199], v183 offset:5120
	ds_read_b128 v[200:203], v183 offset:6144
	ds_read_b128 v[204:207], v183 offset:7168
	global_load_lds_dwordx4 v168, s[6:7]
	s_add_i32 m0, s51, 0xe000
	s_nop 0
	global_load_lds_dwordx4 v170, s[6:7]
	s_waitcnt vmcnt(8)
	s_waitcnt lgkmcnt(0)
	s_barrier
	s_setprio 1
	s_waitcnt lgkmcnt(0)
	v_mfma_f32_16x16x32_bf16 v[158:161], v[10:13], v[172:175], v[158:161]
	v_mfma_f32_16x16x32_bf16 v[154:157], v[18:21], v[172:175], v[154:157]
	v_mfma_f32_16x16x32_bf16 v[142:145], v[10:13], v[184:187], v[142:145]
	v_mfma_f32_16x16x32_bf16 v[138:141], v[18:21], v[184:187], v[138:141]
	v_mfma_f32_16x16x32_bf16 v[126:129], v[10:13], v[192:195], v[126:129]
	v_mfma_f32_16x16x32_bf16 v[122:125], v[18:21], v[192:195], v[122:125]
	v_mfma_f32_16x16x32_bf16 v[110:113], v[10:13], v[200:203], v[110:113]
	v_mfma_f32_16x16x32_bf16 v[106:109], v[18:21], v[200:203], v[106:109]
	v_mfma_f32_16x16x32_bf16 v[158:161], v[14:17], v[176:179], v[158:161]
	v_mfma_f32_16x16x32_bf16 v[154:157], v[22:25], v[176:179], v[154:157]
	v_mfma_f32_16x16x32_bf16 v[142:145], v[14:17], v[188:191], v[142:145]
	v_mfma_f32_16x16x32_bf16 v[138:141], v[22:25], v[188:191], v[138:141]
	v_mfma_f32_16x16x32_bf16 v[126:129], v[14:17], v[196:199], v[126:129]
	v_mfma_f32_16x16x32_bf16 v[122:125], v[22:25], v[196:199], v[122:125]
	v_mfma_f32_16x16x32_bf16 v[110:113], v[14:17], v[204:207], v[110:113]
	v_mfma_f32_16x16x32_bf16 v[106:109], v[22:25], v[204:207], v[106:109]
	s_setprio 0
	s_setprio 1
	v_mfma_f32_16x16x32_bf16 v[150:153], v[26:29], v[172:175], v[150:153]
	v_mfma_f32_16x16x32_bf16 v[146:149], v[50:53], v[172:175], v[146:149]
	v_mfma_f32_16x16x32_bf16 v[134:137], v[26:29], v[184:187], v[134:137]
	v_mfma_f32_16x16x32_bf16 v[130:133], v[50:53], v[184:187], v[130:133]
	v_mfma_f32_16x16x32_bf16 v[118:121], v[26:29], v[192:195], v[118:121]
	v_mfma_f32_16x16x32_bf16 v[114:117], v[50:53], v[192:195], v[114:117]
	v_mfma_f32_16x16x32_bf16 v[102:105], v[26:29], v[200:203], v[102:105]
	v_mfma_f32_16x16x32_bf16 v[98:101], v[50:53], v[200:203], v[98:101]
	v_mfma_f32_16x16x32_bf16 v[150:153], v[38:41], v[176:179], v[150:153]
	v_mfma_f32_16x16x32_bf16 v[146:149], v[54:57], v[176:179], v[146:149]
	v_mfma_f32_16x16x32_bf16 v[134:137], v[38:41], v[188:191], v[134:137]
	v_mfma_f32_16x16x32_bf16 v[130:133], v[54:57], v[188:191], v[130:133]
	v_mfma_f32_16x16x32_bf16 v[118:121], v[38:41], v[196:199], v[118:121]
	v_mfma_f32_16x16x32_bf16 v[114:117], v[54:57], v[196:199], v[114:117]
	v_mfma_f32_16x16x32_bf16 v[102:105], v[38:41], v[204:207], v[102:105]
	v_mfma_f32_16x16x32_bf16 v[98:101], v[54:57], v[204:207], v[98:101]
	s_setprio 0
	s_barrier
	s_add_i32 s65, s65, s2
	s_mov_b32 m0, s65
	ds_read_b128 v[172:175], v183 offset:16384
	ds_read_b128 v[176:179], v183 offset:17408
	ds_read_b128 v[184:187], v183 offset:18432
	ds_read_b128 v[188:191], v183 offset:19456
	ds_read_b128 v[192:195], v183 offset:20480
	ds_read_b128 v[196:199], v183 offset:21504
	ds_read_b128 v[200:203], v183 offset:22528
	ds_read_b128 v[204:207], v183 offset:23552
	global_load_lds_dwordx4 v0, s[88:89]
	s_add_i32 m0, s65, 0x2000
	s_add_u32 s96, s88, 0x4000
	s_addc_u32 s97, s89, 0
	s_add_i32 s65, s66, s2
	global_load_lds_dwordx4 v162, s[88:89]
	s_mov_b32 m0, s65
	s_nop 0
	global_load_lds_dwordx4 v0, s[96:97]
	s_add_i32 m0, s65, 0x2000
	s_nop 0
	global_load_lds_dwordx4 v162, s[96:97]
	s_mov_b32 m0, s51
	s_nop 0
	global_load_lds_dwordx4 v166, s[90:91]
	s_mov_b32 m0, s92
	s_nop 0
	global_load_lds_dwordx4 v164, s[90:91]
	s_waitcnt vmcnt(8)
	s_waitcnt lgkmcnt(0)
	s_barrier
	s_setprio 1
	s_waitcnt lgkmcnt(0)
	v_mfma_f32_16x16x32_bf16 v[94:97], v[10:13], v[172:175], v[94:97]
	v_mfma_f32_16x16x32_bf16 v[90:93], v[18:21], v[172:175], v[90:93]
	v_mfma_f32_16x16x32_bf16 v[78:81], v[10:13], v[184:187], v[78:81]
	v_mfma_f32_16x16x32_bf16 v[74:77], v[18:21], v[184:187], v[74:77]
	v_mfma_f32_16x16x32_bf16 v[62:65], v[10:13], v[192:195], v[62:65]
	v_mfma_f32_16x16x32_bf16 v[58:61], v[18:21], v[192:195], v[58:61]
	v_mfma_f32_16x16x32_bf16 v[10:13], v[10:13], v[200:203], v[34:37]
	v_mfma_f32_16x16x32_bf16 v[94:97], v[14:17], v[176:179], v[94:97]
	v_mfma_f32_16x16x32_bf16 v[90:93], v[22:25], v[176:179], v[90:93]
	v_mfma_f32_16x16x32_bf16 v[78:81], v[14:17], v[188:191], v[78:81]
	v_mfma_f32_16x16x32_bf16 v[74:77], v[22:25], v[188:191], v[74:77]
	v_mfma_f32_16x16x32_bf16 v[62:65], v[14:17], v[196:199], v[62:65]
	v_mfma_f32_16x16x32_bf16 v[58:61], v[22:25], v[196:199], v[58:61]
	v_mfma_f32_16x16x32_bf16 v[10:13], v[14:17], v[204:207], v[10:13]
	v_mfma_f32_16x16x32_bf16 v[14:17], v[18:21], v[200:203], v[30:33]
	v_mfma_f32_16x16x32_bf16 v[14:17], v[22:25], v[204:207], v[14:17]
	s_setprio 0
	s_setprio 1
	v_mfma_f32_16x16x32_bf16 v[30:33], v[26:29], v[184:187], v[70:73]
	v_mfma_f32_16x16x32_bf16 v[70:73], v[38:41], v[188:191], v[30:33]
	v_mfma_f32_16x16x32_bf16 v[30:33], v[50:53], v[184:187], v[66:69]
	v_mfma_f32_16x16x32_bf16 v[66:69], v[54:57], v[188:191], v[30:33]
	v_mfma_f32_16x16x32_bf16 v[30:33], v[26:29], v[192:195], v[46:49]
	v_mfma_f32_16x16x32_bf16 v[46:49], v[38:41], v[196:199], v[30:33]
	v_mfma_f32_16x16x32_bf16 v[30:33], v[50:53], v[192:195], v[42:45]
	v_mfma_f32_16x16x32_bf16 v[6:9], v[26:29], v[200:203], v[6:9]
	v_mfma_f32_16x16x32_bf16 v[2:5], v[50:53], v[200:203], v[2:5]
	v_mfma_f32_16x16x32_bf16 v[18:21], v[26:29], v[172:175], v[86:89]
	v_mfma_f32_16x16x32_bf16 v[22:25], v[50:53], v[172:175], v[82:85]
	v_mfma_f32_16x16x32_bf16 v[42:45], v[54:57], v[196:199], v[30:33]
	v_mfma_f32_16x16x32_bf16 v[6:9], v[38:41], v[204:207], v[6:9]
	v_mfma_f32_16x16x32_bf16 v[2:5], v[54:57], v[204:207], v[2:5]
	v_mfma_f32_16x16x32_bf16 v[18:21], v[38:41], v[176:179], v[18:21]
	v_mfma_f32_16x16x32_bf16 v[22:25], v[54:57], v[176:179], v[22:25]
	s_setprio 0
	s_barrier
; #define PG8_STAGE(bufoff, gbase, voff) do { _Pragma("unroll") for (int _i = 0; _i < 2; ++_i) \
;         __builtin_amdgcn_global_load_lds((const unsigned*)((const char*)(gbase) + (voff)[_i]), (PG8_LAS unsigned*)(lds + (bufoff) + ldsw + _i * 8192), 16, 0, 0); } while (0)
; #define PG8_LDA(dst, b, h) do { _Pragma("unroll") for (int m = 0; m < 4; ++m) _Pragma("unroll") for (int k = 0; k < 2; ++k) dst[m][k] = *(const PG8_LAS bf16x8*)(lds + PG8_SA(b, h) + aoff + m * 2048 + k * 1024); } while (0)
; #define PG8_LDB(dst, b, h) do { _Pragma("unroll") for (int n = 0; n < 2; ++n) _Pragma("unroll") for (int k = 0; k < 2; ++k) dst[n][k] = *(const PG8_LAS bf16x8*)(lds + PG8_SB(b, h) + boff + n * 2048 + k * 1024); } while (0)
; #define PG8_MMA(ai, bj, At, Bt) do { __builtin_amdgcn_s_setprio(1); _Pragma("unroll") for (int m = 0; m < 4; ++m) _Pragma("unroll") for (int n = 0; n < 2; ++n) _Pragma("unroll") for (int k = 0; k < 2; ++k) \
;         acc[ai][bj][m][n] = __builtin_amdgcn_mfma_f32_16x16x32_bf16(Bt[n][k], At[m][k], acc[ai][bj][m][n], 0, 0, 0); __builtin_amdgcn_s_setprio(0); } while (0)
; #define PG8_WAIT_V(n) asm volatile("s_waitcnt vmcnt(" #n ")" ::: "memory")
; #define PG8_WAIT_L(n) asm volatile("s_waitcnt lgkmcnt(" #n ")" ::: "memory")
; #define PG8_BAR __builtin_amdgcn_s_barrier()
; #define PG8_SCHED __builtin_amdgcn_sched_barrier(0)
;     ...
;             PG8_LDB(B0, 1, 0); PG8_LDB(B1, 1, 1); PG8_SCHED; PG8_LDA(At, 1, 0); PG8_STAGE(PG8_SA(0, 1), a2 + hstepA, voffA);
;             PG8_WAIT_V(8); PG8_WAIT_L(0); PG8_BAR; PG8_MMA(0, 0, At, B0); PG8_MMA(0, 1, At, B1); PG8_BAR; PG8_SCHED;
;             PG8_LDA(At, 1, 1); PG8_STAGE(PG8_SB(1, 0), b3, voffB); PG8_STAGE(PG8_SB(1, 1), b3 + hstepB, voffB); PG8_STAGE(PG8_SA(1, 0), a3, voffA);
;             PG8_WAIT_V(8); PG8_WAIT_L(0); PG8_BAR; PG8_MMA(1, 0, At, B0); PG8_MMA(1, 1, At, B1); PG8_BAR; PG8_SCHED;
	s_add_i32 s65, 0, 0x18000
	v_add_u32_e32 v34, s65, v182
	s_add_i32 s66, 0, 0x1c000
	ds_read_b128 v[26:29], v34
	ds_read_b128 v[30:33], v34 offset:1024
	ds_read_b128 v[38:41], v34 offset:2048
	ds_read_b128 v[50:53], v34 offset:3072
	v_add_u32_e32 v34, s66, v182
	ds_read_b128 v[54:57], v34
	ds_read_b128 v[172:175], v34 offset:1024
	ds_read_b128 v[176:179], v34 offset:2048
	ds_read_b128 v[184:187], v34 offset:3072
	s_add_u32 s90, s90, 0x4000
	s_addc_u32 s91, s91, 0
	s_mov_b32 m0, s14
	ds_read_b128 v[34:37], v183 offset:32768
	ds_read_b128 v[82:85], v183 offset:33792
	ds_read_b128 v[86:89], v183 offset:34816
	ds_read_b128 v[188:191], v183 offset:35840
	ds_read_b128 v[192:195], v183 offset:36864
	ds_read_b128 v[196:199], v183 offset:37888
	ds_read_b128 v[200:203], v183 offset:38912
	ds_read_b128 v[204:207], v183 offset:39936
	global_load_lds_dwordx4 v166, s[90:91]
	v_lshl_add_u64 v[208:209], s[90:91], 0, v[164:165]
	s_mov_b32 m0, s15
	s_nop 0
	global_load_lds_dwordx4 v[208:209], off
	s_waitcnt vmcnt(8)
	s_waitcnt lgkmcnt(0)
	s_barrier
	s_setprio 1
	s_waitcnt lgkmcnt(0)
	v_mfma_f32_16x16x32_bf16 v[158:161], v[26:29], v[34:37], v[158:161]
	v_mfma_f32_16x16x32_bf16 v[154:157], v[38:41], v[34:37], v[154:157]
	v_mfma_f32_16x16x32_bf16 v[142:145], v[26:29], v[86:89], v[142:145]
	v_mfma_f32_16x16x32_bf16 v[138:141], v[38:41], v[86:89], v[138:141]
	v_mfma_f32_16x16x32_bf16 v[126:129], v[26:29], v[192:195], v[126:129]
	v_mfma_f32_16x16x32_bf16 v[122:125], v[38:41], v[192:195], v[122:125]
	v_mfma_f32_16x16x32_bf16 v[110:113], v[26:29], v[200:203], v[110:113]
	v_mfma_f32_16x16x32_bf16 v[106:109], v[38:41], v[200:203], v[106:109]
	v_mfma_f32_16x16x32_bf16 v[158:161], v[30:33], v[82:85], v[158:161]
	v_mfma_f32_16x16x32_bf16 v[154:157], v[50:53], v[82:85], v[154:157]
	v_mfma_f32_16x16x32_bf16 v[142:145], v[30:33], v[188:191], v[142:145]
	v_mfma_f32_16x16x32_bf16 v[138:141], v[50:53], v[188:191], v[138:141]
	v_mfma_f32_16x16x32_bf16 v[126:129], v[30:33], v[196:199], v[126:129]
	v_mfma_f32_16x16x32_bf16 v[122:125], v[50:53], v[196:199], v[122:125]
	v_mfma_f32_16x16x32_bf16 v[110:113], v[30:33], v[204:207], v[110:113]
	v_mfma_f32_16x16x32_bf16 v[106:109], v[50:53], v[204:207], v[106:109]
	s_setprio 0
	s_setprio 1
	v_mfma_f32_16x16x32_bf16 v[150:153], v[54:57], v[34:37], v[150:153]
	v_mfma_f32_16x16x32_bf16 v[34:37], v[176:179], v[34:37], v[146:149]
	v_mfma_f32_16x16x32_bf16 v[146:149], v[184:187], v[82:85], v[34:37]
	v_mfma_f32_16x16x32_bf16 v[34:37], v[54:57], v[86:89], v[134:137]
	v_mfma_f32_16x16x32_bf16 v[134:137], v[172:175], v[188:191], v[34:37]
	v_mfma_f32_16x16x32_bf16 v[34:37], v[176:179], v[86:89], v[130:133]
	v_mfma_f32_16x16x32_bf16 v[130:133], v[184:187], v[188:191], v[34:37]
	v_mfma_f32_16x16x32_bf16 v[34:37], v[54:57], v[192:195], v[118:121]
	v_mfma_f32_16x16x32_bf16 v[118:121], v[172:175], v[196:199], v[34:37]
	v_mfma_f32_16x16x32_bf16 v[34:37], v[176:179], v[192:195], v[114:117]
	v_mfma_f32_16x16x32_bf16 v[114:117], v[184:187], v[196:199], v[34:37]
	v_mfma_f32_16x16x32_bf16 v[34:37], v[54:57], v[200:203], v[102:105]
	v_mfma_f32_16x16x32_bf16 v[102:105], v[172:175], v[204:207], v[34:37]
	v_mfma_f32_16x16x32_bf16 v[34:37], v[176:179], v[200:203], v[98:101]
	v_mfma_f32_16x16x32_bf16 v[150:153], v[172:175], v[82:85], v[150:153]
	v_mfma_f32_16x16x32_bf16 v[98:101], v[184:187], v[204:207], v[34:37]
	s_setprio 0
	s_barrier
	s_add_u32 s90, s88, 0x8000
	s_addc_u32 s91, s89, 0
	s_add_i32 s65, s65, s2
	s_nop 0
	s_mov_b32 m0, s65
	ds_read_b128 v[82:85], v183 offset:49152
	ds_read_b128 v[188:191], v183 offset:50176
	ds_read_b128 v[192:195], v183 offset:51200
	ds_read_b128 v[196:199], v183 offset:52224
	ds_read_b128 v[200:203], v183 offset:53248
	ds_read_b128 v[204:207], v183 offset:54272
	ds_read_b128 v[208:211], v183 offset:55296
	ds_read_b128 v[216:219], v183 offset:56320
	global_load_lds_dwordx4 v0, s[90:91]
	s_add_i32 m0, s65, 0x2000
	s_add_u32 s88, s88, 0xc000
	s_addc_u32 s89, s89, 0
	s_add_i32 s65, s66, s2
	global_load_lds_dwordx4 v162, s[90:91]
	s_mov_b32 m0, s65
	s_nop 0
	global_load_lds_dwordx4 v0, s[88:89]
	s_add_i32 m0, s65, 0x2000
	s_nop 0
	global_load_lds_dwordx4 v162, s[88:89]
	s_mov_b32 m0, s71
	s_nop 0
	global_load_lds_dwordx4 v166, s[86:87]
	v_lshl_add_u64 v[34:35], s[86:87], 0, v[164:165]
	s_mov_b32 m0, s80
	s_nop 0
	global_load_lds_dwordx4 v[34:35], off
	s_waitcnt vmcnt(8)
	s_waitcnt lgkmcnt(0)
	s_barrier
	s_setprio 1
	s_waitcnt lgkmcnt(0)
	v_mfma_f32_16x16x32_bf16 v[34:37], v[26:29], v[82:85], v[94:97]
	v_mfma_f32_16x16x32_bf16 v[94:97], v[30:33], v[188:191], v[34:37]
	v_mfma_f32_16x16x32_bf16 v[34:37], v[38:41], v[82:85], v[90:93]
	v_mfma_f32_16x16x32_bf16 v[90:93], v[50:53], v[188:191], v[34:37]
	v_mfma_f32_16x16x32_bf16 v[34:37], v[26:29], v[192:195], v[78:81]
	v_mfma_f32_16x16x32_bf16 v[78:81], v[30:33], v[196:199], v[34:37]
	v_mfma_f32_16x16x32_bf16 v[34:37], v[38:41], v[192:195], v[74:77]
	v_mfma_f32_16x16x32_bf16 v[74:77], v[50:53], v[196:199], v[34:37]
	v_mfma_f32_16x16x32_bf16 v[34:37], v[26:29], v[200:203], v[62:65]
	v_mfma_f32_16x16x32_bf16 v[62:65], v[30:33], v[204:207], v[34:37]
	v_mfma_f32_16x16x32_bf16 v[34:37], v[38:41], v[200:203], v[58:61]
	v_mfma_f32_16x16x32_bf16 v[10:13], v[26:29], v[208:211], v[10:13]
	v_mfma_f32_16x16x32_bf16 v[58:61], v[50:53], v[204:207], v[34:37]
	v_mfma_f32_16x16x32_bf16 v[34:37], v[30:33], v[216:219], v[10:13]
	v_mfma_f32_16x16x32_bf16 v[10:13], v[38:41], v[208:211], v[14:17]
	v_mfma_f32_16x16x32_bf16 v[30:33], v[50:53], v[216:219], v[10:13]
	s_setprio 0
	s_setprio 1
	v_mfma_f32_16x16x32_bf16 v[10:13], v[54:57], v[82:85], v[18:21]
	v_mfma_f32_16x16x32_bf16 v[86:89], v[172:175], v[188:191], v[10:13]
	v_mfma_f32_16x16x32_bf16 v[10:13], v[176:179], v[82:85], v[22:25]
	v_mfma_f32_16x16x32_bf16 v[82:85], v[184:187], v[188:191], v[10:13]
	v_mfma_f32_16x16x32_bf16 v[10:13], v[54:57], v[192:195], v[70:73]
	v_mfma_f32_16x16x32_bf16 v[70:73], v[172:175], v[196:199], v[10:13]
	v_mfma_f32_16x16x32_bf16 v[10:13], v[176:179], v[192:195], v[66:69]
	v_mfma_f32_16x16x32_bf16 v[66:69], v[184:187], v[196:199], v[10:13]
	v_mfma_f32_16x16x32_bf16 v[10:13], v[54:57], v[200:203], v[46:49]
	v_mfma_f32_16x16x32_bf16 v[46:49], v[172:175], v[204:207], v[10:13]
	v_mfma_f32_16x16x32_bf16 v[10:13], v[176:179], v[200:203], v[42:45]
	v_mfma_f32_16x16x32_bf16 v[6:9], v[54:57], v[208:211], v[6:9]
	v_mfma_f32_16x16x32_bf16 v[2:5], v[176:179], v[208:211], v[2:5]
	v_mfma_f32_16x16x32_bf16 v[42:45], v[184:187], v[204:207], v[10:13]
	v_mfma_f32_16x16x32_bf16 v[6:9], v[172:175], v[216:219], v[6:9]
	v_mfma_f32_16x16x32_bf16 v[2:5], v[184:187], v[216:219], v[2:5]
	s_setprio 0
	s_barrier
	s_add_i32 vcc_lo, vcc_lo, 2
	s_add_u32 s6, s6, 0x10000
	s_addc_u32 s7, s7, 0
	s_add_u32 s56, s56, 0x10000
	s_addc_u32 s57, s57, 0
	s_cmp_gt_u32 vcc_lo, 29
	s_cbranch_scc0 .LBB0_328
	s_and_b64 vcc, exec, s[26:27]
	s_cbranch_vccz .LBB0_331
	s_barrier

; #define PG8_STAGE(bufoff, gbase, voff) do { _Pragma("unroll") for (int _i = 0; _i < 2; ++_i) \
;         __builtin_amdgcn_global_load_lds((const unsigned*)((const char*)(gbase) + (voff)[_i]), (PG8_LAS unsigned*)(lds + (bufoff) + ldsw + _i * 8192), 16, 0, 0); } while (0)
; #define PG8_WAIT_V(n) asm volatile("s_waitcnt vmcnt(" #n ")" ::: "memory")
; #define PG8_BAR __builtin_amdgcn_s_barrier()
;     __device__ __forceinline__ size_t b_off(const pg8::Unit& u) const { return (size_t)(u.pm >> 3) * 4 * 131072; }
;     ...
;     const char* cA = (const char*)g.A + (size_t)cur.pm * tstepA + (size_t)cur.pn * APN + kofA; const char* cB = (const char*)g.Bt + (size_t)cur.pn * tstepB + S.b_off(cur) + kofB;
;     S.a_ready(cur);
;     if constexpr (SP2) {
;         PG8_STAGE(PG8_SB(0, 0), cB, voffB); PG8_STAGE(PG8_SB(0, 1), cB + hstepB, voffB); PG8_STAGE(PG8_SA(0, 0), cA, voffA); PG8_STAGE(PG8_SA(0, 1), cA + hstepA, voffA);
;         P();
;         if (wr == 1) PG8_BAR;
;         PG8_WAIT_V(2); PG8_BAR;
;         PG8_STAGE(PG8_SB(1, 0), cB + kstep, voffB); PG8_STAGE(PG8_SA(1, 0), cA + kstepA, voffA); PG8_STAGE(PG8_SB(1, 1), cB + hstepB + kstep, voffB);
;         PG8_WAIT_V(6); PG8_BAR;
;     } else {
;         PG8_STAGE(PG8_SB(0, 0), cB, voffB); PG8_STAGE(PG8_SA(0, 0), cA, voffA); PG8_STAGE(PG8_SB(0, 1), cB + hstepB, voffB); PG8_STAGE(PG8_SA(0, 1), cA + hstepA, voffA);
;         if (wr == 1) PG8_BAR;
;         PG8_WAIT_V(4); PG8_BAR;
;         PG8_STAGE(PG8_SB(1, 0), cB + kstep, voffB); PG8_STAGE(PG8_SA(1, 0), cA + kstepA, voffA); PG8_STAGE(PG8_SB(1, 1), cB + hstepB + kstep, voffB);
;         PG8_WAIT_V(6); PG8_BAR;
;     }
.LBB0_1118:
	s_add_u32 s10, s6, 0x18104000
	s_addc_u32 s11, s7, 0
	v_readlane_b32 s12, v255, 0
	s_cmp_lg_u32 s12, 0
	s_mul_i32 s15, s12, 0x30000
	s_cselect_b64 s[94:95], -1, 0
	s_mul_hi_u32 s14, s12, 0x30000
	s_add_u32 s15, s6, s15
	s_addc_u32 s14, s7, s14
	v_readlane_b32 s13, v255, 1
	s_add_u32 s63, s15, 0x104000
	s_addc_u32 s67, s14, 0
	s_lshl_b64 s[14:15], s[12:13], 15
	s_add_u32 s14, s6, s14
	s_addc_u32 s15, s7, s15
	s_add_u32 s68, s14, 0x1e4000
	s_addc_u32 s70, s15, 0
	s_add_u32 s74, s6, 0x20104000
	s_addc_u32 s75, s7, 0
	s_add_u32 s42, s6, 0x504000
	s_addc_u32 s43, s7, 0
	s_and_b32 s71, s19, 3
	s_lshl_b32 s80, s20, 6
	s_lshl_b32 s19, s20, 13
	s_lshl_b32 s81, s71, 5
	s_lshl_b32 s20, s71, 12
	s_add_u32 s6, s36, 0x8000
	v_mov_b32_e32 v189, v1
	s_addc_u32 s7, s37, 0
	s_add_i32 m0, s51, 0x18000
	v_mov_b32_e32 v193, v1
	s_waitcnt vmcnt(2)
	s_barrier
	global_load_lds_dwordx4 v188, s[6:7]
	s_add_i32 m0, s51, 0x1a000
	v_lshl_add_u64 v[8:9], s[6:7], 0, v[192:193]
	s_add_u32 s6, s34, 0x8000
	v_mov_b32_e32 v187, v1
	s_addc_u32 s7, s35, 0
	s_add_i32 s83, s51, 0x8000
	v_mov_b32_e32 v191, v1
	global_load_lds_dwordx4 v[8:9], off
	s_mov_b32 m0, s83
	s_add_i32 s85, s51, 0xa000
	global_load_lds_dwordx4 v186, s[6:7]
	v_lshl_add_u64 v[8:9], s[6:7], 0, v[190:191]
	s_add_u32 s6, s36, 0xc000
	s_mov_b32 m0, s85
	s_addc_u32 s7, s37, 0
	global_load_lds_dwordx4 v[8:9], off
	s_add_i32 m0, s51, 0x1c000
	s_nop 0
	global_load_lds_dwordx4 v188, s[6:7]
	v_lshl_add_u64 v[8:9], s[6:7], 0, v[192:193]
	s_add_i32 m0, s51, 0x1e000
	s_movk_i32 s6, 0x3c0
	global_load_lds_dwordx4 v[8:9], off
	v_and_b32_e32 v8, 48, v0
	v_lshlrev_b32_e32 v9, 6, v0
	v_lshlrev_b32_e32 v0, 2, v0
	v_and_or_b32 v8, v9, s6, v8
	v_and_b32_e32 v0, 32, v0
	v_bitop3_b32 v9, v8, s19, v0 bitop3:0xde
	v_bitop3_b32 v242, v8, s20, v0 bitop3:0xde
	v_lshlrev_b32_e32 v0, 10, v2
	v_and_b32_e32 v0, 0xfffff800, v0
	v_lshl_add_u32 v0, v3, 7, v0
	v_and_b32_e32 v2, 1, v2
	v_lshl_or_b32 v0, v2, 6, v0
	v_lshl_add_u32 v194, v4, 1, v0
	v_lshlrev_b32_e32 v0, 10, v5
	v_and_b32_e32 v0, 0xfffff800, v0
	s_waitcnt vmcnt(6)
	v_lshl_add_u32 v0, v6, 7, v0
	v_and_b32_e32 v2, 1, v5
	s_cmpk_lt_u32 s18, 0x100
	v_lshl_or_b32 v0, v2, 6, v0
	s_mov_b32 s88, 0
	s_cselect_b64 s[92:93], -1, 0
	s_ashr_i32 s89, s2, 31
	v_mov_b32_e32 v195, v1
	v_lshl_add_u32 v196, v7, 1, v0
	v_mov_b32_e32 v197, v1
	v_add_u32_e32 v243, 0, v9
	s_barrier
	s_branch .LBB0_1121

; #define PG8_STAGE(bufoff, gbase, voff) do { _Pragma("unroll") for (int _i = 0; _i < 2; ++_i) \
;         __builtin_amdgcn_global_load_lds((const unsigned*)((const char*)(gbase) + (voff)[_i]), (PG8_LAS unsigned*)(lds + (bufoff) + ldsw + _i * 8192), 16, 0, 0); } while (0)
; #define PG8_LDA(dst, b, h) do { _Pragma("unroll") for (int m = 0; m < 4; ++m) _Pragma("unroll") for (int k = 0; k < 2; ++k) dst[m][k] = *(const PG8_LAS bf16x8*)(lds + PG8_SA(b, h) + aoff + m * 2048 + k * 1024); } while (0)
; #define PG8_LDB(dst, b, h) do { _Pragma("unroll") for (int n = 0; n < 2; ++n) _Pragma("unroll") for (int k = 0; k < 2; ++k) dst[n][k] = *(const PG8_LAS bf16x8*)(lds + PG8_SB(b, h) + boff + n * 2048 + k * 1024); } while (0)
; #define PG8_MMA(ai, bj, At, Bt) do { __builtin_amdgcn_s_setprio(1); _Pragma("unroll") for (int m = 0; m < 4; ++m) _Pragma("unroll") for (int n = 0; n < 2; ++n) _Pragma("unroll") for (int k = 0; k < 2; ++k) \
;         acc[ai][bj][m][n] = __builtin_amdgcn_mfma_f32_16x16x32_bf16(Bt[n][k], At[m][k], acc[ai][bj][m][n], 0, 0, 0); __builtin_amdgcn_s_setprio(0); } while (0)
; #define PG8_WAIT_V(n) asm volatile("s_waitcnt vmcnt(" #n ")" ::: "memory")
; #define PG8_WAIT_L(n) asm volatile("s_waitcnt lgkmcnt(" #n ")" ::: "memory")
; #define PG8_BAR __builtin_amdgcn_s_barrier()
;     ...
;         for (int t = 0; t < nt; t += 2) {
;             const bool last = (t == nt - 2);
;             const char* a1 = cA + (ptrdiff_t)(t + 1) * kstepA;
;             const char* a2 = last ? nA : cA + (ptrdiff_t)(t + 2) * kstepA; const char* b2 = last ? nB : cB + (ptrdiff_t)(t + 2) * kstep;
;             const char* a3 = a2 + kstepA; const char* b3 = b2 + kstep;
;             if (last && has_next) S.a_ready(nxt);
;             if constexpr (SP2) {
;             PG8_LDB(B0, 0, 0); PG8_LDB(B1, 0, 1); PG8_SCHED; PG8_LDA(At, 0, 0); PG8_STAGE(PG8_SA(1, 1), a1 + hstepA, voffA);
;             PG8_WAIT_V(8); PG8_WAIT_L(0); PG8_BAR; PG8_MMA(0, 0, At, B0); PG8_MMA(0, 1, At, B1); PG8_BAR; PG8_SCHED;
;             PG8_LDA(At, 0, 1); PG8_STAGE(PG8_SB(0, 0), b2, voffB); PG8_STAGE(PG8_SB(0, 1), b2 + hstepB, voffB); PG8_STAGE(PG8_SA(0, 0), a2, voffA);
;             PG8_WAIT_V(8); PG8_WAIT_L(0); PG8_BAR; PG8_MMA(1, 0, At, B0); PG8_MMA(1, 1, At, B1); PG8_BAR; PG8_SCHED;
;             PG8_LDB(B0, 1, 0); PG8_LDB(B1, 1, 1); PG8_SCHED; PG8_LDA(At, 1, 0); PG8_STAGE(PG8_SA(0, 1), a2 + hstepA, voffA);
.LBB0_1128:
	s_add_u32 s36, s34, 0x4000
	s_addc_u32 s37, s35, 0
	s_cmp_eq_u32 s57, 28
	s_cselect_b32 s86, s29, s36
	s_cselect_b32 s87, s23, s37
	s_cselect_b32 s46, s31, s44
	s_cselect_b32 s47, s21, s56
	s_add_u32 s36, s86, 0x8000
	s_addc_u32 s37, s87, 0
	s_add_i32 s65, 0, 0x10000
	v_add_u32_e32 v0, s65, v242
	s_add_i32 s66, 0, 0x14000
	s_waitcnt lgkmcnt(0)
	ds_read_b128 v[130:133], v0
	ds_read_b128 v[134:137], v0 offset:1024
	ds_read_b128 v[138:141], v0 offset:2048
	ds_read_b128 v[142:145], v0 offset:3072
	v_add_u32_e32 v0, s66, v242
	ds_read_b128 v[146:149], v0
	ds_read_b128 v[150:153], v0 offset:1024
	ds_read_b128 v[154:157], v0 offset:2048
	ds_read_b128 v[158:161], v0 offset:3072
	s_add_i32 m0, s51, 0xc000
	ds_read_b128 v[162:165], v243
	ds_read_b128 v[166:169], v243 offset:1024
	ds_read_b128 v[170:173], v243 offset:2048
	ds_read_b128 v[174:177], v243 offset:3072
	ds_read_b128 v[178:181], v243 offset:4096
	ds_read_b128 v[182:185], v243 offset:5120
	ds_read_b128 v[198:201], v243 offset:6144
	ds_read_b128 v[202:205], v243 offset:7168
	global_load_lds_dwordx4 v194, s[34:35]
	s_add_i32 m0, s51, 0xe000
	s_nop 0
	global_load_lds_dwordx4 v196, s[34:35]
	s_waitcnt vmcnt(8)
	s_waitcnt lgkmcnt(0)
	s_barrier
	s_setprio 1
	s_waitcnt lgkmcnt(0)
	v_mfma_f32_16x16x32_bf16 v[126:129], v[130:133], v[162:165], v[126:129]
	v_mfma_f32_16x16x32_bf16 v[122:125], v[138:141], v[162:165], v[122:125]
	v_mfma_f32_16x16x32_bf16 v[110:113], v[130:133], v[170:173], v[110:113]
	v_mfma_f32_16x16x32_bf16 v[106:109], v[138:141], v[170:173], v[106:109]
	v_mfma_f32_16x16x32_bf16 v[94:97], v[130:133], v[178:181], v[94:97]
	v_mfma_f32_16x16x32_bf16 v[90:93], v[138:141], v[178:181], v[90:93]
	v_mfma_f32_16x16x32_bf16 v[78:81], v[130:133], v[198:201], v[78:81]
	v_mfma_f32_16x16x32_bf16 v[74:77], v[138:141], v[198:201], v[74:77]
	v_mfma_f32_16x16x32_bf16 v[126:129], v[134:137], v[166:169], v[126:129]
	v_mfma_f32_16x16x32_bf16 v[122:125], v[142:145], v[166:169], v[122:125]
	v_mfma_f32_16x16x32_bf16 v[110:113], v[134:137], v[174:177], v[110:113]
	v_mfma_f32_16x16x32_bf16 v[106:109], v[142:145], v[174:177], v[106:109]
	v_mfma_f32_16x16x32_bf16 v[94:97], v[134:137], v[182:185], v[94:97]
	v_mfma_f32_16x16x32_bf16 v[90:93], v[142:145], v[182:185], v[90:93]
	v_mfma_f32_16x16x32_bf16 v[78:81], v[134:137], v[202:205], v[78:81]
	v_mfma_f32_16x16x32_bf16 v[74:77], v[142:145], v[202:205], v[74:77]
	s_setprio 0
	s_setprio 1
	v_mfma_f32_16x16x32_bf16 v[118:121], v[146:149], v[162:165], v[118:121]
	v_mfma_f32_16x16x32_bf16 v[114:117], v[154:157], v[162:165], v[114:117]
	v_mfma_f32_16x16x32_bf16 v[102:105], v[146:149], v[170:173], v[102:105]
	v_mfma_f32_16x16x32_bf16 v[98:101], v[154:157], v[170:173], v[98:101]
	v_mfma_f32_16x16x32_bf16 v[86:89], v[146:149], v[178:181], v[86:89]
	v_mfma_f32_16x16x32_bf16 v[82:85], v[154:157], v[178:181], v[82:85]
	v_mfma_f32_16x16x32_bf16 v[70:73], v[146:149], v[198:201], v[70:73]
	v_mfma_f32_16x16x32_bf16 v[66:69], v[154:157], v[198:201], v[66:69]
	v_mfma_f32_16x16x32_bf16 v[118:121], v[150:153], v[166:169], v[118:121]
	v_mfma_f32_16x16x32_bf16 v[114:117], v[158:161], v[166:169], v[114:117]
	v_mfma_f32_16x16x32_bf16 v[102:105], v[150:153], v[174:177], v[102:105]
	v_mfma_f32_16x16x32_bf16 v[98:101], v[158:161], v[174:177], v[98:101]
	v_mfma_f32_16x16x32_bf16 v[86:89], v[150:153], v[182:185], v[86:89]
	v_mfma_f32_16x16x32_bf16 v[82:85], v[158:161], v[182:185], v[82:85]
	v_mfma_f32_16x16x32_bf16 v[70:73], v[150:153], v[202:205], v[70:73]
	v_mfma_f32_16x16x32_bf16 v[66:69], v[158:161], v[202:205], v[66:69]
	s_setprio 0
	s_barrier
	s_add_i32 s65, s65, s49
	s_mov_b32 m0, s65
	ds_read_b128 v[162:165], v243 offset:16384
	ds_read_b128 v[166:169], v243 offset:17408
	ds_read_b128 v[170:173], v243 offset:18432
	ds_read_b128 v[174:177], v243 offset:19456
	ds_read_b128 v[178:181], v243 offset:20480
	ds_read_b128 v[182:185], v243 offset:21504
	ds_read_b128 v[198:201], v243 offset:22528
	ds_read_b128 v[202:205], v243 offset:23552
	global_load_lds_dwordx4 v188, s[46:47]
	s_add_i32 m0, s65, 0x2000
	s_add_u32 s90, s46, 0x4000
	s_addc_u32 s91, s47, 0
	s_add_i32 s65, s66, s49
	global_load_lds_dwordx4 v192, s[46:47]
	s_mov_b32 m0, s65
	s_nop 0
	global_load_lds_dwordx4 v188, s[90:91]
	s_add_i32 m0, s65, 0x2000
	s_nop 0
	global_load_lds_dwordx4 v192, s[90:91]
	s_mov_b32 m0, s51
	s_nop 0
	global_load_lds_dwordx4 v186, s[86:87]
	s_mov_b32 m0, s54
	s_nop 0
	global_load_lds_dwordx4 v190, s[86:87]
	s_waitcnt vmcnt(8)
	s_waitcnt lgkmcnt(0)
	s_barrier
	s_setprio 1
	s_waitcnt lgkmcnt(0)
	v_mfma_f32_16x16x32_bf16 v[62:65], v[130:133], v[162:165], v[62:65]
	v_mfma_f32_16x16x32_bf16 v[58:61], v[138:141], v[162:165], v[58:61]
	v_mfma_f32_16x16x32_bf16 v[46:49], v[130:133], v[170:173], v[46:49]
	v_mfma_f32_16x16x32_bf16 v[42:45], v[138:141], v[170:173], v[42:45]
	v_mfma_f32_16x16x32_bf16 v[30:33], v[130:133], v[178:181], v[30:33]
	v_mfma_f32_16x16x32_bf16 v[26:29], v[138:141], v[178:181], v[26:29]
	v_mfma_f32_16x16x32_bf16 v[14:17], v[130:133], v[198:201], v[14:17]
	v_mfma_f32_16x16x32_bf16 v[10:13], v[138:141], v[198:201], v[10:13]
	v_mfma_f32_16x16x32_bf16 v[62:65], v[134:137], v[166:169], v[62:65]
	v_mfma_f32_16x16x32_bf16 v[58:61], v[142:145], v[166:169], v[58:61]
	v_mfma_f32_16x16x32_bf16 v[46:49], v[134:137], v[174:177], v[46:49]
	v_mfma_f32_16x16x32_bf16 v[42:45], v[142:145], v[174:177], v[42:45]
	v_mfma_f32_16x16x32_bf16 v[30:33], v[134:137], v[182:185], v[30:33]
	v_mfma_f32_16x16x32_bf16 v[26:29], v[142:145], v[182:185], v[26:29]
	v_mfma_f32_16x16x32_bf16 v[14:17], v[134:137], v[202:205], v[14:17]
	v_mfma_f32_16x16x32_bf16 v[10:13], v[142:145], v[202:205], v[10:13]
	s_setprio 0
	s_setprio 1
	v_mfma_f32_16x16x32_bf16 v[54:57], v[146:149], v[162:165], v[54:57]
	v_mfma_f32_16x16x32_bf16 v[50:53], v[154:157], v[162:165], v[50:53]
	v_mfma_f32_16x16x32_bf16 v[38:41], v[146:149], v[170:173], v[38:41]
	v_mfma_f32_16x16x32_bf16 v[34:37], v[154:157], v[170:173], v[34:37]
	v_mfma_f32_16x16x32_bf16 v[22:25], v[146:149], v[178:181], v[22:25]
	v_mfma_f32_16x16x32_bf16 v[18:21], v[154:157], v[178:181], v[18:21]
	v_mfma_f32_16x16x32_bf16 v[6:9], v[146:149], v[198:201], v[6:9]
	v_mfma_f32_16x16x32_bf16 v[2:5], v[154:157], v[198:201], v[2:5]
	v_mfma_f32_16x16x32_bf16 v[54:57], v[150:153], v[166:169], v[54:57]
	v_mfma_f32_16x16x32_bf16 v[50:53], v[158:161], v[166:169], v[50:53]
	v_mfma_f32_16x16x32_bf16 v[38:41], v[150:153], v[174:177], v[38:41]
	v_mfma_f32_16x16x32_bf16 v[34:37], v[158:161], v[174:177], v[34:37]
	v_mfma_f32_16x16x32_bf16 v[22:25], v[150:153], v[182:185], v[22:25]
	v_mfma_f32_16x16x32_bf16 v[18:21], v[158:161], v[182:185], v[18:21]
	v_mfma_f32_16x16x32_bf16 v[6:9], v[150:153], v[202:205], v[6:9]
	v_mfma_f32_16x16x32_bf16 v[2:5], v[158:161], v[202:205], v[2:5]
	s_setprio 0
	s_barrier
; #define PG8_STAGE(bufoff, gbase, voff) do { _Pragma("unroll") for (int _i = 0; _i < 2; ++_i) \
;         __builtin_amdgcn_global_load_lds((const unsigned*)((const char*)(gbase) + (voff)[_i]), (PG8_LAS unsigned*)(lds + (bufoff) + ldsw + _i * 8192), 16, 0, 0); } while (0)
; #define PG8_LDA(dst, b, h) do { _Pragma("unroll") for (int m = 0; m < 4; ++m) _Pragma("unroll") for (int k = 0; k < 2; ++k) dst[m][k] = *(const PG8_LAS bf16x8*)(lds + PG8_SA(b, h) + aoff + m * 2048 + k * 1024); } while (0)
; #define PG8_LDB(dst, b, h) do { _Pragma("unroll") for (int n = 0; n < 2; ++n) _Pragma("unroll") for (int k = 0; k < 2; ++k) dst[n][k] = *(const PG8_LAS bf16x8*)(lds + PG8_SB(b, h) + boff + n * 2048 + k * 1024); } while (0)
; #define PG8_MMA(ai, bj, At, Bt) do { __builtin_amdgcn_s_setprio(1); _Pragma("unroll") for (int m = 0; m < 4; ++m) _Pragma("unroll") for (int n = 0; n < 2; ++n) _Pragma("unroll") for (int k = 0; k < 2; ++k) \
;         acc[ai][bj][m][n] = __builtin_amdgcn_mfma_f32_16x16x32_bf16(Bt[n][k], At[m][k], acc[ai][bj][m][n], 0, 0, 0); __builtin_amdgcn_s_setprio(0); } while (0)
; #define PG8_WAIT_V(n) asm volatile("s_waitcnt vmcnt(" #n ")" ::: "memory")
; #define PG8_WAIT_L(n) asm volatile("s_waitcnt lgkmcnt(" #n ")" ::: "memory")
; #define PG8_BAR __builtin_amdgcn_s_barrier()
; #define PG8_SCHED __builtin_amdgcn_sched_barrier(0)
;     ...
;             PG8_LDB(B0, 1, 0); PG8_LDB(B1, 1, 1); PG8_SCHED; PG8_LDA(At, 1, 0); PG8_STAGE(PG8_SA(0, 1), a2 + hstepA, voffA);
;             PG8_WAIT_V(8); PG8_WAIT_L(0); PG8_BAR; PG8_MMA(0, 0, At, B0); PG8_MMA(0, 1, At, B1); PG8_BAR; PG8_SCHED;
;             PG8_LDA(At, 1, 1); PG8_STAGE(PG8_SB(1, 0), b3, voffB); PG8_STAGE(PG8_SB(1, 1), b3 + hstepB, voffB); PG8_STAGE(PG8_SA(1, 0), a3, voffA);
;             PG8_WAIT_V(8); PG8_WAIT_L(0); PG8_BAR; PG8_MMA(1, 0, At, B0); PG8_MMA(1, 1, At, B1); PG8_BAR; PG8_SCHED;
	s_add_i32 s65, 0, 0x18000
	v_add_u32_e32 v0, s65, v242
	s_add_i32 s66, 0, 0x1c000
	ds_read_b128 v[130:133], v0
	ds_read_b128 v[134:137], v0 offset:1024
	ds_read_b128 v[138:141], v0 offset:2048
	ds_read_b128 v[142:145], v0 offset:3072
	v_add_u32_e32 v0, s66, v242
	ds_read_b128 v[146:149], v0
	ds_read_b128 v[150:153], v0 offset:1024
	ds_read_b128 v[154:157], v0 offset:2048
	ds_read_b128 v[158:161], v0 offset:3072
	s_add_u32 s86, s86, 0x4000
	s_addc_u32 s87, s87, 0
	s_mov_b32 m0, s55
	ds_read_b128 v[162:165], v243 offset:32768
	ds_read_b128 v[166:169], v243 offset:33792
	ds_read_b128 v[170:173], v243 offset:34816
	ds_read_b128 v[174:177], v243 offset:35840
	ds_read_b128 v[178:181], v243 offset:36864
	ds_read_b128 v[182:185], v243 offset:37888
	ds_read_b128 v[198:201], v243 offset:38912
	ds_read_b128 v[202:205], v243 offset:39936
	global_load_lds_dwordx4 v186, s[86:87]
	s_mov_b32 m0, s61
	s_nop 0
	global_load_lds_dwordx4 v190, s[86:87]
	s_waitcnt vmcnt(8)
	s_waitcnt lgkmcnt(0)
	s_barrier
	s_setprio 1
	s_waitcnt lgkmcnt(0)
	v_mfma_f32_16x16x32_bf16 v[126:129], v[130:133], v[162:165], v[126:129]
	v_mfma_f32_16x16x32_bf16 v[122:125], v[138:141], v[162:165], v[122:125]
	v_mfma_f32_16x16x32_bf16 v[110:113], v[130:133], v[170:173], v[110:113]
	v_mfma_f32_16x16x32_bf16 v[106:109], v[138:141], v[170:173], v[106:109]
	v_mfma_f32_16x16x32_bf16 v[94:97], v[130:133], v[178:181], v[94:97]
	v_mfma_f32_16x16x32_bf16 v[90:93], v[138:141], v[178:181], v[90:93]
	v_mfma_f32_16x16x32_bf16 v[78:81], v[130:133], v[198:201], v[78:81]
	v_mfma_f32_16x16x32_bf16 v[74:77], v[138:141], v[198:201], v[74:77]
	v_mfma_f32_16x16x32_bf16 v[126:129], v[134:137], v[166:169], v[126:129]
	v_mfma_f32_16x16x32_bf16 v[122:125], v[142:145], v[166:169], v[122:125]
	v_mfma_f32_16x16x32_bf16 v[110:113], v[134:137], v[174:177], v[110:113]
	v_mfma_f32_16x16x32_bf16 v[106:109], v[142:145], v[174:177], v[106:109]
	v_mfma_f32_16x16x32_bf16 v[94:97], v[134:137], v[182:185], v[94:97]
	v_mfma_f32_16x16x32_bf16 v[90:93], v[142:145], v[182:185], v[90:93]
	v_mfma_f32_16x16x32_bf16 v[78:81], v[134:137], v[202:205], v[78:81]
	v_mfma_f32_16x16x32_bf16 v[74:77], v[142:145], v[202:205], v[74:77]
	s_setprio 0
	s_setprio 1
	v_mfma_f32_16x16x32_bf16 v[118:121], v[146:149], v[162:165], v[118:121]
	v_mfma_f32_16x16x32_bf16 v[114:117], v[154:157], v[162:165], v[114:117]
	v_mfma_f32_16x16x32_bf16 v[102:105], v[146:149], v[170:173], v[102:105]
	v_mfma_f32_16x16x32_bf16 v[98:101], v[154:157], v[170:173], v[98:101]
	v_mfma_f32_16x16x32_bf16 v[86:89], v[146:149], v[178:181], v[86:89]
	v_mfma_f32_16x16x32_bf16 v[82:85], v[154:157], v[178:181], v[82:85]
	v_mfma_f32_16x16x32_bf16 v[70:73], v[146:149], v[198:201], v[70:73]
	v_mfma_f32_16x16x32_bf16 v[66:69], v[154:157], v[198:201], v[66:69]
	v_mfma_f32_16x16x32_bf16 v[118:121], v[150:153], v[166:169], v[118:121]
	v_mfma_f32_16x16x32_bf16 v[114:117], v[158:161], v[166:169], v[114:117]
	v_mfma_f32_16x16x32_bf16 v[102:105], v[150:153], v[174:177], v[102:105]
	v_mfma_f32_16x16x32_bf16 v[98:101], v[158:161], v[174:177], v[98:101]
	v_mfma_f32_16x16x32_bf16 v[86:89], v[150:153], v[182:185], v[86:89]
	v_mfma_f32_16x16x32_bf16 v[82:85], v[158:161], v[182:185], v[82:85]
	v_mfma_f32_16x16x32_bf16 v[70:73], v[150:153], v[202:205], v[70:73]
	v_mfma_f32_16x16x32_bf16 v[66:69], v[158:161], v[202:205], v[66:69]
	s_setprio 0
	s_barrier
	s_add_u32 s86, s46, 0x8000
	s_addc_u32 s87, s47, 0
	s_add_i32 s65, s65, s49
	s_mov_b32 m0, s65
	ds_read_b128 v[162:165], v243 offset:49152
	ds_read_b128 v[166:169], v243 offset:50176
	ds_read_b128 v[170:173], v243 offset:51200
	ds_read_b128 v[174:177], v243 offset:52224
	ds_read_b128 v[178:181], v243 offset:53248
	ds_read_b128 v[182:185], v243 offset:54272
	ds_read_b128 v[198:201], v243 offset:55296
	ds_read_b128 v[202:205], v243 offset:56320
	global_load_lds_dwordx4 v188, s[86:87]
	s_add_i32 m0, s65, 0x2000
	s_add_u32 s46, s46, 0xc000
	s_addc_u32 s47, s47, 0
	s_add_i32 s65, s66, s49
	global_load_lds_dwordx4 v192, s[86:87]
	s_mov_b32 m0, s65
	s_nop 0
	global_load_lds_dwordx4 v188, s[46:47]
	s_add_i32 m0, s65, 0x2000
	s_nop 0
	global_load_lds_dwordx4 v192, s[46:47]
	s_mov_b32 m0, s83
	s_nop 0
	global_load_lds_dwordx4 v186, s[36:37]
	v_lshl_add_u64 v[206:207], s[36:37], 0, v[190:191]
	s_mov_b32 m0, s85
	s_nop 0
	global_load_lds_dwordx4 v[206:207], off
	s_waitcnt vmcnt(8)
	s_waitcnt lgkmcnt(0)
	s_barrier
	s_setprio 1
	s_waitcnt lgkmcnt(0)
	v_mfma_f32_16x16x32_bf16 v[62:65], v[130:133], v[162:165], v[62:65]
	v_mfma_f32_16x16x32_bf16 v[58:61], v[138:141], v[162:165], v[58:61]
	v_mfma_f32_16x16x32_bf16 v[46:49], v[130:133], v[170:173], v[46:49]
	v_mfma_f32_16x16x32_bf16 v[42:45], v[138:141], v[170:173], v[42:45]
	v_mfma_f32_16x16x32_bf16 v[30:33], v[130:133], v[178:181], v[30:33]
	v_mfma_f32_16x16x32_bf16 v[26:29], v[138:141], v[178:181], v[26:29]
	v_mfma_f32_16x16x32_bf16 v[14:17], v[130:133], v[198:201], v[14:17]
	v_mfma_f32_16x16x32_bf16 v[10:13], v[138:141], v[198:201], v[10:13]
	v_mfma_f32_16x16x32_bf16 v[62:65], v[134:137], v[166:169], v[62:65]
	v_mfma_f32_16x16x32_bf16 v[58:61], v[142:145], v[166:169], v[58:61]
	v_mfma_f32_16x16x32_bf16 v[46:49], v[134:137], v[174:177], v[46:49]
	v_mfma_f32_16x16x32_bf16 v[42:45], v[142:145], v[174:177], v[42:45]
	v_mfma_f32_16x16x32_bf16 v[30:33], v[134:137], v[182:185], v[30:33]
	v_mfma_f32_16x16x32_bf16 v[26:29], v[142:145], v[182:185], v[26:29]
	v_mfma_f32_16x16x32_bf16 v[14:17], v[134:137], v[202:205], v[14:17]
	v_mfma_f32_16x16x32_bf16 v[10:13], v[142:145], v[202:205], v[10:13]
	s_setprio 0
	s_setprio 1
	v_mfma_f32_16x16x32_bf16 v[54:57], v[146:149], v[162:165], v[54:57]
	v_mfma_f32_16x16x32_bf16 v[50:53], v[154:157], v[162:165], v[50:53]
	v_mfma_f32_16x16x32_bf16 v[38:41], v[146:149], v[170:173], v[38:41]
	v_mfma_f32_16x16x32_bf16 v[34:37], v[154:157], v[170:173], v[34:37]
	v_mfma_f32_16x16x32_bf16 v[22:25], v[146:149], v[178:181], v[22:25]
	v_mfma_f32_16x16x32_bf16 v[18:21], v[154:157], v[178:181], v[18:21]
	v_mfma_f32_16x16x32_bf16 v[6:9], v[146:149], v[198:201], v[6:9]
	v_mfma_f32_16x16x32_bf16 v[2:5], v[154:157], v[198:201], v[2:5]
	v_mfma_f32_16x16x32_bf16 v[54:57], v[150:153], v[166:169], v[54:57]
	v_mfma_f32_16x16x32_bf16 v[50:53], v[158:161], v[166:169], v[50:53]
	v_mfma_f32_16x16x32_bf16 v[38:41], v[150:153], v[174:177], v[38:41]
	v_mfma_f32_16x16x32_bf16 v[34:37], v[158:161], v[174:177], v[34:37]
	v_mfma_f32_16x16x32_bf16 v[22:25], v[150:153], v[182:185], v[22:25]
	v_mfma_f32_16x16x32_bf16 v[18:21], v[158:161], v[182:185], v[18:21]
	v_mfma_f32_16x16x32_bf16 v[6:9], v[150:153], v[202:205], v[6:9]
	v_mfma_f32_16x16x32_bf16 v[2:5], v[158:161], v[202:205], v[2:5]
	s_setprio 0
	s_barrier
	s_add_i32 s57, s57, 2
	s_add_u32 s34, s34, 0x10000
	s_addc_u32 s35, s35, 0
	s_add_u32 s44, s44, 0x10000
	s_addc_u32 s56, s56, 0
	s_cmp_gt_u32 s57, 29
	s_cbranch_scc0 .LBB0_1128
	s_and_b64 vcc, exec, s[92:93]
	s_cbranch_vccz .LBB0_1131
	s_barrier

; #define PG8_STAGE(bufoff, gbase, voff) do { _Pragma("unroll") for (int _i = 0; _i < 2; ++_i) \
;         __builtin_amdgcn_global_load_lds((const unsigned*)((const char*)(gbase) + (voff)[_i]), (PG8_LAS unsigned*)(lds + (bufoff) + ldsw + _i * 8192), 16, 0, 0); } while (0)
; #define PG8_WAIT_V(n) asm volatile("s_waitcnt vmcnt(" #n ")" ::: "memory")
; #define PG8_BAR __builtin_amdgcn_s_barrier()
;     __device__ __forceinline__ size_t b_off(const pg8::Unit& u) const { return (size_t)(u.pm >> 3) * 4 * 131072; }
;     ...
;     const char* cA = (const char*)g.A + (size_t)cur.pm * tstepA + (size_t)cur.pn * APN + kofA; const char* cB = (const char*)g.Bt + (size_t)cur.pn * tstepB + S.b_off(cur) + kofB;
;     S.a_ready(cur);
;     if constexpr (SP2) {
;         PG8_STAGE(PG8_SB(0, 0), cB, voffB); PG8_STAGE(PG8_SB(0, 1), cB + hstepB, voffB); PG8_STAGE(PG8_SA(0, 0), cA, voffA); PG8_STAGE(PG8_SA(0, 1), cA + hstepA, voffA);
;         P();
;         if (wr == 1) PG8_BAR;
;         PG8_WAIT_V(2); PG8_BAR;
;         PG8_STAGE(PG8_SB(1, 0), cB + kstep, voffB); PG8_STAGE(PG8_SA(1, 0), cA + kstepA, voffA); PG8_STAGE(PG8_SB(1, 1), cB + hstepB + kstep, voffB);
;         PG8_WAIT_V(6); PG8_BAR;
;     } else {
;         PG8_STAGE(PG8_SB(0, 0), cB, voffB); PG8_STAGE(PG8_SA(0, 0), cA, voffA); PG8_STAGE(PG8_SB(0, 1), cB + hstepB, voffB); PG8_STAGE(PG8_SA(0, 1), cA + hstepA, voffA);
;         if (wr == 1) PG8_BAR;
;         PG8_WAIT_V(4); PG8_BAR;
;         PG8_STAGE(PG8_SB(1, 0), cB + kstep, voffB); PG8_STAGE(PG8_SA(1, 0), cA + kstepA, voffA); PG8_STAGE(PG8_SB(1, 1), cB + hstepB + kstep, voffB);
;         PG8_WAIT_V(6); PG8_BAR;
;     }
.LBB0_1250:
	v_readlane_b32 s6, v255, 0
	v_readlane_b32 s7, v255, 1
	s_mov_b32 s20, s6
	s_mul_i32 s7, s20, 0x2c000
	s_mul_hi_u32 s6, s6, 0x2c000
	s_add_u32 s7, s22, s7
	s_addc_u32 s6, s23, s6
	v_readlane_b32 s80, v254, 14
	s_add_u32 s61, s7, 0x254000
	v_readlane_b32 s90, v254, 24
	v_readlane_b32 s91, v254, 25
	s_addc_u32 s63, s6, 0
	s_mul_i32 s7, s20, 0x10800
	s_mov_b64 s[14:15], s[90:91]
	s_mul_hi_u32 s6, s20, 0x10800
	v_readlane_b32 s92, v254, 26
	v_readlane_b32 s93, v254, 27
	s_add_u32 s14, s14, s7
	s_mov_b64 s[16:17], s[92:93]
	s_addc_u32 s15, s15, s6
	s_mul_i32 s7, s20, 0x5800
	s_mul_hi_u32 s6, s20, 0x5800
	s_add_u32 s16, s16, s7
	s_addc_u32 s17, s17, s6
	s_add_u32 s67, s22, 0x24104000
	s_addc_u32 s68, s23, 0
	s_add_u32 s70, s22, 0x2f104000
	s_addc_u32 s71, s23, 0
	v_readlane_b32 s81, v254, 15
	s_add_u32 s80, s22, 0x30704000
	v_readlane_b32 s83, v254, 17
	s_addc_u32 s81, s23, 0
	s_lshl_b32 s6, s24, 5
	s_and_b32 s83, s6, 0x60
	s_lshl_b32 s20, s55, 13
	s_lshl_b32 s21, s83, 7
	s_add_u32 s6, s36, 0x8000
	s_addc_u32 s7, s37, 0
	s_add_i32 m0, s48, 0x18000
	s_waitcnt vmcnt(2)
	s_barrier
	global_load_lds_dwordx4 v162, s[6:7]
	s_add_i32 m0, s48, 0x1a000
	v_readlane_b32 s85, v254, 19
	v_lshl_add_u64 v[2:3], s[6:7], 0, v[158:159]
	s_add_u32 s6, s34, 0x8000
	s_addc_u32 s7, s35, 0
	s_add_i32 s85, s48, 0x8000
	global_load_lds_dwordx4 v[2:3], off
	s_mov_b32 m0, s85
	s_add_i32 s90, s48, 0xa000
	global_load_lds_dwordx4 v164, s[6:7]
	v_lshl_add_u64 v[2:3], s[6:7], 0, v[160:161]
	s_add_u32 s6, s36, 0xc000
	s_mov_b32 m0, s90
	s_addc_u32 s7, s37, 0
	global_load_lds_dwordx4 v[2:3], off
	s_add_i32 m0, s48, 0x1c000
	s_nop 0
	global_load_lds_dwordx4 v162, s[6:7]
	v_lshl_add_u64 v[2:3], s[6:7], 0, v[158:159]
	s_add_i32 m0, s48, 0x1e000
	s_cmpk_lt_u32 s19, 0x100
	global_load_lds_dwordx4 v[2:3], off
	v_and_b32_e32 v2, 15, v0
	v_and_b32_e32 v3, 48, v0
	v_lshlrev_b32_e32 v0, 2, v0
	v_lshl_or_b32 v2, v2, 6, v3
	v_and_b32_e32 v0, 32, v0
	v_bitop3_b32 v3, v2, s20, v0 bitop3:0xde
	v_bitop3_b32 v192, s21, v2, v0 bitop3:0xf6
	v_and_b32_e32 v2, 1, v9
	v_add3_u32 v0, v11, v12, v13
	v_lshlrev_b32_e32 v2, 6, v2
	v_lshl_or_b32 v0, v0, 7, v2
	s_sext_i32_i16 s11, s18
	s_cselect_b64 s[18:19], -1, 0
	s_lshl_b32 s91, s55, 7
	v_lshl_add_u32 v0, v10, 1, v0
	s_mov_b64 s[6:7], 0x8200
	v_and_b32_e32 v2, 1, v4
	s_add_u32 s20, s14, 0x5800
	v_lshl_add_u64 v[166:167], v[0:1], 0, s[6:7]
	v_add3_u32 v0, v6, v7, v8
	v_lshlrev_b32_e32 v2, 6, v2
	s_waitcnt vmcnt(6)
	s_addc_u32 s21, s15, 0
	v_lshl_or_b32 v0, v0, 7, v2
	v_readlane_b32 s82, v254, 16
	v_readlane_b32 s84, v254, 18
	v_readlane_b32 s94, v254, 28
	v_readlane_b32 s95, v254, 29
	s_add_u32 s22, s14, 0xb000
	v_lshl_add_u32 v0, v5, 1, v0
	s_addc_u32 s23, s15, 0
	v_lshl_add_u64 v[168:169], v[0:1], 0, s[6:7]
	s_mov_b32 s92, 0
	v_add_u32_e32 v193, 0, v3
	v_readlane_b32 s93, v254, 57
	v_readlane_b32 s94, v254, 58
	v_readlane_b32 s95, v254, 59
	s_movk_i32 s82, 0x5000
	s_movk_i32 s84, 0x80
	v_readlane_b32 s86, v254, 20
	v_readlane_b32 s87, v254, 21
	v_readlane_b32 s88, v254, 22
	v_readlane_b32 s89, v254, 23
	s_barrier
	s_branch .LBB0_1253

;     __host__ __device__ __forceinline__ bool next(int i, Unit& u) const { const int vv = vid + (i / 5) * G; if (vv >= 256) return false; u.pm = vv >> 2; u.pn = (vv & 3) + 4 * (i % 5); return true; }
; #define PG8_STAGE(bufoff, gbase, voff) do { _Pragma("unroll") for (int _i = 0; _i < 2; ++_i) \
;         __builtin_amdgcn_global_load_lds((const unsigned*)((const char*)(gbase) + (voff)[_i]), (PG8_LAS unsigned*)(lds + (bufoff) + ldsw + _i * 8192), 16, 0, 0); } while (0)
; #define PG8_LDA(dst, b, h) do { _Pragma("unroll") for (int m = 0; m < 4; ++m) _Pragma("unroll") for (int k = 0; k < 2; ++k) dst[m][k] = *(const PG8_LAS bf16x8*)(lds + PG8_SA(b, h) + aoff + m * 2048 + k * 1024); } while (0)
; #define PG8_LDB(dst, b, h) do { _Pragma("unroll") for (int n = 0; n < 2; ++n) _Pragma("unroll") for (int k = 0; k < 2; ++k) dst[n][k] = *(const PG8_LAS bf16x8*)(lds + PG8_SB(b, h) + boff + n * 2048 + k * 1024); } while (0)
; #define PG8_WAIT_V(n) asm volatile("s_waitcnt vmcnt(" #n ")" ::: "memory")
; #define PG8_WAIT_L(n) asm volatile("s_waitcnt lgkmcnt(" #n ")" ::: "memory")
; #define PG8_BAR __builtin_amdgcn_s_barrier()
;     ...
;         const bool has_next = S.next(ui + 1, nxt);
;         const char* nA = has_next ? (const char*)g.A + (size_t)nxt.pm * tstepA + (size_t)nxt.pn * APN + kofA : cA; const char* nB = has_next ? (const char*)g.Bt + (size_t)nxt.pn * tstepB + S.b_off(nxt) + kofB : cB;
;         for (int t = 0; t < nt; t += 2) {
;             const bool last = (t == nt - 2);
;             const char* a1 = cA + (ptrdiff_t)(t + 1) * kstepA;
;             const char* a2 = last ? nA : cA + (ptrdiff_t)(t + 2) * kstepA; const char* b2 = last ? nB : cB + (ptrdiff_t)(t + 2) * kstep;
;             const char* a3 = a2 + kstepA; const char* b3 = b2 + kstep;
;             if (last && has_next) S.a_ready(nxt);
;             if constexpr (SP2) {
;             PG8_LDB(B0, 0, 0); PG8_LDB(B1, 0, 1); PG8_SCHED; PG8_LDA(At, 0, 0); PG8_STAGE(PG8_SA(1, 1), a1 + hstepA, voffA);
;             PG8_WAIT_V(8); PG8_WAIT_L(0); PG8_BAR; PG8_MMA(0, 0, At, B0); PG8_MMA(0, 1, At, B1); PG8_BAR; PG8_SCHED;
;             PG8_LDA(At, 0, 1); PG8_STAGE(PG8_SB(0, 0), b2, voffB); PG8_STAGE(PG8_SB(0, 1), b2 + hstepB, voffB); PG8_STAGE(PG8_SA(0, 0), a2, voffA);
;             PG8_WAIT_V(8); PG8_WAIT_L(0); PG8_BAR; PG8_MMA(1, 0, At, B0); PG8_MMA(1, 1, At, B1); PG8_BAR; PG8_SCHED;
.LBB0_1256:
	s_add_u32 s36, s34, 0x10000
	s_addc_u32 s37, s35, 0
	s_cmp_eq_u32 s66, 28
	s_cselect_b32 s88, s57, s36
	s_cselect_b32 s89, s27, s37
	s_cselect_b32 s86, vcc_lo, vcc_hi
	s_cselect_b32 s87, s25, s65
	s_add_u32 s46, s88, 0x8000
	s_addc_u32 s47, s89, 0
	s_add_i32 s96, 0, 0x10000
	v_add_u32_e32 v0, s96, v192
	s_add_i32 s97, 0, 0x14000
	ds_read_b128 v[130:133], v0
	ds_read_b128 v[134:137], v0 offset:1024
	ds_read_b128 v[138:141], v0 offset:2048
	ds_read_b128 v[142:145], v0 offset:3072
	v_add_u32_e32 v0, s97, v192
	ds_read_b128 v[146:149], v0
	ds_read_b128 v[150:153], v0 offset:1024
	ds_read_b128 v[154:157], v0 offset:2048
	ds_read_b128 v[170:173], v0 offset:3072
	s_add_i32 m0, s48, 0xc000
	ds_read_b128 v[174:177], v193
	ds_read_b128 v[178:181], v193 offset:1024
	ds_read_b128 v[182:185], v193 offset:2048
	ds_read_b128 v[186:189], v193 offset:3072
	ds_read_b128 v[194:197], v193 offset:4096
	ds_read_b128 v[198:201], v193 offset:5120
	ds_read_b128 v[202:205], v193 offset:6144
	ds_read_b128 v[206:209], v193 offset:7168
	global_load_lds_dwordx4 v166, s[34:35]
	s_add_i32 m0, s48, 0xe000
	s_nop 0
	global_load_lds_dwordx4 v168, s[34:35]
	s_waitcnt vmcnt(8)
	s_waitcnt lgkmcnt(0)
	s_barrier
	s_setprio 1
	s_waitcnt lgkmcnt(0)
	v_mfma_f32_16x16x32_bf16 v[126:129], v[130:133], v[174:177], v[126:129]
	v_mfma_f32_16x16x32_bf16 v[122:125], v[138:141], v[174:177], v[122:125]
	v_mfma_f32_16x16x32_bf16 v[118:121], v[130:133], v[182:185], v[118:121]
	v_mfma_f32_16x16x32_bf16 v[114:117], v[138:141], v[182:185], v[114:117]
	v_mfma_f32_16x16x32_bf16 v[110:113], v[130:133], v[194:197], v[110:113]
	v_mfma_f32_16x16x32_bf16 v[106:109], v[138:141], v[194:197], v[106:109]
	v_mfma_f32_16x16x32_bf16 v[102:105], v[130:133], v[202:205], v[102:105]
	v_mfma_f32_16x16x32_bf16 v[98:101], v[138:141], v[202:205], v[98:101]
	v_mfma_f32_16x16x32_bf16 v[126:129], v[134:137], v[178:181], v[126:129]
	v_mfma_f32_16x16x32_bf16 v[122:125], v[142:145], v[178:181], v[122:125]
	v_mfma_f32_16x16x32_bf16 v[118:121], v[134:137], v[186:189], v[118:121]
	v_mfma_f32_16x16x32_bf16 v[114:117], v[142:145], v[186:189], v[114:117]
	v_mfma_f32_16x16x32_bf16 v[110:113], v[134:137], v[198:201], v[110:113]
	v_mfma_f32_16x16x32_bf16 v[106:109], v[142:145], v[198:201], v[106:109]
	v_mfma_f32_16x16x32_bf16 v[102:105], v[134:137], v[206:209], v[102:105]
	v_mfma_f32_16x16x32_bf16 v[98:101], v[142:145], v[206:209], v[98:101]
	s_setprio 0
	s_setprio 1
	v_mfma_f32_16x16x32_bf16 v[30:33], v[146:149], v[174:177], v[30:33]
	v_mfma_f32_16x16x32_bf16 v[46:49], v[154:157], v[174:177], v[46:49]
	v_mfma_f32_16x16x32_bf16 v[26:29], v[146:149], v[182:185], v[26:29]
	v_mfma_f32_16x16x32_bf16 v[34:37], v[154:157], v[182:185], v[34:37]
	v_mfma_f32_16x16x32_bf16 v[94:97], v[146:149], v[194:197], v[94:97]
	v_mfma_f32_16x16x32_bf16 v[90:93], v[154:157], v[194:197], v[90:93]
	v_mfma_f32_16x16x32_bf16 v[86:89], v[146:149], v[202:205], v[86:89]
	v_mfma_f32_16x16x32_bf16 v[82:85], v[154:157], v[202:205], v[82:85]
	v_mfma_f32_16x16x32_bf16 v[30:33], v[150:153], v[178:181], v[30:33]
	v_mfma_f32_16x16x32_bf16 v[46:49], v[170:173], v[178:181], v[46:49]
	v_mfma_f32_16x16x32_bf16 v[26:29], v[150:153], v[186:189], v[26:29]
	v_mfma_f32_16x16x32_bf16 v[34:37], v[170:173], v[186:189], v[34:37]
	v_mfma_f32_16x16x32_bf16 v[94:97], v[150:153], v[198:201], v[94:97]
	v_mfma_f32_16x16x32_bf16 v[90:93], v[170:173], v[198:201], v[90:93]
	v_mfma_f32_16x16x32_bf16 v[86:89], v[150:153], v[206:209], v[86:89]
	v_mfma_f32_16x16x32_bf16 v[82:85], v[170:173], v[206:209], v[82:85]
	s_setprio 0
	s_barrier
	s_add_i32 s34, s96, s44
	s_mov_b32 m0, s34
	ds_read_b128 v[174:177], v193 offset:16384
	ds_read_b128 v[178:181], v193 offset:17408
	ds_read_b128 v[182:185], v193 offset:18432
	ds_read_b128 v[186:189], v193 offset:19456
	ds_read_b128 v[194:197], v193 offset:20480
	ds_read_b128 v[198:201], v193 offset:21504
	ds_read_b128 v[202:205], v193 offset:22528
	ds_read_b128 v[206:209], v193 offset:23552
	global_load_lds_dwordx4 v162, s[86:87]
	s_add_i32 m0, s34, 0x2000
	s_add_u32 s34, s86, 0x4000
	s_addc_u32 s35, s87, 0
	s_add_i32 s96, s97, s44
	global_load_lds_dwordx4 v158, s[86:87]
	s_mov_b32 m0, s96
	v_lshl_add_u64 v[210:211], s[88:89], 0, v[160:161]
	global_load_lds_dwordx4 v162, s[34:35]
	s_add_i32 m0, s96, 0x2000
	s_nop 0
	global_load_lds_dwordx4 v158, s[34:35]
	v_lshl_add_u64 v[190:191], s[88:89], 0, v[164:165]
	s_mov_b32 m0, s48
	s_nop 0
	global_load_lds_dwordx4 v[190:191], off
	s_mov_b32 m0, s49
	s_nop 0
	global_load_lds_dwordx4 v[210:211], off
	s_waitcnt vmcnt(8)
	s_waitcnt lgkmcnt(0)
	s_barrier
; #define PG8_STAGE(bufoff, gbase, voff) do { _Pragma("unroll") for (int _i = 0; _i < 2; ++_i) \
;         __builtin_amdgcn_global_load_lds((const unsigned*)((const char*)(gbase) + (voff)[_i]), (PG8_LAS unsigned*)(lds + (bufoff) + ldsw + _i * 8192), 16, 0, 0); } while (0)
; #define PG8_LDA(dst, b, h) do { _Pragma("unroll") for (int m = 0; m < 4; ++m) _Pragma("unroll") for (int k = 0; k < 2; ++k) dst[m][k] = *(const PG8_LAS bf16x8*)(lds + PG8_SA(b, h) + aoff + m * 2048 + k * 1024); } while (0)
; #define PG8_LDB(dst, b, h) do { _Pragma("unroll") for (int n = 0; n < 2; ++n) _Pragma("unroll") for (int k = 0; k < 2; ++k) dst[n][k] = *(const PG8_LAS bf16x8*)(lds + PG8_SB(b, h) + boff + n * 2048 + k * 1024); } while (0)
; #define PG8_MMA(ai, bj, At, Bt) do { __builtin_amdgcn_s_setprio(1); _Pragma("unroll") for (int m = 0; m < 4; ++m) _Pragma("unroll") for (int n = 0; n < 2; ++n) _Pragma("unroll") for (int k = 0; k < 2; ++k) \
;         acc[ai][bj][m][n] = __builtin_amdgcn_mfma_f32_16x16x32_bf16(Bt[n][k], At[m][k], acc[ai][bj][m][n], 0, 0, 0); __builtin_amdgcn_s_setprio(0); } while (0)
; #define PG8_WAIT_V(n) asm volatile("s_waitcnt vmcnt(" #n ")" ::: "memory")
; #define PG8_WAIT_L(n) asm volatile("s_waitcnt lgkmcnt(" #n ")" ::: "memory")
; #define PG8_BAR __builtin_amdgcn_s_barrier()
; #define PG8_SCHED __builtin_amdgcn_sched_barrier(0)
;     ...
;             PG8_WAIT_V(8); PG8_WAIT_L(0); PG8_BAR; PG8_MMA(1, 0, At, B0); PG8_MMA(1, 1, At, B1); PG8_BAR; PG8_SCHED;
;             PG8_LDB(B0, 1, 0); PG8_LDB(B1, 1, 1); PG8_SCHED; PG8_LDA(At, 1, 0); PG8_STAGE(PG8_SA(0, 1), a2 + hstepA, voffA);
;             PG8_WAIT_V(8); PG8_WAIT_L(0); PG8_BAR; PG8_MMA(0, 0, At, B0); PG8_MMA(0, 1, At, B1); PG8_BAR; PG8_SCHED;
	s_setprio 1
	s_waitcnt lgkmcnt(0)
	v_mfma_f32_16x16x32_bf16 v[78:81], v[130:133], v[174:177], v[78:81]
	v_mfma_f32_16x16x32_bf16 v[74:77], v[138:141], v[174:177], v[74:77]
	v_mfma_f32_16x16x32_bf16 v[70:73], v[130:133], v[182:185], v[70:73]
	v_mfma_f32_16x16x32_bf16 v[66:69], v[138:141], v[182:185], v[66:69]
	v_mfma_f32_16x16x32_bf16 v[42:45], v[130:133], v[194:197], v[42:45]
	v_mfma_f32_16x16x32_bf16 v[6:9], v[138:141], v[194:197], v[6:9]
	v_mfma_f32_16x16x32_bf16 v[38:41], v[130:133], v[202:205], v[38:41]
	v_mfma_f32_16x16x32_bf16 v[2:5], v[138:141], v[202:205], v[2:5]
	v_mfma_f32_16x16x32_bf16 v[78:81], v[134:137], v[178:181], v[78:81]
	v_mfma_f32_16x16x32_bf16 v[74:77], v[142:145], v[178:181], v[74:77]
	v_mfma_f32_16x16x32_bf16 v[70:73], v[134:137], v[186:189], v[70:73]
	v_mfma_f32_16x16x32_bf16 v[66:69], v[142:145], v[186:189], v[66:69]
	v_mfma_f32_16x16x32_bf16 v[42:45], v[134:137], v[198:201], v[42:45]
	v_mfma_f32_16x16x32_bf16 v[6:9], v[142:145], v[198:201], v[6:9]
	v_mfma_f32_16x16x32_bf16 v[38:41], v[134:137], v[206:209], v[38:41]
	v_mfma_f32_16x16x32_bf16 v[2:5], v[142:145], v[206:209], v[2:5]
	s_setprio 0
	s_setprio 1
	v_mfma_f32_16x16x32_bf16 v[62:65], v[146:149], v[174:177], v[62:65]
	v_mfma_f32_16x16x32_bf16 v[58:61], v[154:157], v[174:177], v[58:61]
	v_mfma_f32_16x16x32_bf16 v[54:57], v[146:149], v[182:185], v[54:57]
	v_mfma_f32_16x16x32_bf16 v[50:53], v[154:157], v[182:185], v[50:53]
	v_mfma_f32_16x16x32_bf16 v[22:25], v[146:149], v[194:197], v[22:25]
	v_mfma_f32_16x16x32_bf16 v[18:21], v[154:157], v[194:197], v[18:21]
	v_mfma_f32_16x16x32_bf16 v[14:17], v[146:149], v[202:205], v[14:17]
	v_mfma_f32_16x16x32_bf16 v[10:13], v[154:157], v[202:205], v[10:13]
	v_mfma_f32_16x16x32_bf16 v[62:65], v[150:153], v[178:181], v[62:65]
	v_mfma_f32_16x16x32_bf16 v[58:61], v[170:173], v[178:181], v[58:61]
	v_mfma_f32_16x16x32_bf16 v[54:57], v[150:153], v[186:189], v[54:57]
	v_mfma_f32_16x16x32_bf16 v[50:53], v[170:173], v[186:189], v[50:53]
	v_mfma_f32_16x16x32_bf16 v[22:25], v[150:153], v[198:201], v[22:25]
	v_mfma_f32_16x16x32_bf16 v[18:21], v[170:173], v[198:201], v[18:21]
	v_mfma_f32_16x16x32_bf16 v[14:17], v[150:153], v[206:209], v[14:17]
	v_mfma_f32_16x16x32_bf16 v[10:13], v[170:173], v[206:209], v[10:13]
	s_setprio 0
	s_barrier
	s_add_i32 s88, 0, 0x18000
	v_add_u32_e32 v0, s88, v192
	s_add_i32 s89, 0, 0x1c000
	ds_read_b128 v[130:133], v0
	ds_read_b128 v[134:137], v0 offset:1024
	ds_read_b128 v[138:141], v0 offset:2048
	ds_read_b128 v[142:145], v0 offset:3072
	v_add_u32_e32 v0, s89, v192
	ds_read_b128 v[146:149], v0
	ds_read_b128 v[150:153], v0 offset:1024
	ds_read_b128 v[154:157], v0 offset:2048
	ds_read_b128 v[170:173], v0 offset:3072
	s_mov_b32 m0, s51
	v_lshl_add_u64 v[190:191], v[190:191], 0, s[58:59]
	ds_read_b128 v[174:177], v193 offset:32768
	ds_read_b128 v[178:181], v193 offset:33792
	ds_read_b128 v[182:185], v193 offset:34816
	ds_read_b128 v[186:189], v193 offset:35840
	ds_read_b128 v[194:197], v193 offset:36864
	ds_read_b128 v[198:201], v193 offset:37888
	ds_read_b128 v[202:205], v193 offset:38912
	ds_read_b128 v[206:209], v193 offset:39936
	global_load_lds_dwordx4 v[190:191], off
	v_lshl_add_u64 v[190:191], v[210:211], 0, s[58:59]
	s_mov_b32 m0, s54
	s_nop 0
	global_load_lds_dwordx4 v[190:191], off
	s_waitcnt vmcnt(8)
	s_waitcnt lgkmcnt(0)
	s_barrier
	s_setprio 1
	s_waitcnt lgkmcnt(0)
	v_mfma_f32_16x16x32_bf16 v[126:129], v[130:133], v[174:177], v[126:129]
	v_mfma_f32_16x16x32_bf16 v[122:125], v[138:141], v[174:177], v[122:125]
	v_mfma_f32_16x16x32_bf16 v[118:121], v[130:133], v[182:185], v[118:121]
	v_mfma_f32_16x16x32_bf16 v[114:117], v[138:141], v[182:185], v[114:117]
	v_mfma_f32_16x16x32_bf16 v[110:113], v[130:133], v[194:197], v[110:113]
	v_mfma_f32_16x16x32_bf16 v[106:109], v[138:141], v[194:197], v[106:109]
	v_mfma_f32_16x16x32_bf16 v[102:105], v[130:133], v[202:205], v[102:105]
	v_mfma_f32_16x16x32_bf16 v[98:101], v[138:141], v[202:205], v[98:101]
	v_mfma_f32_16x16x32_bf16 v[126:129], v[134:137], v[178:181], v[126:129]
	v_mfma_f32_16x16x32_bf16 v[122:125], v[142:145], v[178:181], v[122:125]
	v_mfma_f32_16x16x32_bf16 v[118:121], v[134:137], v[186:189], v[118:121]
	v_mfma_f32_16x16x32_bf16 v[114:117], v[142:145], v[186:189], v[114:117]
	v_mfma_f32_16x16x32_bf16 v[110:113], v[134:137], v[198:201], v[110:113]
	v_mfma_f32_16x16x32_bf16 v[106:109], v[142:145], v[198:201], v[106:109]
	v_mfma_f32_16x16x32_bf16 v[102:105], v[134:137], v[206:209], v[102:105]
	v_mfma_f32_16x16x32_bf16 v[98:101], v[142:145], v[206:209], v[98:101]
	s_setprio 0
	s_setprio 1
	v_mfma_f32_16x16x32_bf16 v[30:33], v[146:149], v[174:177], v[30:33]
	v_mfma_f32_16x16x32_bf16 v[46:49], v[154:157], v[174:177], v[46:49]
	v_mfma_f32_16x16x32_bf16 v[26:29], v[146:149], v[182:185], v[26:29]
	v_mfma_f32_16x16x32_bf16 v[34:37], v[154:157], v[182:185], v[34:37]
	v_mfma_f32_16x16x32_bf16 v[94:97], v[146:149], v[194:197], v[94:97]
	v_mfma_f32_16x16x32_bf16 v[90:93], v[154:157], v[194:197], v[90:93]
	v_mfma_f32_16x16x32_bf16 v[86:89], v[146:149], v[202:205], v[86:89]
	v_mfma_f32_16x16x32_bf16 v[82:85], v[154:157], v[202:205], v[82:85]
	v_mfma_f32_16x16x32_bf16 v[30:33], v[150:153], v[178:181], v[30:33]
	v_mfma_f32_16x16x32_bf16 v[46:49], v[170:173], v[178:181], v[46:49]
	v_mfma_f32_16x16x32_bf16 v[26:29], v[150:153], v[186:189], v[26:29]
	v_mfma_f32_16x16x32_bf16 v[34:37], v[170:173], v[186:189], v[34:37]
	v_mfma_f32_16x16x32_bf16 v[94:97], v[150:153], v[198:201], v[94:97]
	v_mfma_f32_16x16x32_bf16 v[90:93], v[170:173], v[198:201], v[90:93]
	v_mfma_f32_16x16x32_bf16 v[86:89], v[150:153], v[206:209], v[86:89]
	v_mfma_f32_16x16x32_bf16 v[82:85], v[170:173], v[206:209], v[82:85]
	s_setprio 0
	s_barrier
; #define PG8_STAGE(bufoff, gbase, voff) do { _Pragma("unroll") for (int _i = 0; _i < 2; ++_i) \
;         __builtin_amdgcn_global_load_lds((const unsigned*)((const char*)(gbase) + (voff)[_i]), (PG8_LAS unsigned*)(lds + (bufoff) + ldsw + _i * 8192), 16, 0, 0); } while (0)
; #define PG8_LDA(dst, b, h) do { _Pragma("unroll") for (int m = 0; m < 4; ++m) _Pragma("unroll") for (int k = 0; k < 2; ++k) dst[m][k] = *(const PG8_LAS bf16x8*)(lds + PG8_SA(b, h) + aoff + m * 2048 + k * 1024); } while (0)
; #define PG8_MMA(ai, bj, At, Bt) do { __builtin_amdgcn_s_setprio(1); _Pragma("unroll") for (int m = 0; m < 4; ++m) _Pragma("unroll") for (int n = 0; n < 2; ++n) _Pragma("unroll") for (int k = 0; k < 2; ++k) \
;         acc[ai][bj][m][n] = __builtin_amdgcn_mfma_f32_16x16x32_bf16(Bt[n][k], At[m][k], acc[ai][bj][m][n], 0, 0, 0); __builtin_amdgcn_s_setprio(0); } while (0)
; #define PG8_WAIT_V(n) asm volatile("s_waitcnt vmcnt(" #n ")" ::: "memory")
; #define PG8_WAIT_L(n) asm volatile("s_waitcnt lgkmcnt(" #n ")" ::: "memory")
; #define PG8_BAR __builtin_amdgcn_s_barrier()
; #define PG8_SCHED __builtin_amdgcn_sched_barrier(0)
;     ...
;             PG8_WAIT_V(8); PG8_WAIT_L(0); PG8_BAR; PG8_MMA(0, 0, At, B0); PG8_MMA(0, 1, At, B1); PG8_BAR; PG8_SCHED;
;             PG8_LDA(At, 1, 1); PG8_STAGE(PG8_SB(1, 0), b3, voffB); PG8_STAGE(PG8_SB(1, 1), b3 + hstepB, voffB); PG8_STAGE(PG8_SA(1, 0), a3, voffA);
;             PG8_WAIT_V(8); PG8_WAIT_L(0); PG8_BAR; PG8_MMA(1, 0, At, B0); PG8_MMA(1, 1, At, B1); PG8_BAR; PG8_SCHED;
;     ...
;         if constexpr (ALIGN_EPI) { if (wr == 0) PG8_BAR; }
	s_add_u32 s34, s86, 0x8000
	s_addc_u32 s35, s87, 0
	s_add_i32 s88, s88, s44
	s_mov_b32 m0, s88
	ds_read_b128 v[174:177], v193 offset:49152
	ds_read_b128 v[178:181], v193 offset:50176
	ds_read_b128 v[182:185], v193 offset:51200
	ds_read_b128 v[186:189], v193 offset:52224
	ds_read_b128 v[194:197], v193 offset:53248
	ds_read_b128 v[198:201], v193 offset:54272
	ds_read_b128 v[202:205], v193 offset:55296
	ds_read_b128 v[206:209], v193 offset:56320
	global_load_lds_dwordx4 v162, s[34:35]
	s_add_i32 m0, s88, 0x2000
	v_lshl_add_u64 v[190:191], s[34:35], 0, v[158:159]
	s_add_u32 s34, s86, 0xc000
	s_addc_u32 s35, s87, 0
	s_add_i32 s86, s89, s44
	global_load_lds_dwordx4 v[190:191], off
	s_mov_b32 m0, s86
	s_nop 0
	global_load_lds_dwordx4 v162, s[34:35]
	s_add_i32 m0, s86, 0x2000
	s_nop 0
	global_load_lds_dwordx4 v158, s[34:35]
	s_mov_b32 m0, s85
	s_nop 0
	global_load_lds_dwordx4 v164, s[46:47]
	v_lshl_add_u64 v[190:191], s[46:47], 0, v[160:161]
	s_mov_b32 m0, s90
	s_nop 0
	global_load_lds_dwordx4 v[190:191], off
	s_waitcnt vmcnt(8)
	s_waitcnt lgkmcnt(0)
	s_barrier
	s_setprio 1
	s_waitcnt lgkmcnt(0)
	v_mfma_f32_16x16x32_bf16 v[78:81], v[130:133], v[174:177], v[78:81]
	v_mfma_f32_16x16x32_bf16 v[74:77], v[138:141], v[174:177], v[74:77]
	v_mfma_f32_16x16x32_bf16 v[70:73], v[130:133], v[182:185], v[70:73]
	v_mfma_f32_16x16x32_bf16 v[66:69], v[138:141], v[182:185], v[66:69]
	v_mfma_f32_16x16x32_bf16 v[42:45], v[130:133], v[194:197], v[42:45]
	v_mfma_f32_16x16x32_bf16 v[6:9], v[138:141], v[194:197], v[6:9]
	v_mfma_f32_16x16x32_bf16 v[38:41], v[130:133], v[202:205], v[38:41]
	v_mfma_f32_16x16x32_bf16 v[2:5], v[138:141], v[202:205], v[2:5]
	v_mfma_f32_16x16x32_bf16 v[78:81], v[134:137], v[178:181], v[78:81]
	v_mfma_f32_16x16x32_bf16 v[74:77], v[142:145], v[178:181], v[74:77]
	v_mfma_f32_16x16x32_bf16 v[70:73], v[134:137], v[186:189], v[70:73]
	v_mfma_f32_16x16x32_bf16 v[66:69], v[142:145], v[186:189], v[66:69]
	v_mfma_f32_16x16x32_bf16 v[42:45], v[134:137], v[198:201], v[42:45]
	v_mfma_f32_16x16x32_bf16 v[6:9], v[142:145], v[198:201], v[6:9]
	v_mfma_f32_16x16x32_bf16 v[38:41], v[134:137], v[206:209], v[38:41]
	v_mfma_f32_16x16x32_bf16 v[2:5], v[142:145], v[206:209], v[2:5]
	s_setprio 0
	s_setprio 1
	v_mfma_f32_16x16x32_bf16 v[62:65], v[146:149], v[174:177], v[62:65]
	v_mfma_f32_16x16x32_bf16 v[58:61], v[154:157], v[174:177], v[58:61]
	v_mfma_f32_16x16x32_bf16 v[54:57], v[146:149], v[182:185], v[54:57]
	v_mfma_f32_16x16x32_bf16 v[50:53], v[154:157], v[182:185], v[50:53]
	v_mfma_f32_16x16x32_bf16 v[22:25], v[146:149], v[194:197], v[22:25]
	v_mfma_f32_16x16x32_bf16 v[18:21], v[154:157], v[194:197], v[18:21]
	v_mfma_f32_16x16x32_bf16 v[14:17], v[146:149], v[202:205], v[14:17]
	v_mfma_f32_16x16x32_bf16 v[10:13], v[154:157], v[202:205], v[10:13]
	v_mfma_f32_16x16x32_bf16 v[62:65], v[150:153], v[178:181], v[62:65]
	v_mfma_f32_16x16x32_bf16 v[58:61], v[170:173], v[178:181], v[58:61]
	v_mfma_f32_16x16x32_bf16 v[54:57], v[150:153], v[186:189], v[54:57]
	v_mfma_f32_16x16x32_bf16 v[50:53], v[170:173], v[186:189], v[50:53]
	v_mfma_f32_16x16x32_bf16 v[22:25], v[150:153], v[198:201], v[22:25]
	v_mfma_f32_16x16x32_bf16 v[18:21], v[170:173], v[198:201], v[18:21]
	v_mfma_f32_16x16x32_bf16 v[14:17], v[150:153], v[206:209], v[14:17]
	v_mfma_f32_16x16x32_bf16 v[10:13], v[170:173], v[206:209], v[10:13]
	s_setprio 0
	s_barrier
	s_add_i32 s66, s66, 2
	s_add_u32 vcc_hi, vcc_hi, 0x10000
	s_addc_u32 s65, s65, 0
	s_cmp_gt_u32 s66, 29
	s_mov_b64 s[34:35], s[36:37]
	s_cbranch_scc0 .LBB0_1256
	s_and_b64 vcc, exec, s[18:19]
	s_cbranch_vccz .LBB0_1259
	s_barrier

; #define PG8_STAGE(bufoff, gbase, voff) do { _Pragma("unroll") for (int _i = 0; _i < 2; ++_i) \
;         __builtin_amdgcn_global_load_lds((const unsigned*)((const char*)(gbase) + (voff)[_i]), (PG8_LAS unsigned*)(lds + (bufoff) + ldsw + _i * 8192), 16, 0, 0); } while (0)
; #define PG8_WAIT_V(n) asm volatile("s_waitcnt vmcnt(" #n ")" ::: "memory")
; #define PG8_BAR __builtin_amdgcn_s_barrier()
;     ...
;     for (int i = 0; i < 2; ++i) { int R, C; stage_rc(tid * 16 + i * 8192, R, C); const int Rb = Epi::PERM ? ((R & ~31) + perm32(R & 31)) : R;
;         const int Ra = ROWP ? (128 * (R >> 6) + 8 * (R & 15) + ((R >> 4) & 3)) : R;
;         voffA[i] = (unsigned)(Ra * LDA + C) * 2u; voffB[i] = (unsigned)(Rb * LDB + C) * 2u; }
;     constexpr ptrdiff_t kstep0 = KSB ? (ptrdiff_t)KSB : (ptrdiff_t)(BK * 2), kstepA0 = KSA ? (ptrdiff_t)KSA : (ptrdiff_t)(BK * 2), kstep = KREV ? -kstep0 : kstep0, kstepA = KREV ? -kstepA0 : kstepA0;
;     constexpr ptrdiff_t kofB = KREV ? (ptrdiff_t)(KK / BK - 1) * kstep0 : 0, kofA = KREV ? (ptrdiff_t)(KK / BK - 1) * kstepA0 : 0;
;     constexpr size_t hstepA = (size_t)(ROWP ? 4 : HALF) * LDA * 2, hstepB = (size_t)HALF * LDB * 2;
;     constexpr size_t tstepA = TSA ? (size_t)TSA : (size_t)2 * HALF * LDA * 2, tstepB = TSB ? (size_t)TSB : 2 * hstepB;
;     const unsigned ldsw = (unsigned)wid * 1024u;
;     const int aoff = lds_byte(wr * 64 + fr, fq * 8), boff = lds_byte(wc * 32 + fr, fq * 8);
;     ...
;         PG8_STAGE(PG8_SB(1, 0), cB + kstep, voffB); PG8_STAGE(PG8_SA(1, 0), cA + kstepA, voffA); PG8_STAGE(PG8_SB(1, 1), cB + hstepB + kstep, voffB);
;         PG8_WAIT_V(6); PG8_BAR;
.LBB0_1430:
	s_add_u32 s14, s6, 0x18104000
	s_addc_u32 s15, s7, 0
	s_mul_i32 s17, s96, 0x30000
	s_mul_hi_u32 s16, s96, 0x30000
	s_add_u32 s17, s6, s17
	s_addc_u32 s16, s7, s16
	s_add_u32 s51, s17, 0x10a000
	s_addc_u32 s54, s16, 0
	s_lshl_b32 s16, s96, 13
	s_add_i32 s20, s16, 0x2000
	s_cmp_lg_u32 s96, 3
	s_cselect_b64 s[16:17], -1, 0
	s_and_b64 s[18:19], s[16:17], exec
	s_cselect_b32 s44, s20, 0
	s_lshl_b64 s[18:19], s[44:45], 2
	s_add_u32 s18, s6, s18
	s_addc_u32 s19, s7, s19
	s_add_u32 s61, s18, 0x1c4000
	s_addc_u32 s63, s19, 0
	s_add_u32 s18, s6, 0x20104000
	s_addc_u32 s19, s7, 0
	s_add_u32 s20, s6, 0x304000
	s_addc_u32 s21, s7, 0
	v_and_b32_e32 v2, 48, v0
	v_lshlrev_b32_e32 v3, 6, v0
	s_movk_i32 s7, 0x3c0
	v_lshlrev_b32_e32 v0, 2, v0
	s_and_b32 s67, s8, 3
	s_lshl_b32 s6, s26, 13
	v_and_or_b32 v2, v3, s7, v2
	v_and_b32_e32 v0, 32, v0
	s_lshl_b32 s68, s26, 6
	v_bitop3_b32 v4, v2, s6, v0 bitop3:0xde
	s_lshl_b32 s70, s67, 5
	s_lshl_b32 s6, s67, 12
	v_bitop3_b32 v230, v2, s6, v0 bitop3:0xde
	s_add_u32 s6, s9, 0x2b0000
	v_mov_b32_e32 v197, v1
	s_addc_u32 s7, s23, 0
	s_add_i32 m0, s46, 0x18000
	v_mov_b32_e32 v201, v1
	s_waitcnt vmcnt(2)
	s_barrier
	global_load_lds_dwordx4 v196, s[6:7]
	s_add_i32 m0, s46, 0x1a000
	v_lshl_add_u64 v[2:3], s[6:7], 0, v[200:201]
	s_add_u32 s6, s24, 0x2b0000
	v_mov_b32_e32 v195, v1
	s_addc_u32 s7, s25, 0
	s_add_i32 s71, s46, 0x8000
	v_mov_b32_e32 v199, v1
	global_load_lds_dwordx4 v[2:3], off
	s_mov_b32 m0, s71
	s_add_i32 s80, s46, 0xa000
	global_load_lds_dwordx4 v194, s[6:7]
	v_lshl_add_u64 v[2:3], s[6:7], 0, v[198:199]
	s_add_u32 s6, s9, 0x2b4000
	s_mov_b32 m0, s80
	s_addc_u32 s7, s23, 0
	global_load_lds_dwordx4 v[2:3], off
	s_add_i32 m0, s46, 0x1c000
	s_nop 0
	global_load_lds_dwordx4 v196, s[6:7]
	s_add_i32 m0, s46, 0x1e000
	s_cmpk_lt_u32 s22, 0x100
	global_load_lds_dwordx4 v200, s[6:7]
	s_waitcnt vmcnt(6)
	s_mov_b32 s55, 0
	s_cselect_b64 s[22:23], -1, 0
	s_ashr_i32 s81, s2, 31
	v_add_u32_e32 v231, 0, v4
	s_barrier
	s_branch .LBB0_1433

; #define PG8_STAGE(bufoff, gbase, voff) do { _Pragma("unroll") for (int _i = 0; _i < 2; ++_i) \
;         __builtin_amdgcn_global_load_lds((const unsigned*)((const char*)(gbase) + (voff)[_i]), (PG8_LAS unsigned*)(lds + (bufoff) + ldsw + _i * 8192), 16, 0, 0); } while (0)
; #define PG8_LDA(dst, b, h) do { _Pragma("unroll") for (int m = 0; m < 4; ++m) _Pragma("unroll") for (int k = 0; k < 2; ++k) dst[m][k] = *(const PG8_LAS bf16x8*)(lds + PG8_SA(b, h) + aoff + m * 2048 + k * 1024); } while (0)
; #define PG8_LDB(dst, b, h) do { _Pragma("unroll") for (int n = 0; n < 2; ++n) _Pragma("unroll") for (int k = 0; k < 2; ++k) dst[n][k] = *(const PG8_LAS bf16x8*)(lds + PG8_SB(b, h) + boff + n * 2048 + k * 1024); } while (0)
; #define PG8_MMA(ai, bj, At, Bt) do { __builtin_amdgcn_s_setprio(1); _Pragma("unroll") for (int m = 0; m < 4; ++m) _Pragma("unroll") for (int n = 0; n < 2; ++n) _Pragma("unroll") for (int k = 0; k < 2; ++k) \
;         acc[ai][bj][m][n] = __builtin_amdgcn_mfma_f32_16x16x32_bf16(Bt[n][k], At[m][k], acc[ai][bj][m][n], 0, 0, 0); __builtin_amdgcn_s_setprio(0); } while (0)
; #define PG8_WAIT_V(n) asm volatile("s_waitcnt vmcnt(" #n ")" ::: "memory")
; #define PG8_WAIT_L(n) asm volatile("s_waitcnt lgkmcnt(" #n ")" ::: "memory")
; #define PG8_BAR __builtin_amdgcn_s_barrier()
; #define PG8_SCHED __builtin_amdgcn_sched_barrier(0)
;     ...
;             const bool last = (t == nt - 2);
;             const char* a1 = cA + (ptrdiff_t)(t + 1) * kstepA;
;             const char* a2 = last ? nA : cA + (ptrdiff_t)(t + 2) * kstepA; const char* b2 = last ? nB : cB + (ptrdiff_t)(t + 2) * kstep;
;             const char* a3 = a2 + kstepA; const char* b3 = b2 + kstep;
;             if (last && has_next) S.a_ready(nxt);
;             if constexpr (SP2) {
;             PG8_LDB(B0, 0, 0); PG8_LDB(B1, 0, 1); PG8_SCHED; PG8_LDA(At, 0, 0); PG8_STAGE(PG8_SA(1, 1), a1 + hstepA, voffA);
;             PG8_WAIT_V(8); PG8_WAIT_L(0); PG8_BAR; PG8_MMA(0, 0, At, B0); PG8_MMA(0, 1, At, B1); PG8_BAR; PG8_SCHED;
;             PG8_LDA(At, 0, 1); PG8_STAGE(PG8_SB(0, 0), b2, voffB); PG8_STAGE(PG8_SB(0, 1), b2 + hstepB, voffB); PG8_STAGE(PG8_SA(0, 0), a2, voffA);
;             PG8_WAIT_V(8); PG8_WAIT_L(0); PG8_BAR; PG8_MMA(1, 0, At, B0); PG8_MMA(1, 1, At, B1); PG8_BAR; PG8_SCHED;
.LBB0_1444:
	s_or_b32 s44, s56, 1
	s_lshl_b64 s[34:35], s[44:45], 15
	s_sub_u32 s34, 0, s34
	s_subb_u32 s35, 0, s35
	s_add_u32 s44, s28, s34
	s_addc_u32 s65, s29, s35
	s_add_u32 s34, s30, 0xffff8000
	s_addc_u32 s35, s31, -1
	s_add_i32 s66, 0, 0x10000
	v_add_u32_e32 v0, s66, v230
	s_add_i32 s90, 0, 0x14000
	s_waitcnt lgkmcnt(0)
	ds_read_b128 v[130:133], v0
	ds_read_b128 v[134:137], v0 offset:1024
	ds_read_b128 v[138:141], v0 offset:2048
	ds_read_b128 v[142:145], v0 offset:3072
	v_add_u32_e32 v0, s90, v230
	ds_read_b128 v[146:149], v0
	ds_read_b128 v[150:153], v0 offset:1024
	ds_read_b128 v[154:157], v0 offset:2048
	ds_read_b128 v[158:161], v0 offset:3072
	s_add_u32 s88, s44, 0x4000
	s_addc_u32 s89, s65, 0
	s_add_i32 m0, s46, 0xc000
	ds_read_b128 v[162:165], v231
	ds_read_b128 v[166:169], v231 offset:1024
	ds_read_b128 v[170:173], v231 offset:2048
	ds_read_b128 v[174:177], v231 offset:3072
	ds_read_b128 v[178:181], v231 offset:4096
	ds_read_b128 v[182:185], v231 offset:5120
	ds_read_b128 v[186:189], v231 offset:6144
	ds_read_b128 v[190:193], v231 offset:7168
	global_load_lds_dwordx4 v194, s[88:89]
	s_add_i32 m0, s46, 0xe000
	s_nop 0
	global_load_lds_dwordx4 v198, s[88:89]
	s_waitcnt vmcnt(8)
	s_waitcnt lgkmcnt(0)
	s_barrier
	s_setprio 1
	s_waitcnt lgkmcnt(0)
	v_mfma_f32_16x16x32_bf16 v[126:129], v[130:133], v[162:165], v[126:129]
	v_mfma_f32_16x16x32_bf16 v[122:125], v[138:141], v[162:165], v[122:125]
	v_mfma_f32_16x16x32_bf16 v[110:113], v[130:133], v[170:173], v[110:113]
	v_mfma_f32_16x16x32_bf16 v[106:109], v[138:141], v[170:173], v[106:109]
	v_mfma_f32_16x16x32_bf16 v[94:97], v[130:133], v[178:181], v[94:97]
	v_mfma_f32_16x16x32_bf16 v[90:93], v[138:141], v[178:181], v[90:93]
	v_mfma_f32_16x16x32_bf16 v[78:81], v[130:133], v[186:189], v[78:81]
	v_mfma_f32_16x16x32_bf16 v[74:77], v[138:141], v[186:189], v[74:77]
	v_mfma_f32_16x16x32_bf16 v[126:129], v[134:137], v[166:169], v[126:129]
	v_mfma_f32_16x16x32_bf16 v[122:125], v[142:145], v[166:169], v[122:125]
	v_mfma_f32_16x16x32_bf16 v[110:113], v[134:137], v[174:177], v[110:113]
	v_mfma_f32_16x16x32_bf16 v[106:109], v[142:145], v[174:177], v[106:109]
	v_mfma_f32_16x16x32_bf16 v[94:97], v[134:137], v[182:185], v[94:97]
	v_mfma_f32_16x16x32_bf16 v[90:93], v[142:145], v[182:185], v[90:93]
	v_mfma_f32_16x16x32_bf16 v[78:81], v[134:137], v[190:193], v[78:81]
	v_mfma_f32_16x16x32_bf16 v[74:77], v[142:145], v[190:193], v[74:77]
	s_setprio 0
	s_setprio 1
	v_mfma_f32_16x16x32_bf16 v[118:121], v[146:149], v[162:165], v[118:121]
	v_mfma_f32_16x16x32_bf16 v[114:117], v[154:157], v[162:165], v[114:117]
	v_mfma_f32_16x16x32_bf16 v[102:105], v[146:149], v[170:173], v[102:105]
	v_mfma_f32_16x16x32_bf16 v[98:101], v[154:157], v[170:173], v[98:101]
	v_mfma_f32_16x16x32_bf16 v[86:89], v[146:149], v[178:181], v[86:89]
	v_mfma_f32_16x16x32_bf16 v[82:85], v[154:157], v[178:181], v[82:85]
	v_mfma_f32_16x16x32_bf16 v[70:73], v[146:149], v[186:189], v[70:73]
	v_mfma_f32_16x16x32_bf16 v[66:69], v[154:157], v[186:189], v[66:69]
	v_mfma_f32_16x16x32_bf16 v[118:121], v[150:153], v[166:169], v[118:121]
	v_mfma_f32_16x16x32_bf16 v[114:117], v[158:161], v[166:169], v[114:117]
	v_mfma_f32_16x16x32_bf16 v[102:105], v[150:153], v[174:177], v[102:105]
	v_mfma_f32_16x16x32_bf16 v[98:101], v[158:161], v[174:177], v[98:101]
	v_mfma_f32_16x16x32_bf16 v[86:89], v[150:153], v[182:185], v[86:89]
	v_mfma_f32_16x16x32_bf16 v[82:85], v[158:161], v[182:185], v[82:85]
	v_mfma_f32_16x16x32_bf16 v[70:73], v[150:153], v[190:193], v[70:73]
	v_mfma_f32_16x16x32_bf16 v[66:69], v[158:161], v[190:193], v[66:69]
	s_setprio 0
	s_barrier
	s_add_i32 s44, s66, s41
	s_mov_b32 m0, s44
	ds_read_b128 v[162:165], v231 offset:16384
	ds_read_b128 v[166:169], v231 offset:17408
	ds_read_b128 v[170:173], v231 offset:18432
	ds_read_b128 v[174:177], v231 offset:19456
	ds_read_b128 v[178:181], v231 offset:20480
	ds_read_b128 v[182:185], v231 offset:21504
	ds_read_b128 v[186:189], v231 offset:22528
	ds_read_b128 v[190:193], v231 offset:23552
	global_load_lds_dwordx4 v196, s[8:9]
	s_add_i32 m0, s44, 0x2000
	s_add_u32 s88, s8, 0x4000
	s_addc_u32 s89, s9, 0
	s_add_i32 s44, s90, s41
	global_load_lds_dwordx4 v200, s[8:9]
	s_mov_b32 m0, s44
	s_nop 0
	global_load_lds_dwordx4 v196, s[88:89]
	s_add_i32 m0, s44, 0x2000
	s_nop 0
	global_load_lds_dwordx4 v200, s[88:89]
	s_mov_b32 m0, s46
	s_nop 0
	global_load_lds_dwordx4 v194, s[30:31]
	s_mov_b32 m0, s47
	s_nop 0
	global_load_lds_dwordx4 v198, s[30:31]
	s_waitcnt vmcnt(8)
	s_waitcnt lgkmcnt(0)
	s_barrier
; #define PG8_STAGE(bufoff, gbase, voff) do { _Pragma("unroll") for (int _i = 0; _i < 2; ++_i) \
;         __builtin_amdgcn_global_load_lds((const unsigned*)((const char*)(gbase) + (voff)[_i]), (PG8_LAS unsigned*)(lds + (bufoff) + ldsw + _i * 8192), 16, 0, 0); } while (0)
; #define PG8_LDA(dst, b, h) do { _Pragma("unroll") for (int m = 0; m < 4; ++m) _Pragma("unroll") for (int k = 0; k < 2; ++k) dst[m][k] = *(const PG8_LAS bf16x8*)(lds + PG8_SA(b, h) + aoff + m * 2048 + k * 1024); } while (0)
; #define PG8_LDB(dst, b, h) do { _Pragma("unroll") for (int n = 0; n < 2; ++n) _Pragma("unroll") for (int k = 0; k < 2; ++k) dst[n][k] = *(const PG8_LAS bf16x8*)(lds + PG8_SB(b, h) + boff + n * 2048 + k * 1024); } while (0)
; #define PG8_MMA(ai, bj, At, Bt) do { __builtin_amdgcn_s_setprio(1); _Pragma("unroll") for (int m = 0; m < 4; ++m) _Pragma("unroll") for (int n = 0; n < 2; ++n) _Pragma("unroll") for (int k = 0; k < 2; ++k) \
;         acc[ai][bj][m][n] = __builtin_amdgcn_mfma_f32_16x16x32_bf16(Bt[n][k], At[m][k], acc[ai][bj][m][n], 0, 0, 0); __builtin_amdgcn_s_setprio(0); } while (0)
; #define PG8_WAIT_V(n) asm volatile("s_waitcnt vmcnt(" #n ")" ::: "memory")
; #define PG8_WAIT_L(n) asm volatile("s_waitcnt lgkmcnt(" #n ")" ::: "memory")
; #define PG8_BAR __builtin_amdgcn_s_barrier()
; #define PG8_SCHED __builtin_amdgcn_sched_barrier(0)
;     ...
;             PG8_WAIT_V(8); PG8_WAIT_L(0); PG8_BAR; PG8_MMA(1, 0, At, B0); PG8_MMA(1, 1, At, B1); PG8_BAR; PG8_SCHED;
;             PG8_LDB(B0, 1, 0); PG8_LDB(B1, 1, 1); PG8_SCHED; PG8_LDA(At, 1, 0); PG8_STAGE(PG8_SA(0, 1), a2 + hstepA, voffA);
;             PG8_WAIT_V(8); PG8_WAIT_L(0); PG8_BAR; PG8_MMA(0, 0, At, B0); PG8_MMA(0, 1, At, B1); PG8_BAR; PG8_SCHED;
	s_setprio 1
	s_waitcnt lgkmcnt(0)
	v_mfma_f32_16x16x32_bf16 v[62:65], v[130:133], v[162:165], v[62:65]
	v_mfma_f32_16x16x32_bf16 v[58:61], v[138:141], v[162:165], v[58:61]
	v_mfma_f32_16x16x32_bf16 v[46:49], v[130:133], v[170:173], v[46:49]
	v_mfma_f32_16x16x32_bf16 v[42:45], v[138:141], v[170:173], v[42:45]
	v_mfma_f32_16x16x32_bf16 v[30:33], v[130:133], v[178:181], v[30:33]
	v_mfma_f32_16x16x32_bf16 v[26:29], v[138:141], v[178:181], v[26:29]
	v_mfma_f32_16x16x32_bf16 v[14:17], v[130:133], v[186:189], v[14:17]
	v_mfma_f32_16x16x32_bf16 v[10:13], v[138:141], v[186:189], v[10:13]
	v_mfma_f32_16x16x32_bf16 v[62:65], v[134:137], v[166:169], v[62:65]
	v_mfma_f32_16x16x32_bf16 v[58:61], v[142:145], v[166:169], v[58:61]
	v_mfma_f32_16x16x32_bf16 v[46:49], v[134:137], v[174:177], v[46:49]
	v_mfma_f32_16x16x32_bf16 v[42:45], v[142:145], v[174:177], v[42:45]
	v_mfma_f32_16x16x32_bf16 v[30:33], v[134:137], v[182:185], v[30:33]
	v_mfma_f32_16x16x32_bf16 v[26:29], v[142:145], v[182:185], v[26:29]
	v_mfma_f32_16x16x32_bf16 v[14:17], v[134:137], v[190:193], v[14:17]
	v_mfma_f32_16x16x32_bf16 v[10:13], v[142:145], v[190:193], v[10:13]
	s_setprio 0
	s_setprio 1
	v_mfma_f32_16x16x32_bf16 v[54:57], v[146:149], v[162:165], v[54:57]
	v_mfma_f32_16x16x32_bf16 v[50:53], v[154:157], v[162:165], v[50:53]
	v_mfma_f32_16x16x32_bf16 v[38:41], v[146:149], v[170:173], v[38:41]
	v_mfma_f32_16x16x32_bf16 v[34:37], v[154:157], v[170:173], v[34:37]
	v_mfma_f32_16x16x32_bf16 v[22:25], v[146:149], v[178:181], v[22:25]
	v_mfma_f32_16x16x32_bf16 v[18:21], v[154:157], v[178:181], v[18:21]
	v_mfma_f32_16x16x32_bf16 v[6:9], v[146:149], v[186:189], v[6:9]
	v_mfma_f32_16x16x32_bf16 v[2:5], v[154:157], v[186:189], v[2:5]
	v_mfma_f32_16x16x32_bf16 v[54:57], v[150:153], v[166:169], v[54:57]
	v_mfma_f32_16x16x32_bf16 v[50:53], v[158:161], v[166:169], v[50:53]
	v_mfma_f32_16x16x32_bf16 v[38:41], v[150:153], v[174:177], v[38:41]
	v_mfma_f32_16x16x32_bf16 v[34:37], v[158:161], v[174:177], v[34:37]
	v_mfma_f32_16x16x32_bf16 v[22:25], v[150:153], v[182:185], v[22:25]
	v_mfma_f32_16x16x32_bf16 v[18:21], v[158:161], v[182:185], v[18:21]
	v_mfma_f32_16x16x32_bf16 v[6:9], v[150:153], v[190:193], v[6:9]
	v_mfma_f32_16x16x32_bf16 v[2:5], v[158:161], v[190:193], v[2:5]
	s_setprio 0
	s_barrier
	s_add_i32 s44, 0, 0x18000
	v_add_u32_e32 v0, s44, v230
	s_add_i32 s65, 0, 0x1c000
	ds_read_b128 v[130:133], v0
	ds_read_b128 v[134:137], v0 offset:1024
	ds_read_b128 v[138:141], v0 offset:2048
	ds_read_b128 v[142:145], v0 offset:3072
	v_add_u32_e32 v0, s65, v230
	ds_read_b128 v[146:149], v0
	ds_read_b128 v[150:153], v0 offset:1024
	ds_read_b128 v[154:157], v0 offset:2048
	ds_read_b128 v[158:161], v0 offset:3072
	s_add_u32 s30, s30, 0x4000
	s_addc_u32 s31, s31, 0
	s_mov_b32 m0, s48
	ds_read_b128 v[162:165], v231 offset:32768
	ds_read_b128 v[166:169], v231 offset:33792
	ds_read_b128 v[170:173], v231 offset:34816
	ds_read_b128 v[174:177], v231 offset:35840
	ds_read_b128 v[178:181], v231 offset:36864
	ds_read_b128 v[182:185], v231 offset:37888
	ds_read_b128 v[186:189], v231 offset:38912
	ds_read_b128 v[190:193], v231 offset:39936
	global_load_lds_dwordx4 v194, s[30:31]
	s_mov_b32 m0, s49
	s_nop 0
	global_load_lds_dwordx4 v198, s[30:31]
	s_waitcnt vmcnt(8)
	s_waitcnt lgkmcnt(0)
	s_barrier
	s_setprio 1
	s_waitcnt lgkmcnt(0)
	v_mfma_f32_16x16x32_bf16 v[126:129], v[130:133], v[162:165], v[126:129]
	v_mfma_f32_16x16x32_bf16 v[122:125], v[138:141], v[162:165], v[122:125]
	v_mfma_f32_16x16x32_bf16 v[110:113], v[130:133], v[170:173], v[110:113]
	v_mfma_f32_16x16x32_bf16 v[106:109], v[138:141], v[170:173], v[106:109]
	v_mfma_f32_16x16x32_bf16 v[94:97], v[130:133], v[178:181], v[94:97]
	v_mfma_f32_16x16x32_bf16 v[90:93], v[138:141], v[178:181], v[90:93]
	v_mfma_f32_16x16x32_bf16 v[78:81], v[130:133], v[186:189], v[78:81]
	v_mfma_f32_16x16x32_bf16 v[74:77], v[138:141], v[186:189], v[74:77]
	v_mfma_f32_16x16x32_bf16 v[126:129], v[134:137], v[166:169], v[126:129]
	v_mfma_f32_16x16x32_bf16 v[122:125], v[142:145], v[166:169], v[122:125]
	v_mfma_f32_16x16x32_bf16 v[110:113], v[134:137], v[174:177], v[110:113]
	v_mfma_f32_16x16x32_bf16 v[106:109], v[142:145], v[174:177], v[106:109]
	v_mfma_f32_16x16x32_bf16 v[94:97], v[134:137], v[182:185], v[94:97]
	v_mfma_f32_16x16x32_bf16 v[90:93], v[142:145], v[182:185], v[90:93]
	v_mfma_f32_16x16x32_bf16 v[78:81], v[134:137], v[190:193], v[78:81]
	v_mfma_f32_16x16x32_bf16 v[74:77], v[142:145], v[190:193], v[74:77]
	s_setprio 0
	s_setprio 1
	v_mfma_f32_16x16x32_bf16 v[118:121], v[146:149], v[162:165], v[118:121]
	v_mfma_f32_16x16x32_bf16 v[114:117], v[154:157], v[162:165], v[114:117]
	v_mfma_f32_16x16x32_bf16 v[102:105], v[146:149], v[170:173], v[102:105]
	v_mfma_f32_16x16x32_bf16 v[98:101], v[154:157], v[170:173], v[98:101]
	v_mfma_f32_16x16x32_bf16 v[86:89], v[146:149], v[178:181], v[86:89]
	v_mfma_f32_16x16x32_bf16 v[82:85], v[154:157], v[178:181], v[82:85]
	v_mfma_f32_16x16x32_bf16 v[70:73], v[146:149], v[186:189], v[70:73]
	v_mfma_f32_16x16x32_bf16 v[66:69], v[154:157], v[186:189], v[66:69]
	v_mfma_f32_16x16x32_bf16 v[118:121], v[150:153], v[166:169], v[118:121]
	v_mfma_f32_16x16x32_bf16 v[114:117], v[158:161], v[166:169], v[114:117]
	v_mfma_f32_16x16x32_bf16 v[102:105], v[150:153], v[174:177], v[102:105]
	v_mfma_f32_16x16x32_bf16 v[98:101], v[158:161], v[174:177], v[98:101]
	v_mfma_f32_16x16x32_bf16 v[86:89], v[150:153], v[182:185], v[86:89]
	v_mfma_f32_16x16x32_bf16 v[82:85], v[158:161], v[182:185], v[82:85]
	v_mfma_f32_16x16x32_bf16 v[70:73], v[150:153], v[190:193], v[70:73]
	v_mfma_f32_16x16x32_bf16 v[66:69], v[158:161], v[190:193], v[66:69]
	s_setprio 0
	s_barrier
; #define PG8_STAGE(bufoff, gbase, voff) do { _Pragma("unroll") for (int _i = 0; _i < 2; ++_i) \
;         __builtin_amdgcn_global_load_lds((const unsigned*)((const char*)(gbase) + (voff)[_i]), (PG8_LAS unsigned*)(lds + (bufoff) + ldsw + _i * 8192), 16, 0, 0); } while (0)
; #define PG8_LDA(dst, b, h) do { _Pragma("unroll") for (int m = 0; m < 4; ++m) _Pragma("unroll") for (int k = 0; k < 2; ++k) dst[m][k] = *(const PG8_LAS bf16x8*)(lds + PG8_SA(b, h) + aoff + m * 2048 + k * 1024); } while (0)
; #define PG8_MMA(ai, bj, At, Bt) do { __builtin_amdgcn_s_setprio(1); _Pragma("unroll") for (int m = 0; m < 4; ++m) _Pragma("unroll") for (int n = 0; n < 2; ++n) _Pragma("unroll") for (int k = 0; k < 2; ++k) \
;         acc[ai][bj][m][n] = __builtin_amdgcn_mfma_f32_16x16x32_bf16(Bt[n][k], At[m][k], acc[ai][bj][m][n], 0, 0, 0); __builtin_amdgcn_s_setprio(0); } while (0)
; #define PG8_WAIT_V(n) asm volatile("s_waitcnt vmcnt(" #n ")" ::: "memory")
; #define PG8_WAIT_L(n) asm volatile("s_waitcnt lgkmcnt(" #n ")" ::: "memory")
; #define PG8_BAR __builtin_amdgcn_s_barrier()
; #define PG8_SCHED __builtin_amdgcn_sched_barrier(0)
;     ...
;             PG8_WAIT_V(8); PG8_WAIT_L(0); PG8_BAR; PG8_MMA(0, 0, At, B0); PG8_MMA(0, 1, At, B1); PG8_BAR; PG8_SCHED;
;             PG8_LDA(At, 1, 1); PG8_STAGE(PG8_SB(1, 0), b3, voffB); PG8_STAGE(PG8_SB(1, 1), b3 + hstepB, voffB); PG8_STAGE(PG8_SA(1, 0), a3, voffA);
;             PG8_WAIT_V(8); PG8_WAIT_L(0); PG8_BAR; PG8_MMA(1, 0, At, B0); PG8_MMA(1, 1, At, B1); PG8_BAR; PG8_SCHED;
	s_add_u32 s30, s8, 0xffff8000
	s_addc_u32 s31, s9, -1
	s_add_i32 s44, s44, s41
	s_mov_b32 m0, s44
	ds_read_b128 v[162:165], v231 offset:49152
	ds_read_b128 v[166:169], v231 offset:50176
	ds_read_b128 v[170:173], v231 offset:51200
	ds_read_b128 v[174:177], v231 offset:52224
	ds_read_b128 v[178:181], v231 offset:53248
	ds_read_b128 v[182:185], v231 offset:54272
	ds_read_b128 v[186:189], v231 offset:55296
	ds_read_b128 v[190:193], v231 offset:56320
	global_load_lds_dwordx4 v196, s[30:31]
	s_add_i32 m0, s44, 0x2000
	s_add_u32 s8, s8, 0xffffc000
	v_lshl_add_u64 v[202:203], s[30:31], 0, v[200:201]
	s_addc_u32 s9, s9, -1
	s_add_i32 s30, s65, s41
	global_load_lds_dwordx4 v[202:203], off
	s_mov_b32 m0, s30
	s_nop 0
	global_load_lds_dwordx4 v196, s[8:9]
	s_add_i32 m0, s30, 0x2000
	s_nop 0
	global_load_lds_dwordx4 v200, s[8:9]
	s_mov_b32 m0, s71
	s_nop 0
	global_load_lds_dwordx4 v194, s[34:35]
	v_lshl_add_u64 v[202:203], s[34:35], 0, v[198:199]
	s_mov_b32 m0, s80
	s_nop 0
	global_load_lds_dwordx4 v[202:203], off
	s_waitcnt vmcnt(8)
	s_waitcnt lgkmcnt(0)
	s_barrier
	s_setprio 1
	s_waitcnt lgkmcnt(0)
	v_mfma_f32_16x16x32_bf16 v[62:65], v[130:133], v[162:165], v[62:65]
	v_mfma_f32_16x16x32_bf16 v[58:61], v[138:141], v[162:165], v[58:61]
	v_mfma_f32_16x16x32_bf16 v[46:49], v[130:133], v[170:173], v[46:49]
	v_mfma_f32_16x16x32_bf16 v[42:45], v[138:141], v[170:173], v[42:45]
	v_mfma_f32_16x16x32_bf16 v[30:33], v[130:133], v[178:181], v[30:33]
	v_mfma_f32_16x16x32_bf16 v[26:29], v[138:141], v[178:181], v[26:29]
	v_mfma_f32_16x16x32_bf16 v[14:17], v[130:133], v[186:189], v[14:17]
	v_mfma_f32_16x16x32_bf16 v[10:13], v[138:141], v[186:189], v[10:13]
	v_mfma_f32_16x16x32_bf16 v[62:65], v[134:137], v[166:169], v[62:65]
	v_mfma_f32_16x16x32_bf16 v[58:61], v[142:145], v[166:169], v[58:61]
	v_mfma_f32_16x16x32_bf16 v[46:49], v[134:137], v[174:177], v[46:49]
	v_mfma_f32_16x16x32_bf16 v[42:45], v[142:145], v[174:177], v[42:45]
	v_mfma_f32_16x16x32_bf16 v[30:33], v[134:137], v[182:185], v[30:33]
	v_mfma_f32_16x16x32_bf16 v[26:29], v[142:145], v[182:185], v[26:29]
	v_mfma_f32_16x16x32_bf16 v[14:17], v[134:137], v[190:193], v[14:17]
	v_mfma_f32_16x16x32_bf16 v[10:13], v[142:145], v[190:193], v[10:13]
	s_setprio 0
	s_setprio 1
	v_mfma_f32_16x16x32_bf16 v[54:57], v[146:149], v[162:165], v[54:57]
	v_mfma_f32_16x16x32_bf16 v[50:53], v[154:157], v[162:165], v[50:53]
	v_mfma_f32_16x16x32_bf16 v[38:41], v[146:149], v[170:173], v[38:41]
	v_mfma_f32_16x16x32_bf16 v[34:37], v[154:157], v[170:173], v[34:37]
	v_mfma_f32_16x16x32_bf16 v[22:25], v[146:149], v[178:181], v[22:25]
	v_mfma_f32_16x16x32_bf16 v[18:21], v[154:157], v[178:181], v[18:21]
	v_mfma_f32_16x16x32_bf16 v[6:9], v[146:149], v[186:189], v[6:9]
	v_mfma_f32_16x16x32_bf16 v[2:5], v[154:157], v[186:189], v[2:5]
	v_mfma_f32_16x16x32_bf16 v[54:57], v[150:153], v[166:169], v[54:57]
	v_mfma_f32_16x16x32_bf16 v[50:53], v[158:161], v[166:169], v[50:53]
	v_mfma_f32_16x16x32_bf16 v[38:41], v[150:153], v[174:177], v[38:41]
	v_mfma_f32_16x16x32_bf16 v[34:37], v[158:161], v[174:177], v[34:37]
	v_mfma_f32_16x16x32_bf16 v[22:25], v[150:153], v[182:185], v[22:25]
	v_mfma_f32_16x16x32_bf16 v[18:21], v[158:161], v[182:185], v[18:21]
	v_mfma_f32_16x16x32_bf16 v[6:9], v[150:153], v[190:193], v[6:9]
	v_mfma_f32_16x16x32_bf16 v[2:5], v[158:161], v[190:193], v[2:5]
	s_setprio 0
	s_barrier
	s_cmpk_gt_u32 s56, 0x55
	s_mov_b32 s56, s57
	s_cbranch_scc1 .LBB0_1449
